# 4+4 DMA split plus DMA-first issue order in the SP2 load segments (the four LDS-DMA loads ahead of the eight fragment reads)
# speedup vs baseline: 1.0018x; 1.0018x over previous
; #define PG8_STAGE(bufoff, gbase, voff) do { _Pragma("unroll") for (int _i = 0; _i < 2; ++_i) \
;         __builtin_amdgcn_global_load_lds((const unsigned*)((const char*)(gbase) + (voff)[_i]), (PG8_LAS unsigned*)(lds + (bufoff) + ldsw + _i * 8192), 16, 0, 0); } while (0)
; #define PG8_LDA(dst, b, h) do { _Pragma("unroll") for (int m = 0; m < 4; ++m) _Pragma("unroll") for (int k = 0; k < 2; ++k) dst[m][k] = *(const PG8_LAS bf16x8*)(lds + PG8_SA(b, h) + aoff + m * 2048 + k * 1024); } while (0)
; #define PG8_LDB(dst, b, h) do { _Pragma("unroll") for (int n = 0; n < 2; ++n) _Pragma("unroll") for (int k = 0; k < 2; ++k) dst[n][k] = *(const PG8_LAS bf16x8*)(lds + PG8_SB(b, h) + boff + n * 2048 + k * 1024); } while (0)
; #define PG8_MMA(ai, bj, At, Bt) do { __builtin_amdgcn_s_setprio(1); _Pragma("unroll") for (int m = 0; m < 4; ++m) _Pragma("unroll") for (int n = 0; n < 2; ++n) _Pragma("unroll") for (int k = 0; k < 2; ++k) \
;         acc[ai][bj][m][n] = __builtin_amdgcn_mfma_f32_16x16x32_bf16(Bt[n][k], At[m][k], acc[ai][bj][m][n], 0, 0, 0); __builtin_amdgcn_s_setprio(0); } while (0)
; #define PG8_WAIT_V(n) asm volatile("s_waitcnt vmcnt(" #n ")" ::: "memory")
; #define PG8_BAR __builtin_amdgcn_s_barrier()
; template <class Epi, class Sched, bool ALIGN_EPI = false, bool SP2 = false>
; __device__ __forceinline__ void gemm_phase(PG8_LAS unsigned char* lds, const Gemm g, const Sched& S, const Epi& E) {
;     ...
;         for (int t = 0; t < nt; t += 2) {
;             const bool last = (t == nt - 2);
;             const char* a1 = cA + (size_t)(t + 1) * kstep;
;             const char* a2 = last ? nA : cA + (size_t)(t + 2) * kstep; const char* b2 = last ? nB : cB + (size_t)(t + 2) * kstep;
;             const char* a3 = a2 + kstep; const char* b3 = b2 + kstep;
;             if (last && has_next) S.a_ready(nxt);
;             if constexpr (SP2) {
;             PG8_LDB(B0, 0, 0); PG8_LDB(B1, 0, 1); PG8_SCHED; PG8_LDA(At, 0, 0); PG8_STAGE(PG8_SA(1, 1), a1 + hstepA, voffA);
;             PG8_WAIT_V(8); PG8_WAIT_L(0); PG8_BAR; PG8_MMA(0, 0, At, B0); PG8_MMA(0, 1, At, B1); PG8_BAR; PG8_SCHED;
;             PG8_LDA(At, 0, 1); PG8_STAGE(PG8_SB(0, 0), b2, voffB); PG8_STAGE(PG8_SB(0, 1), b2 + hstepB, voffB); PG8_STAGE(PG8_SA(0, 0), a2, voffA);
;             PG8_WAIT_V(8); PG8_WAIT_L(0); PG8_BAR; PG8_MMA(1, 0, At, B0); PG8_MMA(1, 1, At, B1); PG8_BAR; PG8_SCHED;
.LBB0_210:
	ds_read_b128 v[146:149], v155
	ds_read_b128 v[158:161], v155 offset:1024
	ds_read_b128 v[162:165], v155 offset:2048
	ds_read_b128 v[166:169], v155 offset:3072
	ds_read_b128 v[170:173], v156
	ds_read_b128 v[174:177], v156 offset:1024
	ds_read_b128 v[178:181], v156 offset:2048
	ds_read_b128 v[182:185], v156 offset:3072
	s_add_u32 s26, s24, 0xfff00080
	s_addc_u32 s27, s25, -1
	s_cmp_eq_u32 s53, 60
	s_cselect_b32 s29, s17, s27
	s_cselect_b32 s28, s49, s26
	s_cselect_b32 s27, s15, s52
	s_cselect_b32 s26, s50, s51
	v_lshl_add_u64 v[214:215], s[24:25], 0, v[138:139]
	s_add_i32 m0, s23, 0xc000
	ds_read_b128 v[186:189], v157
	ds_read_b128 v[190:193], v157 offset:1024
	ds_read_b128 v[194:197], v157 offset:2048
	ds_read_b128 v[198:201], v157 offset:3072
	ds_read_b128 v[202:205], v157 offset:4096
	ds_read_b128 v[206:209], v157 offset:5120
	ds_read_b128 v[210:213], v157 offset:6144
	ds_read_b128 v[218:221], v157 offset:7168
	global_load_lds_dwordx4 v[214:215], off
	v_lshl_add_u64 v[214:215], s[24:25], 0, v[140:141]
	s_add_i32 m0, s23, 0xe000
	s_nop 0
	global_load_lds_dwordx4 v[214:215], off
	s_waitcnt vmcnt(8)
	s_waitcnt lgkmcnt(0)
	s_barrier
	s_setprio 1
	s_waitcnt lgkmcnt(0)
	v_mfma_f32_16x16x32_bf16 v[126:129], v[146:149], v[186:189], v[126:129]
	v_mfma_f32_16x16x32_bf16 v[122:125], v[162:165], v[186:189], v[122:125]
	v_mfma_f32_16x16x32_bf16 v[118:121], v[146:149], v[194:197], v[118:121]
	v_mfma_f32_16x16x32_bf16 v[114:117], v[162:165], v[194:197], v[114:117]
	v_mfma_f32_16x16x32_bf16 v[106:109], v[146:149], v[202:205], v[106:109]
	v_mfma_f32_16x16x32_bf16 v[98:101], v[162:165], v[202:205], v[98:101]
	v_mfma_f32_16x16x32_bf16 v[78:81], v[146:149], v[210:213], v[78:81]
	v_mfma_f32_16x16x32_bf16 v[74:77], v[162:165], v[210:213], v[74:77]
	v_mfma_f32_16x16x32_bf16 v[126:129], v[158:161], v[190:193], v[126:129]
	v_mfma_f32_16x16x32_bf16 v[122:125], v[166:169], v[190:193], v[122:125]
	v_mfma_f32_16x16x32_bf16 v[118:121], v[158:161], v[198:201], v[118:121]
	v_mfma_f32_16x16x32_bf16 v[114:117], v[166:169], v[198:201], v[114:117]
	v_mfma_f32_16x16x32_bf16 v[106:109], v[158:161], v[206:209], v[106:109]
	v_mfma_f32_16x16x32_bf16 v[98:101], v[166:169], v[206:209], v[98:101]
	v_mfma_f32_16x16x32_bf16 v[78:81], v[158:161], v[218:221], v[78:81]
	v_mfma_f32_16x16x32_bf16 v[74:77], v[166:169], v[218:221], v[74:77]
	s_setprio 0
	s_setprio 1
	v_mfma_f32_16x16x32_bf16 v[110:113], v[170:173], v[186:189], v[110:113]
	v_mfma_f32_16x16x32_bf16 v[102:105], v[178:181], v[186:189], v[102:105]
	v_mfma_f32_16x16x32_bf16 v[94:97], v[170:173], v[194:197], v[94:97]
	v_mfma_f32_16x16x32_bf16 v[90:93], v[178:181], v[194:197], v[90:93]
	v_mfma_f32_16x16x32_bf16 v[86:89], v[170:173], v[202:205], v[86:89]
	v_mfma_f32_16x16x32_bf16 v[82:85], v[178:181], v[202:205], v[82:85]
	v_mfma_f32_16x16x32_bf16 v[70:73], v[170:173], v[210:213], v[70:73]
	v_mfma_f32_16x16x32_bf16 v[66:69], v[178:181], v[210:213], v[66:69]
	v_mfma_f32_16x16x32_bf16 v[110:113], v[174:177], v[190:193], v[110:113]
	v_mfma_f32_16x16x32_bf16 v[102:105], v[182:185], v[190:193], v[102:105]
	v_mfma_f32_16x16x32_bf16 v[94:97], v[174:177], v[198:201], v[94:97]
	v_mfma_f32_16x16x32_bf16 v[90:93], v[182:185], v[198:201], v[90:93]
	v_mfma_f32_16x16x32_bf16 v[86:89], v[174:177], v[206:209], v[86:89]
	v_mfma_f32_16x16x32_bf16 v[82:85], v[182:185], v[206:209], v[82:85]
	v_mfma_f32_16x16x32_bf16 v[70:73], v[174:177], v[218:221], v[70:73]
	v_mfma_f32_16x16x32_bf16 v[66:69], v[182:185], v[218:221], v[66:69]
	s_setprio 0
	s_barrier
	s_add_i32 s54, s45, s35
	v_lshl_add_u64 v[214:215], s[26:27], 0, v[134:135]
	s_mov_b32 m0, s54
	global_load_lds_dwordx4 v[214:215], off
	s_add_i32 m0, s54, 0x2000
	s_add_u32 s54, s26, 0x100000
	v_lshl_add_u64 v[222:223], s[26:27], 0, v[130:131]
	s_addc_u32 s55, s27, 0
	s_add_i32 s56, s46, s35
	global_load_lds_dwordx4 v[222:223], off
	v_lshl_add_u64 v[224:225], s[54:55], 0, v[134:135]
	s_mov_b32 m0, s56
	v_lshl_add_u64 v[226:227], s[28:29], 0, v[132:133]
	global_load_lds_dwordx4 v[224:225], off
	v_lshl_add_u64 v[224:225], s[54:55], 0, v[130:131]
	s_add_i32 m0, s56, 0x2000
	s_nop 0
	global_load_lds_dwordx4 v[224:225], off
	v_lshl_add_u64 v[224:225], s[28:29], 0, v[136:137]
	ds_read_b128 v[186:189], v157 offset:16384
	ds_read_b128 v[190:193], v157 offset:17408
	ds_read_b128 v[194:197], v157 offset:18432
	ds_read_b128 v[198:201], v157 offset:19456
	ds_read_b128 v[202:205], v157 offset:20480
	ds_read_b128 v[206:209], v157 offset:21504
	ds_read_b128 v[210:213], v157 offset:22528
	ds_read_b128 v[218:221], v157 offset:23552
	s_waitcnt vmcnt(6)
	s_waitcnt lgkmcnt(0)
	s_barrier
; #define PG8_STAGE(bufoff, gbase, voff) do { _Pragma("unroll") for (int _i = 0; _i < 2; ++_i) \
;         __builtin_amdgcn_global_load_lds((const unsigned*)((const char*)(gbase) + (voff)[_i]), (PG8_LAS unsigned*)(lds + (bufoff) + ldsw + _i * 8192), 16, 0, 0); } while (0)
; #define PG8_LDA(dst, b, h) do { _Pragma("unroll") for (int m = 0; m < 4; ++m) _Pragma("unroll") for (int k = 0; k < 2; ++k) dst[m][k] = *(const PG8_LAS bf16x8*)(lds + PG8_SA(b, h) + aoff + m * 2048 + k * 1024); } while (0)
; #define PG8_LDB(dst, b, h) do { _Pragma("unroll") for (int n = 0; n < 2; ++n) _Pragma("unroll") for (int k = 0; k < 2; ++k) dst[n][k] = *(const PG8_LAS bf16x8*)(lds + PG8_SB(b, h) + boff + n * 2048 + k * 1024); } while (0)
; #define PG8_MMA(ai, bj, At, Bt) do { __builtin_amdgcn_s_setprio(1); _Pragma("unroll") for (int m = 0; m < 4; ++m) _Pragma("unroll") for (int n = 0; n < 2; ++n) _Pragma("unroll") for (int k = 0; k < 2; ++k) \
;         acc[ai][bj][m][n] = __builtin_amdgcn_mfma_f32_16x16x32_bf16(Bt[n][k], At[m][k], acc[ai][bj][m][n], 0, 0, 0); __builtin_amdgcn_s_setprio(0); } while (0)
; #define PG8_WAIT_V(n) asm volatile("s_waitcnt vmcnt(" #n ")" ::: "memory")
; #define PG8_WAIT_L(n) asm volatile("s_waitcnt lgkmcnt(" #n ")" ::: "memory")
; #define PG8_BAR __builtin_amdgcn_s_barrier()
; #define PG8_SCHED __builtin_amdgcn_sched_barrier(0)
; template <class Epi, class Sched, bool ALIGN_EPI = false, bool SP2 = false>
; __device__ __forceinline__ void gemm_phase(PG8_LAS unsigned char* lds, const Gemm g, const Sched& S, const Epi& E) {
;     ...
;             PG8_WAIT_V(8); PG8_WAIT_L(0); PG8_BAR; PG8_MMA(1, 0, At, B0); PG8_MMA(1, 1, At, B1); PG8_BAR; PG8_SCHED;
;             PG8_LDB(B0, 1, 0); PG8_LDB(B1, 1, 1); PG8_SCHED; PG8_LDA(At, 1, 0); PG8_STAGE(PG8_SA(0, 1), a2 + hstepA, voffA);
;             PG8_WAIT_V(8); PG8_WAIT_L(0); PG8_BAR; PG8_MMA(0, 0, At, B0); PG8_MMA(0, 1, At, B1); PG8_BAR; PG8_SCHED;
	s_setprio 1
	s_waitcnt lgkmcnt(0)
	v_mfma_f32_16x16x32_bf16 v[62:65], v[146:149], v[186:189], v[62:65]
	v_mfma_f32_16x16x32_bf16 v[58:61], v[162:165], v[186:189], v[58:61]
	v_mfma_f32_16x16x32_bf16 v[50:53], v[146:149], v[194:197], v[50:53]
	v_mfma_f32_16x16x32_bf16 v[42:45], v[162:165], v[194:197], v[42:45]
	v_mfma_f32_16x16x32_bf16 v[34:37], v[146:149], v[202:205], v[34:37]
	v_mfma_f32_16x16x32_bf16 v[26:29], v[162:165], v[202:205], v[26:29]
	v_mfma_f32_16x16x32_bf16 v[18:21], v[146:149], v[210:213], v[18:21]
	v_mfma_f32_16x16x32_bf16 v[10:13], v[162:165], v[210:213], v[10:13]
	v_mfma_f32_16x16x32_bf16 v[62:65], v[158:161], v[190:193], v[62:65]
	v_mfma_f32_16x16x32_bf16 v[58:61], v[166:169], v[190:193], v[58:61]
	v_mfma_f32_16x16x32_bf16 v[50:53], v[158:161], v[198:201], v[50:53]
	v_mfma_f32_16x16x32_bf16 v[42:45], v[166:169], v[198:201], v[42:45]
	v_mfma_f32_16x16x32_bf16 v[34:37], v[158:161], v[206:209], v[34:37]
	v_mfma_f32_16x16x32_bf16 v[26:29], v[166:169], v[206:209], v[26:29]
	v_mfma_f32_16x16x32_bf16 v[18:21], v[158:161], v[218:221], v[18:21]
	v_mfma_f32_16x16x32_bf16 v[10:13], v[166:169], v[218:221], v[10:13]
	s_setprio 0
	s_setprio 1
	v_mfma_f32_16x16x32_bf16 v[54:57], v[170:173], v[186:189], v[54:57]
	v_mfma_f32_16x16x32_bf16 v[46:49], v[178:181], v[186:189], v[46:49]
	v_mfma_f32_16x16x32_bf16 v[38:41], v[170:173], v[194:197], v[38:41]
	v_mfma_f32_16x16x32_bf16 v[30:33], v[178:181], v[194:197], v[30:33]
	v_mfma_f32_16x16x32_bf16 v[22:25], v[170:173], v[202:205], v[22:25]
	v_mfma_f32_16x16x32_bf16 v[14:17], v[178:181], v[202:205], v[14:17]
	v_mfma_f32_16x16x32_bf16 v[6:9], v[170:173], v[210:213], v[6:9]
	v_mfma_f32_16x16x32_bf16 v[2:5], v[178:181], v[210:213], v[2:5]
	v_mfma_f32_16x16x32_bf16 v[54:57], v[174:177], v[190:193], v[54:57]
	v_mfma_f32_16x16x32_bf16 v[46:49], v[182:185], v[190:193], v[46:49]
	v_mfma_f32_16x16x32_bf16 v[38:41], v[174:177], v[198:201], v[38:41]
	v_mfma_f32_16x16x32_bf16 v[30:33], v[182:185], v[198:201], v[30:33]
	v_mfma_f32_16x16x32_bf16 v[22:25], v[174:177], v[206:209], v[22:25]
	v_mfma_f32_16x16x32_bf16 v[14:17], v[182:185], v[206:209], v[14:17]
	v_mfma_f32_16x16x32_bf16 v[6:9], v[174:177], v[218:221], v[6:9]
	v_mfma_f32_16x16x32_bf16 v[2:5], v[182:185], v[218:221], v[2:5]
	s_setprio 0
	s_barrier
	s_mov_b32 m0, s23
	s_nop 0
	global_load_lds_dwordx4 v[224:225], off
	s_mov_b32 m0, s38
	s_nop 0
	global_load_lds_dwordx4 v[226:227], off
	s_add_i32 s54, 0, 0x18000
	v_add_u32_e32 v150, s54, v151
	s_add_i32 s55, 0, 0x1c000
	ds_read_b128 v[146:149], v150
	ds_read_b128 v[158:161], v150 offset:1024
	ds_read_b128 v[162:165], v150 offset:2048
	ds_read_b128 v[166:169], v150 offset:3072
	v_add_u32_e32 v150, s55, v151
	ds_read_b128 v[170:173], v150
	ds_read_b128 v[174:177], v150 offset:1024
	ds_read_b128 v[178:181], v150 offset:2048
	ds_read_b128 v[182:185], v150 offset:3072
	s_add_u32 s28, s28, 0x100000
	s_addc_u32 s29, s29, 0
	s_mov_b32 m0, s39
	v_lshl_add_u64 v[228:229], s[28:29], 0, v[136:137]
	ds_read_b128 v[186:189], v157 offset:32768
	ds_read_b128 v[190:193], v157 offset:33792
	ds_read_b128 v[194:197], v157 offset:34816
	ds_read_b128 v[198:201], v157 offset:35840
	ds_read_b128 v[202:205], v157 offset:36864
	ds_read_b128 v[206:209], v157 offset:37888
	ds_read_b128 v[210:213], v157 offset:38912
	ds_read_b128 v[218:221], v157 offset:39936
	global_load_lds_dwordx4 v[228:229], off
	v_lshl_add_u64 v[228:229], s[28:29], 0, v[132:133]
	s_mov_b32 m0, s40
	s_nop 0
	global_load_lds_dwordx4 v[228:229], off
	s_waitcnt vmcnt(8)
	s_waitcnt lgkmcnt(0)
	s_barrier
	s_setprio 1
	s_waitcnt lgkmcnt(0)
	v_mfma_f32_16x16x32_bf16 v[126:129], v[146:149], v[186:189], v[126:129]
	v_mfma_f32_16x16x32_bf16 v[122:125], v[162:165], v[186:189], v[122:125]
	v_mfma_f32_16x16x32_bf16 v[118:121], v[146:149], v[194:197], v[118:121]
	v_mfma_f32_16x16x32_bf16 v[114:117], v[162:165], v[194:197], v[114:117]
	v_mfma_f32_16x16x32_bf16 v[106:109], v[146:149], v[202:205], v[106:109]
	v_mfma_f32_16x16x32_bf16 v[98:101], v[162:165], v[202:205], v[98:101]
	v_mfma_f32_16x16x32_bf16 v[78:81], v[146:149], v[210:213], v[78:81]
	v_mfma_f32_16x16x32_bf16 v[74:77], v[162:165], v[210:213], v[74:77]
	v_mfma_f32_16x16x32_bf16 v[126:129], v[158:161], v[190:193], v[126:129]
	v_mfma_f32_16x16x32_bf16 v[122:125], v[166:169], v[190:193], v[122:125]
	v_mfma_f32_16x16x32_bf16 v[118:121], v[158:161], v[198:201], v[118:121]
	v_mfma_f32_16x16x32_bf16 v[114:117], v[166:169], v[198:201], v[114:117]
	v_mfma_f32_16x16x32_bf16 v[106:109], v[158:161], v[206:209], v[106:109]
	v_mfma_f32_16x16x32_bf16 v[98:101], v[166:169], v[206:209], v[98:101]
	v_mfma_f32_16x16x32_bf16 v[78:81], v[158:161], v[218:221], v[78:81]
	v_mfma_f32_16x16x32_bf16 v[74:77], v[166:169], v[218:221], v[74:77]
	s_setprio 0
	s_setprio 1
	v_mfma_f32_16x16x32_bf16 v[110:113], v[170:173], v[186:189], v[110:113]
	v_mfma_f32_16x16x32_bf16 v[102:105], v[178:181], v[186:189], v[102:105]
	v_mfma_f32_16x16x32_bf16 v[94:97], v[170:173], v[194:197], v[94:97]
	v_mfma_f32_16x16x32_bf16 v[90:93], v[178:181], v[194:197], v[90:93]
	v_mfma_f32_16x16x32_bf16 v[86:89], v[170:173], v[202:205], v[86:89]
	v_mfma_f32_16x16x32_bf16 v[82:85], v[178:181], v[202:205], v[82:85]
	v_mfma_f32_16x16x32_bf16 v[70:73], v[170:173], v[210:213], v[70:73]
	v_mfma_f32_16x16x32_bf16 v[66:69], v[178:181], v[210:213], v[66:69]
	v_mfma_f32_16x16x32_bf16 v[110:113], v[174:177], v[190:193], v[110:113]
	v_mfma_f32_16x16x32_bf16 v[102:105], v[182:185], v[190:193], v[102:105]
	v_mfma_f32_16x16x32_bf16 v[94:97], v[174:177], v[198:201], v[94:97]
	v_mfma_f32_16x16x32_bf16 v[90:93], v[182:185], v[198:201], v[90:93]
	v_mfma_f32_16x16x32_bf16 v[86:89], v[174:177], v[206:209], v[86:89]
	v_mfma_f32_16x16x32_bf16 v[82:85], v[182:185], v[206:209], v[82:85]
	v_mfma_f32_16x16x32_bf16 v[70:73], v[174:177], v[218:221], v[70:73]
	v_mfma_f32_16x16x32_bf16 v[66:69], v[182:185], v[218:221], v[66:69]
	s_setprio 0
	s_barrier
; #define PG8_STAGE(bufoff, gbase, voff) do { _Pragma("unroll") for (int _i = 0; _i < 2; ++_i) \
;         __builtin_amdgcn_global_load_lds((const unsigned*)((const char*)(gbase) + (voff)[_i]), (PG8_LAS unsigned*)(lds + (bufoff) + ldsw + _i * 8192), 16, 0, 0); } while (0)
; #define PG8_LDA(dst, b, h) do { _Pragma("unroll") for (int m = 0; m < 4; ++m) _Pragma("unroll") for (int k = 0; k < 2; ++k) dst[m][k] = *(const PG8_LAS bf16x8*)(lds + PG8_SA(b, h) + aoff + m * 2048 + k * 1024); } while (0)
; #define PG8_MMA(ai, bj, At, Bt) do { __builtin_amdgcn_s_setprio(1); _Pragma("unroll") for (int m = 0; m < 4; ++m) _Pragma("unroll") for (int n = 0; n < 2; ++n) _Pragma("unroll") for (int k = 0; k < 2; ++k) \
;         acc[ai][bj][m][n] = __builtin_amdgcn_mfma_f32_16x16x32_bf16(Bt[n][k], At[m][k], acc[ai][bj][m][n], 0, 0, 0); __builtin_amdgcn_s_setprio(0); } while (0)
; #define PG8_WAIT_V(n) asm volatile("s_waitcnt vmcnt(" #n ")" ::: "memory")
; #define PG8_WAIT_L(n) asm volatile("s_waitcnt lgkmcnt(" #n ")" ::: "memory")
; #define PG8_BAR __builtin_amdgcn_s_barrier()
; #define PG8_SCHED __builtin_amdgcn_sched_barrier(0)
; template <class Epi, class Sched, bool ALIGN_EPI = false, bool SP2 = false>
; __device__ __forceinline__ void gemm_phase(PG8_LAS unsigned char* lds, const Gemm g, const Sched& S, const Epi& E) {
;     ...
;         for (int t = 0; t < nt; t += 2) {
;             const bool last = (t == nt - 2);
;             const char* a1 = cA + (size_t)(t + 1) * kstep;
;             const char* a2 = last ? nA : cA + (size_t)(t + 2) * kstep; const char* b2 = last ? nB : cB + (size_t)(t + 2) * kstep;
;             const char* a3 = a2 + kstep; const char* b3 = b2 + kstep;
;     ...
;             PG8_LDA(At, 1, 1); PG8_STAGE(PG8_SB(1, 0), b3, voffB); PG8_STAGE(PG8_SB(1, 1), b3 + hstepB, voffB); PG8_STAGE(PG8_SA(1, 0), a3, voffA);
;             PG8_WAIT_V(8); PG8_WAIT_L(0); PG8_BAR; PG8_MMA(1, 0, At, B0); PG8_MMA(1, 1, At, B1); PG8_BAR; PG8_SCHED;
	s_add_i32 s28, s54, s35
	v_lshl_add_u64 v[214:215], v[214:215], 0, s[10:11]
	s_mov_b32 m0, s28
	global_load_lds_dwordx4 v[214:215], off
	s_add_i32 m0, s28, 0x2000
	s_add_u32 s26, s26, 0x100080
	v_lshl_add_u64 v[214:215], v[222:223], 0, s[10:11]
	s_addc_u32 s27, s27, 0
	s_add_i32 s28, s55, s35
	global_load_lds_dwordx4 v[214:215], off
	v_lshl_add_u64 v[214:215], s[26:27], 0, v[134:135]
	s_mov_b32 m0, s28
	s_nop 0
	global_load_lds_dwordx4 v[214:215], off
	v_lshl_add_u64 v[214:215], s[26:27], 0, v[130:131]
	s_add_i32 m0, s28, 0x2000
	s_nop 0
	global_load_lds_dwordx4 v[214:215], off
	ds_read_b128 v[186:189], v157 offset:49152
	ds_read_b128 v[190:193], v157 offset:50176
	ds_read_b128 v[194:197], v157 offset:51200
	ds_read_b128 v[198:201], v157 offset:52224
	ds_read_b128 v[202:205], v157 offset:53248
	ds_read_b128 v[206:209], v157 offset:54272
	ds_read_b128 v[210:213], v157 offset:55296
	ds_read_b128 v[218:221], v157 offset:56320
	s_waitcnt vmcnt(6)
	s_waitcnt lgkmcnt(0)
	s_barrier
	s_setprio 1
	s_waitcnt lgkmcnt(0)
	v_mfma_f32_16x16x32_bf16 v[62:65], v[146:149], v[186:189], v[62:65]
	v_mfma_f32_16x16x32_bf16 v[58:61], v[162:165], v[186:189], v[58:61]
	v_mfma_f32_16x16x32_bf16 v[50:53], v[146:149], v[194:197], v[50:53]
	v_mfma_f32_16x16x32_bf16 v[42:45], v[162:165], v[194:197], v[42:45]
	v_mfma_f32_16x16x32_bf16 v[34:37], v[146:149], v[202:205], v[34:37]
	v_mfma_f32_16x16x32_bf16 v[26:29], v[162:165], v[202:205], v[26:29]
	v_mfma_f32_16x16x32_bf16 v[18:21], v[146:149], v[210:213], v[18:21]
	v_mfma_f32_16x16x32_bf16 v[10:13], v[162:165], v[210:213], v[10:13]
	v_mfma_f32_16x16x32_bf16 v[62:65], v[158:161], v[190:193], v[62:65]
	v_mfma_f32_16x16x32_bf16 v[58:61], v[166:169], v[190:193], v[58:61]
	v_mfma_f32_16x16x32_bf16 v[50:53], v[158:161], v[198:201], v[50:53]
	v_mfma_f32_16x16x32_bf16 v[42:45], v[166:169], v[198:201], v[42:45]
	v_mfma_f32_16x16x32_bf16 v[34:37], v[158:161], v[206:209], v[34:37]
	v_mfma_f32_16x16x32_bf16 v[26:29], v[166:169], v[206:209], v[26:29]
	v_mfma_f32_16x16x32_bf16 v[18:21], v[158:161], v[218:221], v[18:21]
	v_mfma_f32_16x16x32_bf16 v[10:13], v[166:169], v[218:221], v[10:13]
	s_setprio 0
	s_setprio 1
	v_mfma_f32_16x16x32_bf16 v[54:57], v[170:173], v[186:189], v[54:57]
	v_mfma_f32_16x16x32_bf16 v[46:49], v[178:181], v[186:189], v[46:49]
	v_mfma_f32_16x16x32_bf16 v[38:41], v[170:173], v[194:197], v[38:41]
	v_mfma_f32_16x16x32_bf16 v[30:33], v[178:181], v[194:197], v[30:33]
	v_mfma_f32_16x16x32_bf16 v[22:25], v[170:173], v[202:205], v[22:25]
	v_mfma_f32_16x16x32_bf16 v[14:17], v[178:181], v[202:205], v[14:17]
	v_mfma_f32_16x16x32_bf16 v[6:9], v[170:173], v[210:213], v[6:9]
	v_mfma_f32_16x16x32_bf16 v[2:5], v[178:181], v[210:213], v[2:5]
	v_mfma_f32_16x16x32_bf16 v[54:57], v[174:177], v[190:193], v[54:57]
	v_mfma_f32_16x16x32_bf16 v[46:49], v[182:185], v[190:193], v[46:49]
	v_mfma_f32_16x16x32_bf16 v[38:41], v[174:177], v[198:201], v[38:41]
	v_mfma_f32_16x16x32_bf16 v[30:33], v[182:185], v[198:201], v[30:33]
	v_mfma_f32_16x16x32_bf16 v[22:25], v[174:177], v[206:209], v[22:25]
	v_mfma_f32_16x16x32_bf16 v[14:17], v[182:185], v[206:209], v[14:17]
	v_mfma_f32_16x16x32_bf16 v[6:9], v[174:177], v[218:221], v[6:9]
	v_mfma_f32_16x16x32_bf16 v[2:5], v[182:185], v[218:221], v[2:5]
	s_setprio 0
	s_barrier
	v_lshl_add_u64 v[214:215], v[224:225], 0, s[10:11]
	s_mov_b32 m0, s42
	s_nop 0
	global_load_lds_dwordx4 v[214:215], off
	v_lshl_add_u64 v[214:215], v[226:227], 0, s[10:11]
	s_mov_b32 m0, s43
	s_nop 0
	global_load_lds_dwordx4 v[214:215], off
	s_add_i32 s53, s53, 2
	s_add_u32 s24, s24, 0x100
	s_addc_u32 s25, s25, 0
	s_add_u32 s51, s51, 0x100
	s_addc_u32 s52, s52, 0
	s_cmp_gt_u32 s53, 61
	s_cbranch_scc0 .LBB0_210
	s_and_b64 vcc, exec, s[12:13]
	s_cbranch_vccz .LBB0_213
	s_barrier

; #define PG8_STAGE(bufoff, gbase, voff) do { _Pragma("unroll") for (int _i = 0; _i < 2; ++_i) \
;         __builtin_amdgcn_global_load_lds((const unsigned*)((const char*)(gbase) + (voff)[_i]), (PG8_LAS unsigned*)(lds + (bufoff) + ldsw + _i * 8192), 16, 0, 0); } while (0)
; #define PG8_LDA(dst, b, h) do { _Pragma("unroll") for (int m = 0; m < 4; ++m) _Pragma("unroll") for (int k = 0; k < 2; ++k) dst[m][k] = *(const PG8_LAS bf16x8*)(lds + PG8_SA(b, h) + aoff + m * 2048 + k * 1024); } while (0)
; #define PG8_LDB(dst, b, h) do { _Pragma("unroll") for (int n = 0; n < 2; ++n) _Pragma("unroll") for (int k = 0; k < 2; ++k) dst[n][k] = *(const PG8_LAS bf16x8*)(lds + PG8_SB(b, h) + boff + n * 2048 + k * 1024); } while (0)
; #define PG8_MMA(ai, bj, At, Bt) do { __builtin_amdgcn_s_setprio(1); _Pragma("unroll") for (int m = 0; m < 4; ++m) _Pragma("unroll") for (int n = 0; n < 2; ++n) _Pragma("unroll") for (int k = 0; k < 2; ++k) \
;         acc[ai][bj][m][n] = __builtin_amdgcn_mfma_f32_16x16x32_bf16(Bt[n][k], At[m][k], acc[ai][bj][m][n], 0, 0, 0); __builtin_amdgcn_s_setprio(0); } while (0)
; #define PG8_WAIT_V(n) asm volatile("s_waitcnt vmcnt(" #n ")" ::: "memory")
; #define PG8_WAIT_L(n) asm volatile("s_waitcnt lgkmcnt(" #n ")" ::: "memory")
; #define PG8_BAR __builtin_amdgcn_s_barrier()
; #define PG8_SCHED __builtin_amdgcn_sched_barrier(0)
; template <class Epi, class Sched, bool ALIGN_EPI = false, bool SP2 = false>
; __device__ __forceinline__ void gemm_phase(PG8_LAS unsigned char* lds, const Gemm g, const Sched& S, const Epi& E) {
;     ...
;         for (int t = 0; t < nt; t += 2) {
;             const bool last = (t == nt - 2);
;             const char* a1 = cA + (size_t)(t + 1) * kstep;
;             const char* a2 = last ? nA : cA + (size_t)(t + 2) * kstep; const char* b2 = last ? nB : cB + (size_t)(t + 2) * kstep;
;             const char* a3 = a2 + kstep; const char* b3 = b2 + kstep;
;             if (last && has_next) S.a_ready(nxt);
;             if constexpr (SP2) {
;             PG8_LDB(B0, 0, 0); PG8_LDB(B1, 0, 1); PG8_SCHED; PG8_LDA(At, 0, 0); PG8_STAGE(PG8_SA(1, 1), a1 + hstepA, voffA);
;             PG8_WAIT_V(8); PG8_WAIT_L(0); PG8_BAR; PG8_MMA(0, 0, At, B0); PG8_MMA(0, 1, At, B1); PG8_BAR; PG8_SCHED;
;             PG8_LDA(At, 0, 1); PG8_STAGE(PG8_SB(0, 0), b2, voffB); PG8_STAGE(PG8_SB(0, 1), b2 + hstepB, voffB); PG8_STAGE(PG8_SA(0, 0), a2, voffA);
.LBB0_241:
	s_lshl_b32 s26, s54, 7
	s_add_u32 s27, s16, s26
	s_addc_u32 s28, s17, 0
	v_add_u32_e32 v170, s46, v1
	s_add_u32 s29, s27, 0x100
	ds_read_b128 v[178:181], v170
	ds_read_b128 v[182:185], v170 offset:1024
	ds_read_b128 v[186:189], v170 offset:2048
	ds_read_b128 v[190:193], v170 offset:3072
	v_add_u32_e32 v170, s47, v1
	s_addc_u32 s55, s28, 0
	ds_read_b128 v[194:197], v170
	ds_read_b128 v[198:201], v170 offset:1024
	ds_read_b128 v[202:205], v170 offset:2048
	ds_read_b128 v[206:209], v170 offset:3072
	s_and_b64 s[24:25], s[22:23], exec
	s_cselect_b32 s25, s50, s55
	s_cselect_b32 s24, s51, s29
	s_add_u32 s26, s18, s26
	s_addc_u32 s29, s19, 0
	s_add_u32 s26, s26, 0x100
	s_addc_u32 s29, s29, 0
	s_and_b64 s[22:23], s[22:23], exec
	s_cselect_b32 s23, s52, s29
	s_cselect_b32 s22, s53, s26
	s_add_u32 s26, s27, 0x100080
	s_addc_u32 s27, s28, 0
	v_lshl_add_u64 v[214:215], s[26:27], 0, v[132:133]
	s_add_i32 m0, s1, 0xc000
	ds_read_b128 v[210:213], v175
	ds_read_b128 v[218:221], v175 offset:1024
	ds_read_b128 v[222:225], v175 offset:2048
	ds_read_b128 v[226:229], v175 offset:3072
	ds_read_b128 v[230:233], v175 offset:4096
	ds_read_b128 v[234:237], v175 offset:5120
	ds_read_b128 v[238:241], v175 offset:6144
	ds_read_b128 v[242:245], v175 offset:7168
	global_load_lds_dwordx4 v[214:215], off
	v_lshl_add_u64 v[214:215], s[26:27], 0, v[134:135]
	s_add_i32 m0, s1, 0xe000
	s_nop 0
	global_load_lds_dwordx4 v[214:215], off
	s_waitcnt vmcnt(8)
	s_waitcnt lgkmcnt(0)
	s_barrier
	s_setprio 1
	s_waitcnt lgkmcnt(0)
	v_mfma_f32_16x16x32_bf16 v[126:129], v[178:181], v[210:213], v[126:129]
	v_mfma_f32_16x16x32_bf16 v[122:125], v[186:189], v[210:213], v[122:125]
	v_mfma_f32_16x16x32_bf16 v[118:121], v[178:181], v[222:225], v[118:121]
	v_mfma_f32_16x16x32_bf16 v[114:117], v[186:189], v[222:225], v[114:117]
	v_mfma_f32_16x16x32_bf16 v[110:113], v[178:181], v[230:233], v[110:113]
	v_mfma_f32_16x16x32_bf16 v[102:105], v[186:189], v[230:233], v[102:105]
	v_mfma_f32_16x16x32_bf16 v[94:97], v[178:181], v[238:241], v[94:97]
	v_mfma_f32_16x16x32_bf16 v[86:89], v[186:189], v[238:241], v[86:89]
	v_mfma_f32_16x16x32_bf16 v[126:129], v[182:185], v[218:221], v[126:129]
	v_mfma_f32_16x16x32_bf16 v[122:125], v[190:193], v[218:221], v[122:125]
	v_mfma_f32_16x16x32_bf16 v[118:121], v[182:185], v[226:229], v[118:121]
	v_mfma_f32_16x16x32_bf16 v[114:117], v[190:193], v[226:229], v[114:117]
	v_mfma_f32_16x16x32_bf16 v[110:113], v[182:185], v[234:237], v[110:113]
	v_mfma_f32_16x16x32_bf16 v[102:105], v[190:193], v[234:237], v[102:105]
	v_mfma_f32_16x16x32_bf16 v[94:97], v[182:185], v[242:245], v[94:97]
	v_mfma_f32_16x16x32_bf16 v[86:89], v[190:193], v[242:245], v[86:89]
	s_setprio 0
	s_setprio 1
	v_mfma_f32_16x16x32_bf16 v[106:109], v[194:197], v[210:213], v[106:109]
	v_mfma_f32_16x16x32_bf16 v[98:101], v[202:205], v[210:213], v[98:101]
	v_mfma_f32_16x16x32_bf16 v[90:93], v[194:197], v[222:225], v[90:93]
	v_mfma_f32_16x16x32_bf16 v[82:85], v[202:205], v[222:225], v[82:85]
	v_mfma_f32_16x16x32_bf16 v[78:81], v[194:197], v[230:233], v[78:81]
	v_mfma_f32_16x16x32_bf16 v[74:77], v[202:205], v[230:233], v[74:77]
	v_mfma_f32_16x16x32_bf16 v[70:73], v[194:197], v[238:241], v[70:73]
	v_mfma_f32_16x16x32_bf16 v[66:69], v[202:205], v[238:241], v[66:69]
	v_mfma_f32_16x16x32_bf16 v[106:109], v[198:201], v[218:221], v[106:109]
	v_mfma_f32_16x16x32_bf16 v[98:101], v[206:209], v[218:221], v[98:101]
	v_mfma_f32_16x16x32_bf16 v[90:93], v[198:201], v[226:229], v[90:93]
	v_mfma_f32_16x16x32_bf16 v[82:85], v[206:209], v[226:229], v[82:85]
	v_mfma_f32_16x16x32_bf16 v[78:81], v[198:201], v[234:237], v[78:81]
	v_mfma_f32_16x16x32_bf16 v[74:77], v[206:209], v[234:237], v[74:77]
	v_mfma_f32_16x16x32_bf16 v[70:73], v[198:201], v[242:245], v[70:73]
	v_mfma_f32_16x16x32_bf16 v[66:69], v[206:209], v[242:245], v[66:69]
	s_setprio 0
	s_barrier
	s_add_i32 s26, s46, s39
	v_lshl_add_u64 v[214:215], s[22:23], 0, v[130:131]
	s_mov_b32 m0, s26
	global_load_lds_dwordx4 v[214:215], off
	s_add_i32 m0, s26, 0x2000
	s_add_u32 s26, s22, 0x100000
	v_lshl_add_u64 v[246:247], s[22:23], 0, v[136:137]
	s_addc_u32 s27, s23, 0
	s_add_i32 s28, s47, s39
	global_load_lds_dwordx4 v[246:247], off
	v_lshl_add_u64 v[248:249], s[26:27], 0, v[130:131]
	s_mov_b32 m0, s28
	v_lshl_add_u64 v[250:251], s[24:25], 0, v[134:135]
	global_load_lds_dwordx4 v[248:249], off
	v_lshl_add_u64 v[248:249], s[26:27], 0, v[136:137]
	s_add_i32 m0, s28, 0x2000
	s_nop 0
	global_load_lds_dwordx4 v[248:249], off
	v_lshl_add_u64 v[248:249], s[24:25], 0, v[132:133]
	ds_read_b128 v[210:213], v175 offset:16384
	ds_read_b128 v[218:221], v175 offset:17408
	ds_read_b128 v[222:225], v175 offset:18432
	ds_read_b128 v[226:229], v175 offset:19456
	ds_read_b128 v[230:233], v175 offset:20480
	ds_read_b128 v[234:237], v175 offset:21504
	ds_read_b128 v[238:241], v175 offset:22528
	ds_read_b128 v[242:245], v175 offset:23552
	s_waitcnt vmcnt(6)
	s_waitcnt lgkmcnt(0)
	s_barrier
; #define PG8_STAGE(bufoff, gbase, voff) do { _Pragma("unroll") for (int _i = 0; _i < 2; ++_i) \
;         __builtin_amdgcn_global_load_lds((const unsigned*)((const char*)(gbase) + (voff)[_i]), (PG8_LAS unsigned*)(lds + (bufoff) + ldsw + _i * 8192), 16, 0, 0); } while (0)
; #define PG8_LDA(dst, b, h) do { _Pragma("unroll") for (int m = 0; m < 4; ++m) _Pragma("unroll") for (int k = 0; k < 2; ++k) dst[m][k] = *(const PG8_LAS bf16x8*)(lds + PG8_SA(b, h) + aoff + m * 2048 + k * 1024); } while (0)
; #define PG8_LDB(dst, b, h) do { _Pragma("unroll") for (int n = 0; n < 2; ++n) _Pragma("unroll") for (int k = 0; k < 2; ++k) dst[n][k] = *(const PG8_LAS bf16x8*)(lds + PG8_SB(b, h) + boff + n * 2048 + k * 1024); } while (0)
; #define PG8_MMA(ai, bj, At, Bt) do { __builtin_amdgcn_s_setprio(1); _Pragma("unroll") for (int m = 0; m < 4; ++m) _Pragma("unroll") for (int n = 0; n < 2; ++n) _Pragma("unroll") for (int k = 0; k < 2; ++k) \
;         acc[ai][bj][m][n] = __builtin_amdgcn_mfma_f32_16x16x32_bf16(Bt[n][k], At[m][k], acc[ai][bj][m][n], 0, 0, 0); __builtin_amdgcn_s_setprio(0); } while (0)
; #define PG8_WAIT_V(n) asm volatile("s_waitcnt vmcnt(" #n ")" ::: "memory")
; #define PG8_WAIT_L(n) asm volatile("s_waitcnt lgkmcnt(" #n ")" ::: "memory")
; #define PG8_BAR __builtin_amdgcn_s_barrier()
; #define PG8_SCHED __builtin_amdgcn_sched_barrier(0)
; template <class Epi, class Sched, bool ALIGN_EPI = false, bool SP2 = false>
; __device__ __forceinline__ void gemm_phase(PG8_LAS unsigned char* lds, const Gemm g, const Sched& S, const Epi& E) {
;     ...
;             PG8_WAIT_V(8); PG8_WAIT_L(0); PG8_BAR; PG8_MMA(1, 0, At, B0); PG8_MMA(1, 1, At, B1); PG8_BAR; PG8_SCHED;
;             PG8_LDB(B0, 1, 0); PG8_LDB(B1, 1, 1); PG8_SCHED; PG8_LDA(At, 1, 0); PG8_STAGE(PG8_SA(0, 1), a2 + hstepA, voffA);
;             PG8_WAIT_V(8); PG8_WAIT_L(0); PG8_BAR; PG8_MMA(0, 0, At, B0); PG8_MMA(0, 1, At, B1); PG8_BAR; PG8_SCHED;
	s_setprio 1
	s_waitcnt lgkmcnt(0)
	v_mfma_f32_16x16x32_bf16 v[62:65], v[178:181], v[210:213], v[62:65]
	v_mfma_f32_16x16x32_bf16 v[58:61], v[186:189], v[210:213], v[58:61]
	v_mfma_f32_16x16x32_bf16 v[50:53], v[178:181], v[222:225], v[50:53]
	v_mfma_f32_16x16x32_bf16 v[42:45], v[186:189], v[222:225], v[42:45]
	v_mfma_f32_16x16x32_bf16 v[34:37], v[178:181], v[230:233], v[34:37]
	v_mfma_f32_16x16x32_bf16 v[26:29], v[186:189], v[230:233], v[26:29]
	v_mfma_f32_16x16x32_bf16 v[18:21], v[178:181], v[238:241], v[18:21]
	v_mfma_f32_16x16x32_bf16 v[10:13], v[186:189], v[238:241], v[10:13]
	v_mfma_f32_16x16x32_bf16 v[62:65], v[182:185], v[218:221], v[62:65]
	v_mfma_f32_16x16x32_bf16 v[58:61], v[190:193], v[218:221], v[58:61]
	v_mfma_f32_16x16x32_bf16 v[50:53], v[182:185], v[226:229], v[50:53]
	v_mfma_f32_16x16x32_bf16 v[42:45], v[190:193], v[226:229], v[42:45]
	v_mfma_f32_16x16x32_bf16 v[34:37], v[182:185], v[234:237], v[34:37]
	v_mfma_f32_16x16x32_bf16 v[26:29], v[190:193], v[234:237], v[26:29]
	v_mfma_f32_16x16x32_bf16 v[18:21], v[182:185], v[242:245], v[18:21]
	v_mfma_f32_16x16x32_bf16 v[10:13], v[190:193], v[242:245], v[10:13]
	s_setprio 0
	s_setprio 1
	v_mfma_f32_16x16x32_bf16 v[54:57], v[194:197], v[210:213], v[54:57]
	v_mfma_f32_16x16x32_bf16 v[46:49], v[202:205], v[210:213], v[46:49]
	v_mfma_f32_16x16x32_bf16 v[38:41], v[194:197], v[222:225], v[38:41]
	v_mfma_f32_16x16x32_bf16 v[30:33], v[202:205], v[222:225], v[30:33]
	v_mfma_f32_16x16x32_bf16 v[22:25], v[194:197], v[230:233], v[22:25]
	v_mfma_f32_16x16x32_bf16 v[14:17], v[202:205], v[230:233], v[14:17]
	v_mfma_f32_16x16x32_bf16 v[6:9], v[194:197], v[238:241], v[6:9]
	v_mfma_f32_16x16x32_bf16 v[2:5], v[202:205], v[238:241], v[2:5]
	v_mfma_f32_16x16x32_bf16 v[54:57], v[198:201], v[218:221], v[54:57]
	v_mfma_f32_16x16x32_bf16 v[46:49], v[206:209], v[218:221], v[46:49]
	v_mfma_f32_16x16x32_bf16 v[38:41], v[198:201], v[226:229], v[38:41]
	v_mfma_f32_16x16x32_bf16 v[30:33], v[206:209], v[226:229], v[30:33]
	v_mfma_f32_16x16x32_bf16 v[22:25], v[198:201], v[234:237], v[22:25]
	v_mfma_f32_16x16x32_bf16 v[14:17], v[206:209], v[234:237], v[14:17]
	v_mfma_f32_16x16x32_bf16 v[6:9], v[198:201], v[242:245], v[6:9]
	v_mfma_f32_16x16x32_bf16 v[2:5], v[206:209], v[242:245], v[2:5]
	s_setprio 0
	s_barrier
	s_mov_b32 m0, s1
	s_nop 0
	global_load_lds_dwordx4 v[248:249], off
	s_mov_b32 m0, s40
	s_nop 0
	global_load_lds_dwordx4 v[250:251], off
	s_add_i32 s26, 0, 0x18000
	v_add_u32_e32 v170, s26, v1
	s_add_i32 s27, 0, 0x1c000
	ds_read_b128 v[178:181], v170
	ds_read_b128 v[182:185], v170 offset:1024
	ds_read_b128 v[186:189], v170 offset:2048
	ds_read_b128 v[190:193], v170 offset:3072
	v_add_u32_e32 v170, s27, v1
	ds_read_b128 v[194:197], v170
	ds_read_b128 v[198:201], v170 offset:1024
	ds_read_b128 v[202:205], v170 offset:2048
	ds_read_b128 v[206:209], v170 offset:3072
	s_add_u32 s24, s24, 0x100000
	s_addc_u32 s25, s25, 0
	s_mov_b32 m0, s41
	v_lshl_add_u64 v[252:253], s[24:25], 0, v[132:133]
	ds_read_b128 v[210:213], v175 offset:32768
	ds_read_b128 v[218:221], v175 offset:33792
	ds_read_b128 v[222:225], v175 offset:34816
	ds_read_b128 v[226:229], v175 offset:35840
	ds_read_b128 v[230:233], v175 offset:36864
	ds_read_b128 v[234:237], v175 offset:37888
	ds_read_b128 v[238:241], v175 offset:38912
	ds_read_b128 v[242:245], v175 offset:39936
	global_load_lds_dwordx4 v[252:253], off
	v_lshl_add_u64 v[252:253], s[24:25], 0, v[134:135]
	s_mov_b32 m0, s42
	s_nop 0
	global_load_lds_dwordx4 v[252:253], off
	s_waitcnt vmcnt(8)
	s_waitcnt lgkmcnt(0)
	s_barrier
	s_setprio 1
	s_waitcnt lgkmcnt(0)
	v_mfma_f32_16x16x32_bf16 v[126:129], v[178:181], v[210:213], v[126:129]
	v_mfma_f32_16x16x32_bf16 v[122:125], v[186:189], v[210:213], v[122:125]
	v_mfma_f32_16x16x32_bf16 v[118:121], v[178:181], v[222:225], v[118:121]
	v_mfma_f32_16x16x32_bf16 v[114:117], v[186:189], v[222:225], v[114:117]
	v_mfma_f32_16x16x32_bf16 v[110:113], v[178:181], v[230:233], v[110:113]
	v_mfma_f32_16x16x32_bf16 v[102:105], v[186:189], v[230:233], v[102:105]
	v_mfma_f32_16x16x32_bf16 v[94:97], v[178:181], v[238:241], v[94:97]
	v_mfma_f32_16x16x32_bf16 v[86:89], v[186:189], v[238:241], v[86:89]
	v_mfma_f32_16x16x32_bf16 v[126:129], v[182:185], v[218:221], v[126:129]
	v_mfma_f32_16x16x32_bf16 v[122:125], v[190:193], v[218:221], v[122:125]
	v_mfma_f32_16x16x32_bf16 v[118:121], v[182:185], v[226:229], v[118:121]
	v_mfma_f32_16x16x32_bf16 v[114:117], v[190:193], v[226:229], v[114:117]
	v_mfma_f32_16x16x32_bf16 v[110:113], v[182:185], v[234:237], v[110:113]
	v_mfma_f32_16x16x32_bf16 v[102:105], v[190:193], v[234:237], v[102:105]
	v_mfma_f32_16x16x32_bf16 v[94:97], v[182:185], v[242:245], v[94:97]
	v_mfma_f32_16x16x32_bf16 v[86:89], v[190:193], v[242:245], v[86:89]
	s_setprio 0
	s_setprio 1
	v_mfma_f32_16x16x32_bf16 v[106:109], v[194:197], v[210:213], v[106:109]
	v_mfma_f32_16x16x32_bf16 v[98:101], v[202:205], v[210:213], v[98:101]
	v_mfma_f32_16x16x32_bf16 v[90:93], v[194:197], v[222:225], v[90:93]
	v_mfma_f32_16x16x32_bf16 v[82:85], v[202:205], v[222:225], v[82:85]
	v_mfma_f32_16x16x32_bf16 v[78:81], v[194:197], v[230:233], v[78:81]
	v_mfma_f32_16x16x32_bf16 v[74:77], v[202:205], v[230:233], v[74:77]
	v_mfma_f32_16x16x32_bf16 v[70:73], v[194:197], v[238:241], v[70:73]
	v_mfma_f32_16x16x32_bf16 v[66:69], v[202:205], v[238:241], v[66:69]
	v_mfma_f32_16x16x32_bf16 v[106:109], v[198:201], v[218:221], v[106:109]
	v_mfma_f32_16x16x32_bf16 v[98:101], v[206:209], v[218:221], v[98:101]
	v_mfma_f32_16x16x32_bf16 v[90:93], v[198:201], v[226:229], v[90:93]
	v_mfma_f32_16x16x32_bf16 v[82:85], v[206:209], v[226:229], v[82:85]
	v_mfma_f32_16x16x32_bf16 v[78:81], v[198:201], v[234:237], v[78:81]
	v_mfma_f32_16x16x32_bf16 v[74:77], v[206:209], v[234:237], v[74:77]
	v_mfma_f32_16x16x32_bf16 v[70:73], v[198:201], v[242:245], v[70:73]
	v_mfma_f32_16x16x32_bf16 v[66:69], v[206:209], v[242:245], v[66:69]
	s_setprio 0
	s_barrier
; #define PG8_STAGE(bufoff, gbase, voff) do { _Pragma("unroll") for (int _i = 0; _i < 2; ++_i) \
;         __builtin_amdgcn_global_load_lds((const unsigned*)((const char*)(gbase) + (voff)[_i]), (PG8_LAS unsigned*)(lds + (bufoff) + ldsw + _i * 8192), 16, 0, 0); } while (0)
; #define PG8_LDA(dst, b, h) do { _Pragma("unroll") for (int m = 0; m < 4; ++m) _Pragma("unroll") for (int k = 0; k < 2; ++k) dst[m][k] = *(const PG8_LAS bf16x8*)(lds + PG8_SA(b, h) + aoff + m * 2048 + k * 1024); } while (0)
; #define PG8_MMA(ai, bj, At, Bt) do { __builtin_amdgcn_s_setprio(1); _Pragma("unroll") for (int m = 0; m < 4; ++m) _Pragma("unroll") for (int n = 0; n < 2; ++n) _Pragma("unroll") for (int k = 0; k < 2; ++k) \
;         acc[ai][bj][m][n] = __builtin_amdgcn_mfma_f32_16x16x32_bf16(Bt[n][k], At[m][k], acc[ai][bj][m][n], 0, 0, 0); __builtin_amdgcn_s_setprio(0); } while (0)
; #define PG8_WAIT_V(n) asm volatile("s_waitcnt vmcnt(" #n ")" ::: "memory")
; #define PG8_WAIT_L(n) asm volatile("s_waitcnt lgkmcnt(" #n ")" ::: "memory")
; #define PG8_BAR __builtin_amdgcn_s_barrier()
; #define PG8_SCHED __builtin_amdgcn_sched_barrier(0)
; template <class Epi, class Sched, bool ALIGN_EPI = false, bool SP2 = false>
; __device__ __forceinline__ void gemm_phase(PG8_LAS unsigned char* lds, const Gemm g, const Sched& S, const Epi& E) {
;     ...
;         for (int t = 0; t < nt; t += 2) {
;             const bool last = (t == nt - 2);
;     ...
;             PG8_LDA(At, 1, 1); PG8_STAGE(PG8_SB(1, 0), b3, voffB); PG8_STAGE(PG8_SB(1, 1), b3 + hstepB, voffB); PG8_STAGE(PG8_SA(1, 0), a3, voffA);
;             PG8_WAIT_V(8); PG8_WAIT_L(0); PG8_BAR; PG8_MMA(1, 0, At, B0); PG8_MMA(1, 1, At, B1); PG8_BAR; PG8_SCHED;
	s_add_i32 s24, s26, s39
	v_lshl_add_u64 v[214:215], v[214:215], 0, s[10:11]
	s_mov_b32 m0, s24
	global_load_lds_dwordx4 v[214:215], off
	s_add_i32 m0, s24, 0x2000
	s_add_u32 s22, s22, 0x100080
	v_lshl_add_u64 v[214:215], v[246:247], 0, s[10:11]
	s_addc_u32 s23, s23, 0
	s_add_i32 s24, s27, s39
	global_load_lds_dwordx4 v[214:215], off
	v_lshl_add_u64 v[214:215], s[22:23], 0, v[130:131]
	s_mov_b32 m0, s24
	s_nop 0
	global_load_lds_dwordx4 v[214:215], off
	v_lshl_add_u64 v[214:215], s[22:23], 0, v[136:137]
	s_add_i32 m0, s24, 0x2000
	s_nop 0
	global_load_lds_dwordx4 v[214:215], off
	ds_read_b128 v[210:213], v175 offset:49152
	ds_read_b128 v[218:221], v175 offset:50176
	ds_read_b128 v[222:225], v175 offset:51200
	ds_read_b128 v[226:229], v175 offset:52224
	ds_read_b128 v[230:233], v175 offset:53248
	ds_read_b128 v[234:237], v175 offset:54272
	ds_read_b128 v[238:241], v175 offset:55296
	ds_read_b128 v[242:245], v175 offset:56320
	s_waitcnt vmcnt(6)
	s_waitcnt lgkmcnt(0)
	s_barrier
	s_setprio 1
	s_waitcnt lgkmcnt(0)
	v_mfma_f32_16x16x32_bf16 v[62:65], v[178:181], v[210:213], v[62:65]
	v_mfma_f32_16x16x32_bf16 v[58:61], v[186:189], v[210:213], v[58:61]
	v_mfma_f32_16x16x32_bf16 v[50:53], v[178:181], v[222:225], v[50:53]
	v_mfma_f32_16x16x32_bf16 v[42:45], v[186:189], v[222:225], v[42:45]
	v_mfma_f32_16x16x32_bf16 v[34:37], v[178:181], v[230:233], v[34:37]
	v_mfma_f32_16x16x32_bf16 v[26:29], v[186:189], v[230:233], v[26:29]
	v_mfma_f32_16x16x32_bf16 v[18:21], v[178:181], v[238:241], v[18:21]
	v_mfma_f32_16x16x32_bf16 v[10:13], v[186:189], v[238:241], v[10:13]
	v_mfma_f32_16x16x32_bf16 v[62:65], v[182:185], v[218:221], v[62:65]
	v_mfma_f32_16x16x32_bf16 v[58:61], v[190:193], v[218:221], v[58:61]
	v_mfma_f32_16x16x32_bf16 v[50:53], v[182:185], v[226:229], v[50:53]
	v_mfma_f32_16x16x32_bf16 v[42:45], v[190:193], v[226:229], v[42:45]
	v_mfma_f32_16x16x32_bf16 v[34:37], v[182:185], v[234:237], v[34:37]
	v_mfma_f32_16x16x32_bf16 v[26:29], v[190:193], v[234:237], v[26:29]
	v_mfma_f32_16x16x32_bf16 v[18:21], v[182:185], v[242:245], v[18:21]
	v_mfma_f32_16x16x32_bf16 v[10:13], v[190:193], v[242:245], v[10:13]
	s_setprio 0
	s_setprio 1
	v_mfma_f32_16x16x32_bf16 v[54:57], v[194:197], v[210:213], v[54:57]
	v_mfma_f32_16x16x32_bf16 v[46:49], v[202:205], v[210:213], v[46:49]
	v_mfma_f32_16x16x32_bf16 v[38:41], v[194:197], v[222:225], v[38:41]
	v_mfma_f32_16x16x32_bf16 v[30:33], v[202:205], v[222:225], v[30:33]
	v_mfma_f32_16x16x32_bf16 v[22:25], v[194:197], v[230:233], v[22:25]
	v_mfma_f32_16x16x32_bf16 v[14:17], v[202:205], v[230:233], v[14:17]
	v_mfma_f32_16x16x32_bf16 v[6:9], v[194:197], v[238:241], v[6:9]
	v_mfma_f32_16x16x32_bf16 v[2:5], v[202:205], v[238:241], v[2:5]
	v_mfma_f32_16x16x32_bf16 v[54:57], v[198:201], v[218:221], v[54:57]
	v_mfma_f32_16x16x32_bf16 v[46:49], v[206:209], v[218:221], v[46:49]
	v_mfma_f32_16x16x32_bf16 v[38:41], v[198:201], v[226:229], v[38:41]
	v_mfma_f32_16x16x32_bf16 v[30:33], v[206:209], v[226:229], v[30:33]
	v_mfma_f32_16x16x32_bf16 v[22:25], v[198:201], v[234:237], v[22:25]
	v_mfma_f32_16x16x32_bf16 v[14:17], v[206:209], v[234:237], v[14:17]
	v_mfma_f32_16x16x32_bf16 v[6:9], v[198:201], v[242:245], v[6:9]
	v_mfma_f32_16x16x32_bf16 v[2:5], v[206:209], v[242:245], v[2:5]
	s_setprio 0
	s_barrier
	v_lshl_add_u64 v[214:215], v[248:249], 0, s[10:11]
	s_mov_b32 m0, s43
	s_nop 0
	global_load_lds_dwordx4 v[214:215], off
	v_lshl_add_u64 v[214:215], v[250:251], 0, s[10:11]
	s_mov_b32 m0, s44
	s_nop 0
	global_load_lds_dwordx4 v[214:215], off
	s_add_i32 s22, s54, 2
	s_cmp_gt_u32 s54, 61
	s_mov_b32 s54, s22
	s_cbranch_scc1 .LBB0_255

; #define PG8_STAGE(bufoff, gbase, voff) do { _Pragma("unroll") for (int _i = 0; _i < 2; ++_i) \
;         __builtin_amdgcn_global_load_lds((const unsigned*)((const char*)(gbase) + (voff)[_i]), (PG8_LAS unsigned*)(lds + (bufoff) + ldsw + _i * 8192), 16, 0, 0); } while (0)
; #define PG8_LDA(dst, b, h) do { _Pragma("unroll") for (int m = 0; m < 4; ++m) _Pragma("unroll") for (int k = 0; k < 2; ++k) dst[m][k] = *(const PG8_LAS bf16x8*)(lds + PG8_SA(b, h) + aoff + m * 2048 + k * 1024); } while (0)
; #define PG8_LDB(dst, b, h) do { _Pragma("unroll") for (int n = 0; n < 2; ++n) _Pragma("unroll") for (int k = 0; k < 2; ++k) dst[n][k] = *(const PG8_LAS bf16x8*)(lds + PG8_SB(b, h) + boff + n * 2048 + k * 1024); } while (0)
; #define PG8_MMA(ai, bj, At, Bt) do { __builtin_amdgcn_s_setprio(1); _Pragma("unroll") for (int m = 0; m < 4; ++m) _Pragma("unroll") for (int n = 0; n < 2; ++n) _Pragma("unroll") for (int k = 0; k < 2; ++k) \
;         acc[ai][bj][m][n] = __builtin_amdgcn_mfma_f32_16x16x32_bf16(Bt[n][k], At[m][k], acc[ai][bj][m][n], 0, 0, 0); __builtin_amdgcn_s_setprio(0); } while (0)
; #define PG8_WAIT_V(n) asm volatile("s_waitcnt vmcnt(" #n ")" ::: "memory")
; #define PG8_WAIT_L(n) asm volatile("s_waitcnt lgkmcnt(" #n ")" ::: "memory")
; #define PG8_BAR __builtin_amdgcn_s_barrier()
; #define PG8_SCHED __builtin_amdgcn_sched_barrier(0)
; template <class Epi, class Sched, bool ALIGN_EPI = false, bool SP2 = false>
; __device__ __forceinline__ void gemm_phase(PG8_LAS unsigned char* lds, const Gemm g, const Sched& S, const Epi& E) {
;     ...
;         for (int t = 0; t < nt; t += 2) {
;             const bool last = (t == nt - 2);
;             const char* a1 = cA + (size_t)(t + 1) * kstep;
;             const char* a2 = last ? nA : cA + (size_t)(t + 2) * kstep; const char* b2 = last ? nB : cB + (size_t)(t + 2) * kstep;
;             const char* a3 = a2 + kstep; const char* b3 = b2 + kstep;
;             if (last && has_next) S.a_ready(nxt);
;             if constexpr (SP2) {
;             PG8_LDB(B0, 0, 0); PG8_LDB(B1, 0, 1); PG8_SCHED; PG8_LDA(At, 0, 0); PG8_STAGE(PG8_SA(1, 1), a1 + hstepA, voffA);
;             PG8_WAIT_V(8); PG8_WAIT_L(0); PG8_BAR; PG8_MMA(0, 0, At, B0); PG8_MMA(0, 1, At, B1); PG8_BAR; PG8_SCHED;
;             PG8_LDA(At, 0, 1); PG8_STAGE(PG8_SB(0, 0), b2, voffB); PG8_STAGE(PG8_SB(0, 1), b2 + hstepB, voffB); PG8_STAGE(PG8_SA(0, 0), a2, voffA);
.LBB0_443:
	ds_read_b128 v[146:149], v155
	ds_read_b128 v[158:161], v155 offset:1024
	ds_read_b128 v[162:165], v155 offset:2048
	ds_read_b128 v[166:169], v155 offset:3072
	ds_read_b128 v[174:177], v156
	ds_read_b128 v[178:181], v156 offset:1024
	ds_read_b128 v[182:185], v156 offset:2048
	ds_read_b128 v[186:189], v156 offset:3072
	s_add_u32 s28, s26, 0xfff00080
	s_addc_u32 s29, s27, -1
	s_cmp_eq_u32 s53, 60
	s_cselect_b32 s31, s17, s29
	s_cselect_b32 s30, s49, s28
	s_cselect_b32 s29, s19, s52
	s_cselect_b32 s28, s50, s51
	v_lshl_add_u64 v[170:171], s[26:27], 0, v[138:139]
	s_add_i32 m0, s25, 0xc000
	ds_read_b128 v[190:193], v157
	ds_read_b128 v[194:197], v157 offset:1024
	ds_read_b128 v[198:201], v157 offset:2048
	ds_read_b128 v[202:205], v157 offset:3072
	ds_read_b128 v[206:209], v157 offset:4096
	ds_read_b128 v[210:213], v157 offset:5120
	ds_read_b128 v[218:221], v157 offset:6144
	ds_read_b128 v[222:225], v157 offset:7168
	global_load_lds_dwordx4 v[170:171], off
	v_lshl_add_u64 v[170:171], s[26:27], 0, v[140:141]
	s_add_i32 m0, s25, 0xe000
	s_nop 0
	global_load_lds_dwordx4 v[170:171], off
	s_waitcnt vmcnt(8)
	s_waitcnt lgkmcnt(0)
	s_barrier
	s_setprio 1
	s_waitcnt lgkmcnt(0)
	v_mfma_f32_16x16x32_bf16 v[126:129], v[146:149], v[190:193], v[126:129]
	v_mfma_f32_16x16x32_bf16 v[122:125], v[162:165], v[190:193], v[122:125]
	v_mfma_f32_16x16x32_bf16 v[118:121], v[146:149], v[198:201], v[118:121]
	v_mfma_f32_16x16x32_bf16 v[114:117], v[162:165], v[198:201], v[114:117]
	v_mfma_f32_16x16x32_bf16 v[106:109], v[146:149], v[206:209], v[106:109]
	v_mfma_f32_16x16x32_bf16 v[98:101], v[162:165], v[206:209], v[98:101]
	v_mfma_f32_16x16x32_bf16 v[78:81], v[146:149], v[218:221], v[78:81]
	v_mfma_f32_16x16x32_bf16 v[74:77], v[162:165], v[218:221], v[74:77]
	v_mfma_f32_16x16x32_bf16 v[126:129], v[158:161], v[194:197], v[126:129]
	v_mfma_f32_16x16x32_bf16 v[122:125], v[166:169], v[194:197], v[122:125]
	v_mfma_f32_16x16x32_bf16 v[118:121], v[158:161], v[202:205], v[118:121]
	v_mfma_f32_16x16x32_bf16 v[114:117], v[166:169], v[202:205], v[114:117]
	v_mfma_f32_16x16x32_bf16 v[106:109], v[158:161], v[210:213], v[106:109]
	v_mfma_f32_16x16x32_bf16 v[98:101], v[166:169], v[210:213], v[98:101]
	v_mfma_f32_16x16x32_bf16 v[78:81], v[158:161], v[222:225], v[78:81]
	v_mfma_f32_16x16x32_bf16 v[74:77], v[166:169], v[222:225], v[74:77]
	s_setprio 0
	s_setprio 1
	v_mfma_f32_16x16x32_bf16 v[110:113], v[174:177], v[190:193], v[110:113]
	v_mfma_f32_16x16x32_bf16 v[102:105], v[182:185], v[190:193], v[102:105]
	v_mfma_f32_16x16x32_bf16 v[94:97], v[174:177], v[198:201], v[94:97]
	v_mfma_f32_16x16x32_bf16 v[90:93], v[182:185], v[198:201], v[90:93]
	v_mfma_f32_16x16x32_bf16 v[86:89], v[174:177], v[206:209], v[86:89]
	v_mfma_f32_16x16x32_bf16 v[82:85], v[182:185], v[206:209], v[82:85]
	v_mfma_f32_16x16x32_bf16 v[70:73], v[174:177], v[218:221], v[70:73]
	v_mfma_f32_16x16x32_bf16 v[66:69], v[182:185], v[218:221], v[66:69]
	v_mfma_f32_16x16x32_bf16 v[110:113], v[178:181], v[194:197], v[110:113]
	v_mfma_f32_16x16x32_bf16 v[102:105], v[186:189], v[194:197], v[102:105]
	v_mfma_f32_16x16x32_bf16 v[94:97], v[178:181], v[202:205], v[94:97]
	v_mfma_f32_16x16x32_bf16 v[90:93], v[186:189], v[202:205], v[90:93]
	v_mfma_f32_16x16x32_bf16 v[86:89], v[178:181], v[210:213], v[86:89]
	v_mfma_f32_16x16x32_bf16 v[82:85], v[186:189], v[210:213], v[82:85]
	v_mfma_f32_16x16x32_bf16 v[70:73], v[178:181], v[222:225], v[70:73]
	v_mfma_f32_16x16x32_bf16 v[66:69], v[186:189], v[222:225], v[66:69]
	s_setprio 0
	s_barrier
	s_add_i32 s54, s45, s37
	v_lshl_add_u64 v[170:171], s[28:29], 0, v[134:135]
	s_mov_b32 m0, s54
	global_load_lds_dwordx4 v[170:171], off
	s_add_i32 m0, s54, 0x2000
	s_add_u32 s54, s28, 0x100000
	v_lshl_add_u64 v[214:215], s[28:29], 0, v[130:131]
	s_addc_u32 s55, s29, 0
	s_add_i32 s56, s46, s37
	global_load_lds_dwordx4 v[214:215], off
	v_lshl_add_u64 v[226:227], s[54:55], 0, v[134:135]
	s_mov_b32 m0, s56
	v_lshl_add_u64 v[228:229], s[30:31], 0, v[132:133]
	global_load_lds_dwordx4 v[226:227], off
	v_lshl_add_u64 v[226:227], s[54:55], 0, v[130:131]
	s_add_i32 m0, s56, 0x2000
	s_nop 0
	global_load_lds_dwordx4 v[226:227], off
	v_lshl_add_u64 v[226:227], s[30:31], 0, v[136:137]
	ds_read_b128 v[190:193], v157 offset:16384
	ds_read_b128 v[194:197], v157 offset:17408
	ds_read_b128 v[198:201], v157 offset:18432
	ds_read_b128 v[202:205], v157 offset:19456
	ds_read_b128 v[206:209], v157 offset:20480
	ds_read_b128 v[210:213], v157 offset:21504
	ds_read_b128 v[218:221], v157 offset:22528
	ds_read_b128 v[222:225], v157 offset:23552
	s_waitcnt vmcnt(6)
	s_waitcnt lgkmcnt(0)
	s_barrier
; #define PG8_STAGE(bufoff, gbase, voff) do { _Pragma("unroll") for (int _i = 0; _i < 2; ++_i) \
;         __builtin_amdgcn_global_load_lds((const unsigned*)((const char*)(gbase) + (voff)[_i]), (PG8_LAS unsigned*)(lds + (bufoff) + ldsw + _i * 8192), 16, 0, 0); } while (0)
; #define PG8_LDA(dst, b, h) do { _Pragma("unroll") for (int m = 0; m < 4; ++m) _Pragma("unroll") for (int k = 0; k < 2; ++k) dst[m][k] = *(const PG8_LAS bf16x8*)(lds + PG8_SA(b, h) + aoff + m * 2048 + k * 1024); } while (0)
; #define PG8_LDB(dst, b, h) do { _Pragma("unroll") for (int n = 0; n < 2; ++n) _Pragma("unroll") for (int k = 0; k < 2; ++k) dst[n][k] = *(const PG8_LAS bf16x8*)(lds + PG8_SB(b, h) + boff + n * 2048 + k * 1024); } while (0)
; #define PG8_MMA(ai, bj, At, Bt) do { __builtin_amdgcn_s_setprio(1); _Pragma("unroll") for (int m = 0; m < 4; ++m) _Pragma("unroll") for (int n = 0; n < 2; ++n) _Pragma("unroll") for (int k = 0; k < 2; ++k) \
;         acc[ai][bj][m][n] = __builtin_amdgcn_mfma_f32_16x16x32_bf16(Bt[n][k], At[m][k], acc[ai][bj][m][n], 0, 0, 0); __builtin_amdgcn_s_setprio(0); } while (0)
; #define PG8_WAIT_V(n) asm volatile("s_waitcnt vmcnt(" #n ")" ::: "memory")
; #define PG8_WAIT_L(n) asm volatile("s_waitcnt lgkmcnt(" #n ")" ::: "memory")
; #define PG8_BAR __builtin_amdgcn_s_barrier()
; #define PG8_SCHED __builtin_amdgcn_sched_barrier(0)
; template <class Epi, class Sched, bool ALIGN_EPI = false, bool SP2 = false>
; __device__ __forceinline__ void gemm_phase(PG8_LAS unsigned char* lds, const Gemm g, const Sched& S, const Epi& E) {
;     ...
;             PG8_WAIT_V(8); PG8_WAIT_L(0); PG8_BAR; PG8_MMA(1, 0, At, B0); PG8_MMA(1, 1, At, B1); PG8_BAR; PG8_SCHED;
;             PG8_LDB(B0, 1, 0); PG8_LDB(B1, 1, 1); PG8_SCHED; PG8_LDA(At, 1, 0); PG8_STAGE(PG8_SA(0, 1), a2 + hstepA, voffA);
;             PG8_WAIT_V(8); PG8_WAIT_L(0); PG8_BAR; PG8_MMA(0, 0, At, B0); PG8_MMA(0, 1, At, B1); PG8_BAR; PG8_SCHED;
	s_setprio 1
	s_waitcnt lgkmcnt(0)
	v_mfma_f32_16x16x32_bf16 v[62:65], v[146:149], v[190:193], v[62:65]
	v_mfma_f32_16x16x32_bf16 v[58:61], v[162:165], v[190:193], v[58:61]
	v_mfma_f32_16x16x32_bf16 v[50:53], v[146:149], v[198:201], v[50:53]
	v_mfma_f32_16x16x32_bf16 v[42:45], v[162:165], v[198:201], v[42:45]
	v_mfma_f32_16x16x32_bf16 v[34:37], v[146:149], v[206:209], v[34:37]
	v_mfma_f32_16x16x32_bf16 v[26:29], v[162:165], v[206:209], v[26:29]
	v_mfma_f32_16x16x32_bf16 v[18:21], v[146:149], v[218:221], v[18:21]
	v_mfma_f32_16x16x32_bf16 v[10:13], v[162:165], v[218:221], v[10:13]
	v_mfma_f32_16x16x32_bf16 v[62:65], v[158:161], v[194:197], v[62:65]
	v_mfma_f32_16x16x32_bf16 v[58:61], v[166:169], v[194:197], v[58:61]
	v_mfma_f32_16x16x32_bf16 v[50:53], v[158:161], v[202:205], v[50:53]
	v_mfma_f32_16x16x32_bf16 v[42:45], v[166:169], v[202:205], v[42:45]
	v_mfma_f32_16x16x32_bf16 v[34:37], v[158:161], v[210:213], v[34:37]
	v_mfma_f32_16x16x32_bf16 v[26:29], v[166:169], v[210:213], v[26:29]
	v_mfma_f32_16x16x32_bf16 v[18:21], v[158:161], v[222:225], v[18:21]
	v_mfma_f32_16x16x32_bf16 v[10:13], v[166:169], v[222:225], v[10:13]
	s_setprio 0
	s_setprio 1
	v_mfma_f32_16x16x32_bf16 v[54:57], v[174:177], v[190:193], v[54:57]
	v_mfma_f32_16x16x32_bf16 v[46:49], v[182:185], v[190:193], v[46:49]
	v_mfma_f32_16x16x32_bf16 v[38:41], v[174:177], v[198:201], v[38:41]
	v_mfma_f32_16x16x32_bf16 v[30:33], v[182:185], v[198:201], v[30:33]
	v_mfma_f32_16x16x32_bf16 v[22:25], v[174:177], v[206:209], v[22:25]
	v_mfma_f32_16x16x32_bf16 v[14:17], v[182:185], v[206:209], v[14:17]
	v_mfma_f32_16x16x32_bf16 v[6:9], v[174:177], v[218:221], v[6:9]
	v_mfma_f32_16x16x32_bf16 v[2:5], v[182:185], v[218:221], v[2:5]
	v_mfma_f32_16x16x32_bf16 v[54:57], v[178:181], v[194:197], v[54:57]
	v_mfma_f32_16x16x32_bf16 v[46:49], v[186:189], v[194:197], v[46:49]
	v_mfma_f32_16x16x32_bf16 v[38:41], v[178:181], v[202:205], v[38:41]
	v_mfma_f32_16x16x32_bf16 v[30:33], v[186:189], v[202:205], v[30:33]
	v_mfma_f32_16x16x32_bf16 v[22:25], v[178:181], v[210:213], v[22:25]
	v_mfma_f32_16x16x32_bf16 v[14:17], v[186:189], v[210:213], v[14:17]
	v_mfma_f32_16x16x32_bf16 v[6:9], v[178:181], v[222:225], v[6:9]
	v_mfma_f32_16x16x32_bf16 v[2:5], v[186:189], v[222:225], v[2:5]
	s_setprio 0
	s_barrier
	s_mov_b32 m0, s25
	s_nop 0
	global_load_lds_dwordx4 v[226:227], off
	s_mov_b32 m0, s40
	s_nop 0
	global_load_lds_dwordx4 v[228:229], off
	s_add_i32 s54, 0, 0x18000
	v_add_u32_e32 v150, s54, v151
	s_add_i32 s55, 0, 0x1c000
	ds_read_b128 v[146:149], v150
	ds_read_b128 v[158:161], v150 offset:1024
	ds_read_b128 v[162:165], v150 offset:2048
	ds_read_b128 v[166:169], v150 offset:3072
	v_add_u32_e32 v150, s55, v151
	ds_read_b128 v[174:177], v150
	ds_read_b128 v[178:181], v150 offset:1024
	ds_read_b128 v[182:185], v150 offset:2048
	ds_read_b128 v[186:189], v150 offset:3072
	s_add_u32 s30, s30, 0x100000
	s_addc_u32 s31, s31, 0
	s_mov_b32 m0, s41
	v_lshl_add_u64 v[230:231], s[30:31], 0, v[136:137]
	ds_read_b128 v[190:193], v157 offset:32768
	ds_read_b128 v[194:197], v157 offset:33792
	ds_read_b128 v[198:201], v157 offset:34816
	ds_read_b128 v[202:205], v157 offset:35840
	ds_read_b128 v[206:209], v157 offset:36864
	ds_read_b128 v[210:213], v157 offset:37888
	ds_read_b128 v[218:221], v157 offset:38912
	ds_read_b128 v[222:225], v157 offset:39936
	global_load_lds_dwordx4 v[230:231], off
	v_lshl_add_u64 v[230:231], s[30:31], 0, v[132:133]
	s_mov_b32 m0, s42
	s_nop 0
	global_load_lds_dwordx4 v[230:231], off
	s_waitcnt vmcnt(8)
	s_waitcnt lgkmcnt(0)
	s_barrier
	s_setprio 1
	s_waitcnt lgkmcnt(0)
	v_mfma_f32_16x16x32_bf16 v[126:129], v[146:149], v[190:193], v[126:129]
	v_mfma_f32_16x16x32_bf16 v[122:125], v[162:165], v[190:193], v[122:125]
	v_mfma_f32_16x16x32_bf16 v[118:121], v[146:149], v[198:201], v[118:121]
	v_mfma_f32_16x16x32_bf16 v[114:117], v[162:165], v[198:201], v[114:117]
	v_mfma_f32_16x16x32_bf16 v[106:109], v[146:149], v[206:209], v[106:109]
	v_mfma_f32_16x16x32_bf16 v[98:101], v[162:165], v[206:209], v[98:101]
	v_mfma_f32_16x16x32_bf16 v[78:81], v[146:149], v[218:221], v[78:81]
	v_mfma_f32_16x16x32_bf16 v[74:77], v[162:165], v[218:221], v[74:77]
	v_mfma_f32_16x16x32_bf16 v[126:129], v[158:161], v[194:197], v[126:129]
	v_mfma_f32_16x16x32_bf16 v[122:125], v[166:169], v[194:197], v[122:125]
	v_mfma_f32_16x16x32_bf16 v[118:121], v[158:161], v[202:205], v[118:121]
	v_mfma_f32_16x16x32_bf16 v[114:117], v[166:169], v[202:205], v[114:117]
	v_mfma_f32_16x16x32_bf16 v[106:109], v[158:161], v[210:213], v[106:109]
	v_mfma_f32_16x16x32_bf16 v[98:101], v[166:169], v[210:213], v[98:101]
	v_mfma_f32_16x16x32_bf16 v[78:81], v[158:161], v[222:225], v[78:81]
	v_mfma_f32_16x16x32_bf16 v[74:77], v[166:169], v[222:225], v[74:77]
	s_setprio 0
	s_setprio 1
	v_mfma_f32_16x16x32_bf16 v[110:113], v[174:177], v[190:193], v[110:113]
	v_mfma_f32_16x16x32_bf16 v[102:105], v[182:185], v[190:193], v[102:105]
	v_mfma_f32_16x16x32_bf16 v[94:97], v[174:177], v[198:201], v[94:97]
	v_mfma_f32_16x16x32_bf16 v[90:93], v[182:185], v[198:201], v[90:93]
	v_mfma_f32_16x16x32_bf16 v[86:89], v[174:177], v[206:209], v[86:89]
	v_mfma_f32_16x16x32_bf16 v[82:85], v[182:185], v[206:209], v[82:85]
	v_mfma_f32_16x16x32_bf16 v[70:73], v[174:177], v[218:221], v[70:73]
	v_mfma_f32_16x16x32_bf16 v[66:69], v[182:185], v[218:221], v[66:69]
	v_mfma_f32_16x16x32_bf16 v[110:113], v[178:181], v[194:197], v[110:113]
	v_mfma_f32_16x16x32_bf16 v[102:105], v[186:189], v[194:197], v[102:105]
	v_mfma_f32_16x16x32_bf16 v[94:97], v[178:181], v[202:205], v[94:97]
	v_mfma_f32_16x16x32_bf16 v[90:93], v[186:189], v[202:205], v[90:93]
	v_mfma_f32_16x16x32_bf16 v[86:89], v[178:181], v[210:213], v[86:89]
	v_mfma_f32_16x16x32_bf16 v[82:85], v[186:189], v[210:213], v[82:85]
	v_mfma_f32_16x16x32_bf16 v[70:73], v[178:181], v[222:225], v[70:73]
	v_mfma_f32_16x16x32_bf16 v[66:69], v[186:189], v[222:225], v[66:69]
	s_setprio 0
	s_barrier
; #define PG8_STAGE(bufoff, gbase, voff) do { _Pragma("unroll") for (int _i = 0; _i < 2; ++_i) \
;         __builtin_amdgcn_global_load_lds((const unsigned*)((const char*)(gbase) + (voff)[_i]), (PG8_LAS unsigned*)(lds + (bufoff) + ldsw + _i * 8192), 16, 0, 0); } while (0)
; #define PG8_LDA(dst, b, h) do { _Pragma("unroll") for (int m = 0; m < 4; ++m) _Pragma("unroll") for (int k = 0; k < 2; ++k) dst[m][k] = *(const PG8_LAS bf16x8*)(lds + PG8_SA(b, h) + aoff + m * 2048 + k * 1024); } while (0)
; #define PG8_MMA(ai, bj, At, Bt) do { __builtin_amdgcn_s_setprio(1); _Pragma("unroll") for (int m = 0; m < 4; ++m) _Pragma("unroll") for (int n = 0; n < 2; ++n) _Pragma("unroll") for (int k = 0; k < 2; ++k) \
;         acc[ai][bj][m][n] = __builtin_amdgcn_mfma_f32_16x16x32_bf16(Bt[n][k], At[m][k], acc[ai][bj][m][n], 0, 0, 0); __builtin_amdgcn_s_setprio(0); } while (0)
; #define PG8_WAIT_V(n) asm volatile("s_waitcnt vmcnt(" #n ")" ::: "memory")
; #define PG8_WAIT_L(n) asm volatile("s_waitcnt lgkmcnt(" #n ")" ::: "memory")
; #define PG8_BAR __builtin_amdgcn_s_barrier()
; #define PG8_SCHED __builtin_amdgcn_sched_barrier(0)
; template <class Epi, class Sched, bool ALIGN_EPI = false, bool SP2 = false>
; __device__ __forceinline__ void gemm_phase(PG8_LAS unsigned char* lds, const Gemm g, const Sched& S, const Epi& E) {
;     ...
;         for (int t = 0; t < nt; t += 2) {
;             const bool last = (t == nt - 2);
;     ...
;             PG8_LDA(At, 1, 1); PG8_STAGE(PG8_SB(1, 0), b3, voffB); PG8_STAGE(PG8_SB(1, 1), b3 + hstepB, voffB); PG8_STAGE(PG8_SA(1, 0), a3, voffA);
;             PG8_WAIT_V(8); PG8_WAIT_L(0); PG8_BAR; PG8_MMA(1, 0, At, B0); PG8_MMA(1, 1, At, B1); PG8_BAR; PG8_SCHED;
	s_add_i32 s30, s54, s37
	v_lshl_add_u64 v[170:171], v[170:171], 0, s[12:13]
	s_mov_b32 m0, s30
	global_load_lds_dwordx4 v[170:171], off
	s_add_i32 m0, s30, 0x2000
	s_add_u32 s28, s28, 0x100080
	v_lshl_add_u64 v[170:171], v[214:215], 0, s[12:13]
	s_addc_u32 s29, s29, 0
	s_add_i32 s30, s55, s37
	global_load_lds_dwordx4 v[170:171], off
	v_lshl_add_u64 v[170:171], s[28:29], 0, v[134:135]
	s_mov_b32 m0, s30
	s_nop 0
	global_load_lds_dwordx4 v[170:171], off
	v_lshl_add_u64 v[170:171], s[28:29], 0, v[130:131]
	s_add_i32 m0, s30, 0x2000
	s_nop 0
	global_load_lds_dwordx4 v[170:171], off
	ds_read_b128 v[190:193], v157 offset:49152
	ds_read_b128 v[194:197], v157 offset:50176
	ds_read_b128 v[198:201], v157 offset:51200
	ds_read_b128 v[202:205], v157 offset:52224
	ds_read_b128 v[206:209], v157 offset:53248
	ds_read_b128 v[210:213], v157 offset:54272
	ds_read_b128 v[218:221], v157 offset:55296
	ds_read_b128 v[222:225], v157 offset:56320
	s_waitcnt vmcnt(6)
	s_waitcnt lgkmcnt(0)
	s_barrier
	s_setprio 1
	s_waitcnt lgkmcnt(0)
	v_mfma_f32_16x16x32_bf16 v[62:65], v[146:149], v[190:193], v[62:65]
	v_mfma_f32_16x16x32_bf16 v[58:61], v[162:165], v[190:193], v[58:61]
	v_mfma_f32_16x16x32_bf16 v[50:53], v[146:149], v[198:201], v[50:53]
	v_mfma_f32_16x16x32_bf16 v[42:45], v[162:165], v[198:201], v[42:45]
	v_mfma_f32_16x16x32_bf16 v[34:37], v[146:149], v[206:209], v[34:37]
	v_mfma_f32_16x16x32_bf16 v[26:29], v[162:165], v[206:209], v[26:29]
	v_mfma_f32_16x16x32_bf16 v[18:21], v[146:149], v[218:221], v[18:21]
	v_mfma_f32_16x16x32_bf16 v[10:13], v[162:165], v[218:221], v[10:13]
	v_mfma_f32_16x16x32_bf16 v[62:65], v[158:161], v[194:197], v[62:65]
	v_mfma_f32_16x16x32_bf16 v[58:61], v[166:169], v[194:197], v[58:61]
	v_mfma_f32_16x16x32_bf16 v[50:53], v[158:161], v[202:205], v[50:53]
	v_mfma_f32_16x16x32_bf16 v[42:45], v[166:169], v[202:205], v[42:45]
	v_mfma_f32_16x16x32_bf16 v[34:37], v[158:161], v[210:213], v[34:37]
	v_mfma_f32_16x16x32_bf16 v[26:29], v[166:169], v[210:213], v[26:29]
	v_mfma_f32_16x16x32_bf16 v[18:21], v[158:161], v[222:225], v[18:21]
	v_mfma_f32_16x16x32_bf16 v[10:13], v[166:169], v[222:225], v[10:13]
	s_setprio 0
	s_setprio 1
	v_mfma_f32_16x16x32_bf16 v[54:57], v[174:177], v[190:193], v[54:57]
	v_mfma_f32_16x16x32_bf16 v[46:49], v[182:185], v[190:193], v[46:49]
	v_mfma_f32_16x16x32_bf16 v[38:41], v[174:177], v[198:201], v[38:41]
	v_mfma_f32_16x16x32_bf16 v[30:33], v[182:185], v[198:201], v[30:33]
	v_mfma_f32_16x16x32_bf16 v[22:25], v[174:177], v[206:209], v[22:25]
	v_mfma_f32_16x16x32_bf16 v[14:17], v[182:185], v[206:209], v[14:17]
	v_mfma_f32_16x16x32_bf16 v[6:9], v[174:177], v[218:221], v[6:9]
	v_mfma_f32_16x16x32_bf16 v[2:5], v[182:185], v[218:221], v[2:5]
	v_mfma_f32_16x16x32_bf16 v[54:57], v[178:181], v[194:197], v[54:57]
	v_mfma_f32_16x16x32_bf16 v[46:49], v[186:189], v[194:197], v[46:49]
	v_mfma_f32_16x16x32_bf16 v[38:41], v[178:181], v[202:205], v[38:41]
	v_mfma_f32_16x16x32_bf16 v[30:33], v[186:189], v[202:205], v[30:33]
	v_mfma_f32_16x16x32_bf16 v[22:25], v[178:181], v[210:213], v[22:25]
	v_mfma_f32_16x16x32_bf16 v[14:17], v[186:189], v[210:213], v[14:17]
	v_mfma_f32_16x16x32_bf16 v[6:9], v[178:181], v[222:225], v[6:9]
	v_mfma_f32_16x16x32_bf16 v[2:5], v[186:189], v[222:225], v[2:5]
	s_setprio 0
	s_barrier
	v_lshl_add_u64 v[170:171], v[226:227], 0, s[12:13]
	s_mov_b32 m0, s43
	s_nop 0
	global_load_lds_dwordx4 v[170:171], off
	v_lshl_add_u64 v[170:171], v[228:229], 0, s[12:13]
	s_mov_b32 m0, s44
	s_nop 0
	global_load_lds_dwordx4 v[170:171], off
	s_add_i32 s53, s53, 2
	s_add_u32 s26, s26, 0x100
	s_addc_u32 s27, s27, 0
	s_add_u32 s51, s51, 0x100
	s_addc_u32 s52, s52, 0
	s_cmp_gt_u32 s53, 61
	s_cbranch_scc0 .LBB0_443
	s_and_b64 vcc, exec, s[14:15]
	s_cbranch_vccz .LBB0_446
	s_barrier

; #define PG8_STAGE(bufoff, gbase, voff) do { _Pragma("unroll") for (int _i = 0; _i < 2; ++_i) \
;         __builtin_amdgcn_global_load_lds((const unsigned*)((const char*)(gbase) + (voff)[_i]), (PG8_LAS unsigned*)(lds + (bufoff) + ldsw + _i * 8192), 16, 0, 0); } while (0)
; #define PG8_LDA(dst, b, h) do { _Pragma("unroll") for (int m = 0; m < 4; ++m) _Pragma("unroll") for (int k = 0; k < 2; ++k) dst[m][k] = *(const PG8_LAS bf16x8*)(lds + PG8_SA(b, h) + aoff + m * 2048 + k * 1024); } while (0)
; #define PG8_LDB(dst, b, h) do { _Pragma("unroll") for (int n = 0; n < 2; ++n) _Pragma("unroll") for (int k = 0; k < 2; ++k) dst[n][k] = *(const PG8_LAS bf16x8*)(lds + PG8_SB(b, h) + boff + n * 2048 + k * 1024); } while (0)
; #define PG8_MMA(ai, bj, At, Bt) do { __builtin_amdgcn_s_setprio(1); _Pragma("unroll") for (int m = 0; m < 4; ++m) _Pragma("unroll") for (int n = 0; n < 2; ++n) _Pragma("unroll") for (int k = 0; k < 2; ++k) \
;         acc[ai][bj][m][n] = __builtin_amdgcn_mfma_f32_16x16x32_bf16(Bt[n][k], At[m][k], acc[ai][bj][m][n], 0, 0, 0); __builtin_amdgcn_s_setprio(0); } while (0)
; #define PG8_WAIT_V(n) asm volatile("s_waitcnt vmcnt(" #n ")" ::: "memory")
; #define PG8_WAIT_L(n) asm volatile("s_waitcnt lgkmcnt(" #n ")" ::: "memory")
; #define PG8_BAR __builtin_amdgcn_s_barrier()
; #define PG8_SCHED __builtin_amdgcn_sched_barrier(0)
; template <class Epi, class Sched, bool ALIGN_EPI = false, bool SP2 = false>
; __device__ __forceinline__ void gemm_phase(PG8_LAS unsigned char* lds, const Gemm g, const Sched& S, const Epi& E) {
;     ...
;         for (int t = 0; t < nt; t += 2) {
;             const bool last = (t == nt - 2);
;             const char* a1 = cA + (size_t)(t + 1) * kstep;
;             const char* a2 = last ? nA : cA + (size_t)(t + 2) * kstep; const char* b2 = last ? nB : cB + (size_t)(t + 2) * kstep;
;             const char* a3 = a2 + kstep; const char* b3 = b2 + kstep;
;             if (last && has_next) S.a_ready(nxt);
;             if constexpr (SP2) {
;             PG8_LDB(B0, 0, 0); PG8_LDB(B1, 0, 1); PG8_SCHED; PG8_LDA(At, 0, 0); PG8_STAGE(PG8_SA(1, 1), a1 + hstepA, voffA);
;             PG8_WAIT_V(8); PG8_WAIT_L(0); PG8_BAR; PG8_MMA(0, 0, At, B0); PG8_MMA(0, 1, At, B1); PG8_BAR; PG8_SCHED;
;             PG8_LDA(At, 0, 1); PG8_STAGE(PG8_SB(0, 0), b2, voffB); PG8_STAGE(PG8_SB(0, 1), b2 + hstepB, voffB); PG8_STAGE(PG8_SA(0, 0), a2, voffA);
.LBB0_966:
	ds_read_b128 v[154:157], v150
	ds_read_b128 v[158:161], v150 offset:1024
	ds_read_b128 v[162:165], v150 offset:2048
	ds_read_b128 v[166:169], v150 offset:3072
	ds_read_b128 v[170:173], v151
	ds_read_b128 v[174:177], v151 offset:1024
	ds_read_b128 v[178:181], v151 offset:2048
	ds_read_b128 v[182:185], v151 offset:3072
	s_add_u32 s34, s30, 0xfff00080
	s_addc_u32 s35, s31, -1
	s_cmp_eq_u32 s61, 60
	s_cselect_b32 s37, s23, s35
	s_cselect_b32 s36, s57, s34
	s_cselect_b32 s35, s21, s60
	s_cselect_b32 s34, s58, s59
	v_lshl_add_u64 v[146:147], s[30:31], 0, v[138:139]
	s_add_i32 m0, s29, 0xc000
	ds_read_b128 v[186:189], v152
	ds_read_b128 v[190:193], v152 offset:1024
	ds_read_b128 v[194:197], v152 offset:2048
	ds_read_b128 v[198:201], v152 offset:3072
	ds_read_b128 v[202:205], v152 offset:4096
	ds_read_b128 v[206:209], v152 offset:5120
	ds_read_b128 v[210:213], v152 offset:6144
	ds_read_b128 v[218:221], v152 offset:7168
	global_load_lds_dwordx4 v[146:147], off
	v_lshl_add_u64 v[146:147], s[30:31], 0, v[140:141]
	s_add_i32 m0, s29, 0xe000
	s_nop 0
	global_load_lds_dwordx4 v[146:147], off
	s_waitcnt vmcnt(8)
	s_waitcnt lgkmcnt(0)
	s_barrier
	s_setprio 1
	s_waitcnt lgkmcnt(0)
	v_mfma_f32_16x16x32_bf16 v[126:129], v[154:157], v[186:189], v[126:129]
	v_mfma_f32_16x16x32_bf16 v[122:125], v[162:165], v[186:189], v[122:125]
	v_mfma_f32_16x16x32_bf16 v[114:117], v[154:157], v[194:197], v[114:117]
	v_mfma_f32_16x16x32_bf16 v[106:109], v[162:165], v[194:197], v[106:109]
	v_mfma_f32_16x16x32_bf16 v[98:101], v[154:157], v[202:205], v[98:101]
	v_mfma_f32_16x16x32_bf16 v[90:93], v[162:165], v[202:205], v[90:93]
	v_mfma_f32_16x16x32_bf16 v[82:85], v[154:157], v[210:213], v[82:85]
	v_mfma_f32_16x16x32_bf16 v[74:77], v[162:165], v[210:213], v[74:77]
	v_mfma_f32_16x16x32_bf16 v[126:129], v[158:161], v[190:193], v[126:129]
	v_mfma_f32_16x16x32_bf16 v[122:125], v[166:169], v[190:193], v[122:125]
	v_mfma_f32_16x16x32_bf16 v[114:117], v[158:161], v[198:201], v[114:117]
	v_mfma_f32_16x16x32_bf16 v[106:109], v[166:169], v[198:201], v[106:109]
	v_mfma_f32_16x16x32_bf16 v[98:101], v[158:161], v[206:209], v[98:101]
	v_mfma_f32_16x16x32_bf16 v[90:93], v[166:169], v[206:209], v[90:93]
	v_mfma_f32_16x16x32_bf16 v[82:85], v[158:161], v[218:221], v[82:85]
	v_mfma_f32_16x16x32_bf16 v[74:77], v[166:169], v[218:221], v[74:77]
	s_setprio 0
	s_setprio 1
	v_mfma_f32_16x16x32_bf16 v[118:121], v[170:173], v[186:189], v[118:121]
	v_mfma_f32_16x16x32_bf16 v[110:113], v[178:181], v[186:189], v[110:113]
	v_mfma_f32_16x16x32_bf16 v[102:105], v[170:173], v[194:197], v[102:105]
	v_mfma_f32_16x16x32_bf16 v[94:97], v[178:181], v[194:197], v[94:97]
	v_mfma_f32_16x16x32_bf16 v[86:89], v[170:173], v[202:205], v[86:89]
	v_mfma_f32_16x16x32_bf16 v[78:81], v[178:181], v[202:205], v[78:81]
	v_mfma_f32_16x16x32_bf16 v[70:73], v[170:173], v[210:213], v[70:73]
	v_mfma_f32_16x16x32_bf16 v[66:69], v[178:181], v[210:213], v[66:69]
	v_mfma_f32_16x16x32_bf16 v[118:121], v[174:177], v[190:193], v[118:121]
	v_mfma_f32_16x16x32_bf16 v[110:113], v[182:185], v[190:193], v[110:113]
	v_mfma_f32_16x16x32_bf16 v[102:105], v[174:177], v[198:201], v[102:105]
	v_mfma_f32_16x16x32_bf16 v[94:97], v[182:185], v[198:201], v[94:97]
	v_mfma_f32_16x16x32_bf16 v[86:89], v[174:177], v[206:209], v[86:89]
	v_mfma_f32_16x16x32_bf16 v[78:81], v[182:185], v[206:209], v[78:81]
	v_mfma_f32_16x16x32_bf16 v[70:73], v[174:177], v[218:221], v[70:73]
	v_mfma_f32_16x16x32_bf16 v[66:69], v[182:185], v[218:221], v[66:69]
	s_setprio 0
	s_barrier
	s_add_i32 s62, s50, s42
	v_lshl_add_u64 v[146:147], s[34:35], 0, v[132:133]
	s_mov_b32 m0, s62
	global_load_lds_dwordx4 v[146:147], off
	s_add_i32 m0, s62, 0x2000
	s_add_u32 s62, s34, 0x100000
	v_lshl_add_u64 v[214:215], s[34:35], 0, v[136:137]
	s_addc_u32 s63, s35, 0
	s_add_i32 s64, s51, s42
	global_load_lds_dwordx4 v[214:215], off
	v_lshl_add_u64 v[222:223], s[62:63], 0, v[132:133]
	s_mov_b32 m0, s64
	v_lshl_add_u64 v[224:225], s[36:37], 0, v[134:135]
	global_load_lds_dwordx4 v[222:223], off
	v_lshl_add_u64 v[222:223], s[62:63], 0, v[136:137]
	s_add_i32 m0, s64, 0x2000
	s_nop 0
	global_load_lds_dwordx4 v[222:223], off
	v_lshl_add_u64 v[222:223], s[36:37], 0, v[130:131]
	ds_read_b128 v[186:189], v152 offset:16384
	ds_read_b128 v[190:193], v152 offset:17408
	ds_read_b128 v[194:197], v152 offset:18432
	ds_read_b128 v[198:201], v152 offset:19456
	ds_read_b128 v[202:205], v152 offset:20480
	ds_read_b128 v[206:209], v152 offset:21504
	ds_read_b128 v[210:213], v152 offset:22528
	ds_read_b128 v[218:221], v152 offset:23552
	s_waitcnt vmcnt(6)
	s_waitcnt lgkmcnt(0)
	s_barrier
; #define PG8_STAGE(bufoff, gbase, voff) do { _Pragma("unroll") for (int _i = 0; _i < 2; ++_i) \
;         __builtin_amdgcn_global_load_lds((const unsigned*)((const char*)(gbase) + (voff)[_i]), (PG8_LAS unsigned*)(lds + (bufoff) + ldsw + _i * 8192), 16, 0, 0); } while (0)
; #define PG8_LDA(dst, b, h) do { _Pragma("unroll") for (int m = 0; m < 4; ++m) _Pragma("unroll") for (int k = 0; k < 2; ++k) dst[m][k] = *(const PG8_LAS bf16x8*)(lds + PG8_SA(b, h) + aoff + m * 2048 + k * 1024); } while (0)
; #define PG8_LDB(dst, b, h) do { _Pragma("unroll") for (int n = 0; n < 2; ++n) _Pragma("unroll") for (int k = 0; k < 2; ++k) dst[n][k] = *(const PG8_LAS bf16x8*)(lds + PG8_SB(b, h) + boff + n * 2048 + k * 1024); } while (0)
; #define PG8_MMA(ai, bj, At, Bt) do { __builtin_amdgcn_s_setprio(1); _Pragma("unroll") for (int m = 0; m < 4; ++m) _Pragma("unroll") for (int n = 0; n < 2; ++n) _Pragma("unroll") for (int k = 0; k < 2; ++k) \
;         acc[ai][bj][m][n] = __builtin_amdgcn_mfma_f32_16x16x32_bf16(Bt[n][k], At[m][k], acc[ai][bj][m][n], 0, 0, 0); __builtin_amdgcn_s_setprio(0); } while (0)
; #define PG8_WAIT_V(n) asm volatile("s_waitcnt vmcnt(" #n ")" ::: "memory")
; #define PG8_WAIT_L(n) asm volatile("s_waitcnt lgkmcnt(" #n ")" ::: "memory")
; #define PG8_BAR __builtin_amdgcn_s_barrier()
; #define PG8_SCHED __builtin_amdgcn_sched_barrier(0)
; template <class Epi, class Sched, bool ALIGN_EPI = false, bool SP2 = false>
; __device__ __forceinline__ void gemm_phase(PG8_LAS unsigned char* lds, const Gemm g, const Sched& S, const Epi& E) {
;     ...
;             PG8_WAIT_V(8); PG8_WAIT_L(0); PG8_BAR; PG8_MMA(1, 0, At, B0); PG8_MMA(1, 1, At, B1); PG8_BAR; PG8_SCHED;
;             PG8_LDB(B0, 1, 0); PG8_LDB(B1, 1, 1); PG8_SCHED; PG8_LDA(At, 1, 0); PG8_STAGE(PG8_SA(0, 1), a2 + hstepA, voffA);
;             PG8_WAIT_V(8); PG8_WAIT_L(0); PG8_BAR; PG8_MMA(0, 0, At, B0); PG8_MMA(0, 1, At, B1); PG8_BAR; PG8_SCHED;
	s_setprio 1
	s_waitcnt lgkmcnt(0)
	v_mfma_f32_16x16x32_bf16 v[62:65], v[154:157], v[186:189], v[62:65]
	v_mfma_f32_16x16x32_bf16 v[58:61], v[162:165], v[186:189], v[58:61]
	v_mfma_f32_16x16x32_bf16 v[50:53], v[154:157], v[194:197], v[50:53]
	v_mfma_f32_16x16x32_bf16 v[42:45], v[162:165], v[194:197], v[42:45]
	v_mfma_f32_16x16x32_bf16 v[34:37], v[154:157], v[202:205], v[34:37]
	v_mfma_f32_16x16x32_bf16 v[26:29], v[162:165], v[202:205], v[26:29]
	v_mfma_f32_16x16x32_bf16 v[18:21], v[154:157], v[210:213], v[18:21]
	v_mfma_f32_16x16x32_bf16 v[10:13], v[162:165], v[210:213], v[10:13]
	v_mfma_f32_16x16x32_bf16 v[62:65], v[158:161], v[190:193], v[62:65]
	v_mfma_f32_16x16x32_bf16 v[58:61], v[166:169], v[190:193], v[58:61]
	v_mfma_f32_16x16x32_bf16 v[50:53], v[158:161], v[198:201], v[50:53]
	v_mfma_f32_16x16x32_bf16 v[42:45], v[166:169], v[198:201], v[42:45]
	v_mfma_f32_16x16x32_bf16 v[34:37], v[158:161], v[206:209], v[34:37]
	v_mfma_f32_16x16x32_bf16 v[26:29], v[166:169], v[206:209], v[26:29]
	v_mfma_f32_16x16x32_bf16 v[18:21], v[158:161], v[218:221], v[18:21]
	v_mfma_f32_16x16x32_bf16 v[10:13], v[166:169], v[218:221], v[10:13]
	s_setprio 0
	s_setprio 1
	v_mfma_f32_16x16x32_bf16 v[54:57], v[170:173], v[186:189], v[54:57]
	v_mfma_f32_16x16x32_bf16 v[46:49], v[178:181], v[186:189], v[46:49]
	v_mfma_f32_16x16x32_bf16 v[38:41], v[170:173], v[194:197], v[38:41]
	v_mfma_f32_16x16x32_bf16 v[30:33], v[178:181], v[194:197], v[30:33]
	v_mfma_f32_16x16x32_bf16 v[22:25], v[170:173], v[202:205], v[22:25]
	v_mfma_f32_16x16x32_bf16 v[14:17], v[178:181], v[202:205], v[14:17]
	v_mfma_f32_16x16x32_bf16 v[6:9], v[170:173], v[210:213], v[6:9]
	v_mfma_f32_16x16x32_bf16 v[2:5], v[178:181], v[210:213], v[2:5]
	v_mfma_f32_16x16x32_bf16 v[54:57], v[174:177], v[190:193], v[54:57]
	v_mfma_f32_16x16x32_bf16 v[46:49], v[182:185], v[190:193], v[46:49]
	v_mfma_f32_16x16x32_bf16 v[38:41], v[174:177], v[198:201], v[38:41]
	v_mfma_f32_16x16x32_bf16 v[30:33], v[182:185], v[198:201], v[30:33]
	v_mfma_f32_16x16x32_bf16 v[22:25], v[174:177], v[206:209], v[22:25]
	v_mfma_f32_16x16x32_bf16 v[14:17], v[182:185], v[206:209], v[14:17]
	v_mfma_f32_16x16x32_bf16 v[6:9], v[174:177], v[218:221], v[6:9]
	v_mfma_f32_16x16x32_bf16 v[2:5], v[182:185], v[218:221], v[2:5]
	s_setprio 0
	s_barrier
	s_mov_b32 m0, s29
	s_nop 0
	global_load_lds_dwordx4 v[222:223], off
	s_mov_b32 m0, s43
	s_nop 0
	global_load_lds_dwordx4 v[224:225], off
	s_add_i32 s62, 0, 0x18000
	v_add_u32_e32 v153, s62, v148
	s_add_i32 s63, 0, 0x1c000
	ds_read_b128 v[154:157], v153
	ds_read_b128 v[158:161], v153 offset:1024
	ds_read_b128 v[162:165], v153 offset:2048
	ds_read_b128 v[166:169], v153 offset:3072
	v_add_u32_e32 v153, s63, v148
	ds_read_b128 v[170:173], v153
	ds_read_b128 v[174:177], v153 offset:1024
	ds_read_b128 v[178:181], v153 offset:2048
	ds_read_b128 v[182:185], v153 offset:3072
	s_add_u32 s36, s36, 0x100000
	s_addc_u32 s37, s37, 0
	s_mov_b32 m0, s44
	v_lshl_add_u64 v[226:227], s[36:37], 0, v[130:131]
	ds_read_b128 v[186:189], v152 offset:32768
	ds_read_b128 v[190:193], v152 offset:33792
	ds_read_b128 v[194:197], v152 offset:34816
	ds_read_b128 v[198:201], v152 offset:35840
	ds_read_b128 v[202:205], v152 offset:36864
	ds_read_b128 v[206:209], v152 offset:37888
	ds_read_b128 v[210:213], v152 offset:38912
	ds_read_b128 v[218:221], v152 offset:39936
	global_load_lds_dwordx4 v[226:227], off
	v_lshl_add_u64 v[226:227], s[36:37], 0, v[134:135]
	s_mov_b32 m0, s45
	s_nop 0
	global_load_lds_dwordx4 v[226:227], off
	s_waitcnt vmcnt(8)
	s_waitcnt lgkmcnt(0)
	s_barrier
	s_setprio 1
	s_waitcnt lgkmcnt(0)
	v_mfma_f32_16x16x32_bf16 v[126:129], v[154:157], v[186:189], v[126:129]
	v_mfma_f32_16x16x32_bf16 v[122:125], v[162:165], v[186:189], v[122:125]
	v_mfma_f32_16x16x32_bf16 v[114:117], v[154:157], v[194:197], v[114:117]
	v_mfma_f32_16x16x32_bf16 v[106:109], v[162:165], v[194:197], v[106:109]
	v_mfma_f32_16x16x32_bf16 v[98:101], v[154:157], v[202:205], v[98:101]
	v_mfma_f32_16x16x32_bf16 v[90:93], v[162:165], v[202:205], v[90:93]
	v_mfma_f32_16x16x32_bf16 v[82:85], v[154:157], v[210:213], v[82:85]
	v_mfma_f32_16x16x32_bf16 v[74:77], v[162:165], v[210:213], v[74:77]
	v_mfma_f32_16x16x32_bf16 v[126:129], v[158:161], v[190:193], v[126:129]
	v_mfma_f32_16x16x32_bf16 v[122:125], v[166:169], v[190:193], v[122:125]
	v_mfma_f32_16x16x32_bf16 v[114:117], v[158:161], v[198:201], v[114:117]
	v_mfma_f32_16x16x32_bf16 v[106:109], v[166:169], v[198:201], v[106:109]
	v_mfma_f32_16x16x32_bf16 v[98:101], v[158:161], v[206:209], v[98:101]
	v_mfma_f32_16x16x32_bf16 v[90:93], v[166:169], v[206:209], v[90:93]
	v_mfma_f32_16x16x32_bf16 v[82:85], v[158:161], v[218:221], v[82:85]
	v_mfma_f32_16x16x32_bf16 v[74:77], v[166:169], v[218:221], v[74:77]
	s_setprio 0
	s_setprio 1
	v_mfma_f32_16x16x32_bf16 v[118:121], v[170:173], v[186:189], v[118:121]
	v_mfma_f32_16x16x32_bf16 v[110:113], v[178:181], v[186:189], v[110:113]
	v_mfma_f32_16x16x32_bf16 v[102:105], v[170:173], v[194:197], v[102:105]
	v_mfma_f32_16x16x32_bf16 v[94:97], v[178:181], v[194:197], v[94:97]
	v_mfma_f32_16x16x32_bf16 v[86:89], v[170:173], v[202:205], v[86:89]
	v_mfma_f32_16x16x32_bf16 v[78:81], v[178:181], v[202:205], v[78:81]
	v_mfma_f32_16x16x32_bf16 v[70:73], v[170:173], v[210:213], v[70:73]
	v_mfma_f32_16x16x32_bf16 v[66:69], v[178:181], v[210:213], v[66:69]
	v_mfma_f32_16x16x32_bf16 v[118:121], v[174:177], v[190:193], v[118:121]
	v_mfma_f32_16x16x32_bf16 v[110:113], v[182:185], v[190:193], v[110:113]
	v_mfma_f32_16x16x32_bf16 v[102:105], v[174:177], v[198:201], v[102:105]
	v_mfma_f32_16x16x32_bf16 v[94:97], v[182:185], v[198:201], v[94:97]
	v_mfma_f32_16x16x32_bf16 v[86:89], v[174:177], v[206:209], v[86:89]
	v_mfma_f32_16x16x32_bf16 v[78:81], v[182:185], v[206:209], v[78:81]
	v_mfma_f32_16x16x32_bf16 v[70:73], v[174:177], v[218:221], v[70:73]
	v_mfma_f32_16x16x32_bf16 v[66:69], v[182:185], v[218:221], v[66:69]
	s_setprio 0
	s_barrier
; #define PG8_STAGE(bufoff, gbase, voff) do { _Pragma("unroll") for (int _i = 0; _i < 2; ++_i) \
;         __builtin_amdgcn_global_load_lds((const unsigned*)((const char*)(gbase) + (voff)[_i]), (PG8_LAS unsigned*)(lds + (bufoff) + ldsw + _i * 8192), 16, 0, 0); } while (0)
; #define PG8_LDA(dst, b, h) do { _Pragma("unroll") for (int m = 0; m < 4; ++m) _Pragma("unroll") for (int k = 0; k < 2; ++k) dst[m][k] = *(const PG8_LAS bf16x8*)(lds + PG8_SA(b, h) + aoff + m * 2048 + k * 1024); } while (0)
; #define PG8_MMA(ai, bj, At, Bt) do { __builtin_amdgcn_s_setprio(1); _Pragma("unroll") for (int m = 0; m < 4; ++m) _Pragma("unroll") for (int n = 0; n < 2; ++n) _Pragma("unroll") for (int k = 0; k < 2; ++k) \
;         acc[ai][bj][m][n] = __builtin_amdgcn_mfma_f32_16x16x32_bf16(Bt[n][k], At[m][k], acc[ai][bj][m][n], 0, 0, 0); __builtin_amdgcn_s_setprio(0); } while (0)
; #define PG8_WAIT_V(n) asm volatile("s_waitcnt vmcnt(" #n ")" ::: "memory")
; #define PG8_WAIT_L(n) asm volatile("s_waitcnt lgkmcnt(" #n ")" ::: "memory")
; #define PG8_BAR __builtin_amdgcn_s_barrier()
; #define PG8_SCHED __builtin_amdgcn_sched_barrier(0)
; template <class Epi, class Sched, bool ALIGN_EPI = false, bool SP2 = false>
; __device__ __forceinline__ void gemm_phase(PG8_LAS unsigned char* lds, const Gemm g, const Sched& S, const Epi& E) {
;     ...
;         for (int t = 0; t < nt; t += 2) {
;             const bool last = (t == nt - 2);
;     ...
;             PG8_LDA(At, 1, 1); PG8_STAGE(PG8_SB(1, 0), b3, voffB); PG8_STAGE(PG8_SB(1, 1), b3 + hstepB, voffB); PG8_STAGE(PG8_SA(1, 0), a3, voffA);
;             PG8_WAIT_V(8); PG8_WAIT_L(0); PG8_BAR; PG8_MMA(1, 0, At, B0); PG8_MMA(1, 1, At, B1); PG8_BAR; PG8_SCHED;
	s_add_i32 s36, s62, s42
	v_lshl_add_u64 v[146:147], v[146:147], 0, s[10:11]
	s_mov_b32 m0, s36
	global_load_lds_dwordx4 v[146:147], off
	s_add_i32 m0, s36, 0x2000
	s_add_u32 s34, s34, 0x100080
	v_lshl_add_u64 v[146:147], v[214:215], 0, s[10:11]
	s_addc_u32 s35, s35, 0
	s_add_i32 s36, s63, s42
	global_load_lds_dwordx4 v[146:147], off
	v_lshl_add_u64 v[146:147], s[34:35], 0, v[132:133]
	s_mov_b32 m0, s36
	s_nop 0
	global_load_lds_dwordx4 v[146:147], off
	v_lshl_add_u64 v[146:147], s[34:35], 0, v[136:137]
	s_add_i32 m0, s36, 0x2000
	s_nop 0
	global_load_lds_dwordx4 v[146:147], off
	ds_read_b128 v[186:189], v152 offset:49152
	ds_read_b128 v[190:193], v152 offset:50176
	ds_read_b128 v[194:197], v152 offset:51200
	ds_read_b128 v[198:201], v152 offset:52224
	ds_read_b128 v[202:205], v152 offset:53248
	ds_read_b128 v[206:209], v152 offset:54272
	ds_read_b128 v[210:213], v152 offset:55296
	ds_read_b128 v[218:221], v152 offset:56320
	s_waitcnt vmcnt(6)
	s_waitcnt lgkmcnt(0)
	s_barrier
	s_setprio 1
	s_waitcnt lgkmcnt(0)
	v_mfma_f32_16x16x32_bf16 v[62:65], v[154:157], v[186:189], v[62:65]
	v_mfma_f32_16x16x32_bf16 v[58:61], v[162:165], v[186:189], v[58:61]
	v_mfma_f32_16x16x32_bf16 v[50:53], v[154:157], v[194:197], v[50:53]
	v_mfma_f32_16x16x32_bf16 v[42:45], v[162:165], v[194:197], v[42:45]
	v_mfma_f32_16x16x32_bf16 v[34:37], v[154:157], v[202:205], v[34:37]
	v_mfma_f32_16x16x32_bf16 v[26:29], v[162:165], v[202:205], v[26:29]
	v_mfma_f32_16x16x32_bf16 v[18:21], v[154:157], v[210:213], v[18:21]
	v_mfma_f32_16x16x32_bf16 v[10:13], v[162:165], v[210:213], v[10:13]
	v_mfma_f32_16x16x32_bf16 v[62:65], v[158:161], v[190:193], v[62:65]
	v_mfma_f32_16x16x32_bf16 v[58:61], v[166:169], v[190:193], v[58:61]
	v_mfma_f32_16x16x32_bf16 v[50:53], v[158:161], v[198:201], v[50:53]
	v_mfma_f32_16x16x32_bf16 v[42:45], v[166:169], v[198:201], v[42:45]
	v_mfma_f32_16x16x32_bf16 v[34:37], v[158:161], v[206:209], v[34:37]
	v_mfma_f32_16x16x32_bf16 v[26:29], v[166:169], v[206:209], v[26:29]
	v_mfma_f32_16x16x32_bf16 v[18:21], v[158:161], v[218:221], v[18:21]
	v_mfma_f32_16x16x32_bf16 v[10:13], v[166:169], v[218:221], v[10:13]
	s_setprio 0
	s_setprio 1
	v_mfma_f32_16x16x32_bf16 v[54:57], v[170:173], v[186:189], v[54:57]
	v_mfma_f32_16x16x32_bf16 v[46:49], v[178:181], v[186:189], v[46:49]
	v_mfma_f32_16x16x32_bf16 v[38:41], v[170:173], v[194:197], v[38:41]
	v_mfma_f32_16x16x32_bf16 v[30:33], v[178:181], v[194:197], v[30:33]
	v_mfma_f32_16x16x32_bf16 v[22:25], v[170:173], v[202:205], v[22:25]
	v_mfma_f32_16x16x32_bf16 v[14:17], v[178:181], v[202:205], v[14:17]
	v_mfma_f32_16x16x32_bf16 v[6:9], v[170:173], v[210:213], v[6:9]
	v_mfma_f32_16x16x32_bf16 v[2:5], v[178:181], v[210:213], v[2:5]
	v_mfma_f32_16x16x32_bf16 v[54:57], v[174:177], v[190:193], v[54:57]
	v_mfma_f32_16x16x32_bf16 v[46:49], v[182:185], v[190:193], v[46:49]
	v_mfma_f32_16x16x32_bf16 v[38:41], v[174:177], v[198:201], v[38:41]
	v_mfma_f32_16x16x32_bf16 v[30:33], v[182:185], v[198:201], v[30:33]
	v_mfma_f32_16x16x32_bf16 v[22:25], v[174:177], v[206:209], v[22:25]
	v_mfma_f32_16x16x32_bf16 v[14:17], v[182:185], v[206:209], v[14:17]
	v_mfma_f32_16x16x32_bf16 v[6:9], v[174:177], v[218:221], v[6:9]
	v_mfma_f32_16x16x32_bf16 v[2:5], v[182:185], v[218:221], v[2:5]
	s_setprio 0
	s_barrier
	v_lshl_add_u64 v[146:147], v[222:223], 0, s[10:11]
	s_mov_b32 m0, s47
	s_nop 0
	global_load_lds_dwordx4 v[146:147], off
	v_lshl_add_u64 v[146:147], v[224:225], 0, s[10:11]
	s_mov_b32 m0, s48
	s_nop 0
	global_load_lds_dwordx4 v[146:147], off
	s_add_i32 s61, s61, 2
	s_add_u32 s30, s30, 0x100
	s_addc_u32 s31, s31, 0
	s_add_u32 s59, s59, 0x100
	s_addc_u32 s60, s60, 0
	s_cmp_gt_u32 s61, 61
	s_cbranch_scc0 .LBB0_966
	s_and_b64 vcc, exec, s[12:13]
	s_cbranch_vccz .LBB0_969
	s_barrier

; #define PG8_STAGE(bufoff, gbase, voff) do { _Pragma("unroll") for (int _i = 0; _i < 2; ++_i) \
;         __builtin_amdgcn_global_load_lds((const unsigned*)((const char*)(gbase) + (voff)[_i]), (PG8_LAS unsigned*)(lds + (bufoff) + ldsw + _i * 8192), 16, 0, 0); } while (0)
; #define PG8_LDA(dst, b, h) do { _Pragma("unroll") for (int m = 0; m < 4; ++m) _Pragma("unroll") for (int k = 0; k < 2; ++k) dst[m][k] = *(const PG8_LAS bf16x8*)(lds + PG8_SA(b, h) + aoff + m * 2048 + k * 1024); } while (0)
; #define PG8_LDB(dst, b, h) do { _Pragma("unroll") for (int n = 0; n < 2; ++n) _Pragma("unroll") for (int k = 0; k < 2; ++k) dst[n][k] = *(const PG8_LAS bf16x8*)(lds + PG8_SB(b, h) + boff + n * 2048 + k * 1024); } while (0)
; #define PG8_MMA(ai, bj, At, Bt) do { __builtin_amdgcn_s_setprio(1); _Pragma("unroll") for (int m = 0; m < 4; ++m) _Pragma("unroll") for (int n = 0; n < 2; ++n) _Pragma("unroll") for (int k = 0; k < 2; ++k) \
;         acc[ai][bj][m][n] = __builtin_amdgcn_mfma_f32_16x16x32_bf16(Bt[n][k], At[m][k], acc[ai][bj][m][n], 0, 0, 0); __builtin_amdgcn_s_setprio(0); } while (0)
; #define PG8_WAIT_V(n) asm volatile("s_waitcnt vmcnt(" #n ")" ::: "memory")
; #define PG8_WAIT_L(n) asm volatile("s_waitcnt lgkmcnt(" #n ")" ::: "memory")
; #define PG8_BAR __builtin_amdgcn_s_barrier()
; #define PG8_SCHED __builtin_amdgcn_sched_barrier(0)
; template <class Epi, class Sched, bool ALIGN_EPI = false, bool SP2 = false>
; __device__ __forceinline__ void gemm_phase(PG8_LAS unsigned char* lds, const Gemm g, const Sched& S, const Epi& E) {
;     ...
;         for (int t = 0; t < nt; t += 2) {
;             const bool last = (t == nt - 2);
;             const char* a1 = cA + (size_t)(t + 1) * kstep;
;             const char* a2 = last ? nA : cA + (size_t)(t + 2) * kstep; const char* b2 = last ? nB : cB + (size_t)(t + 2) * kstep;
;             const char* a3 = a2 + kstep; const char* b3 = b2 + kstep;
;             if (last && has_next) S.a_ready(nxt);
;             if constexpr (SP2) {
;             PG8_LDB(B0, 0, 0); PG8_LDB(B1, 0, 1); PG8_SCHED; PG8_LDA(At, 0, 0); PG8_STAGE(PG8_SA(1, 1), a1 + hstepA, voffA);
;             PG8_WAIT_V(8); PG8_WAIT_L(0); PG8_BAR; PG8_MMA(0, 0, At, B0); PG8_MMA(0, 1, At, B1); PG8_BAR; PG8_SCHED;
;             PG8_LDA(At, 0, 1); PG8_STAGE(PG8_SB(0, 0), b2, voffB); PG8_STAGE(PG8_SB(0, 1), b2 + hstepB, voffB); PG8_STAGE(PG8_SA(0, 0), a2, voffA);
.LBB0_1097:
	ds_read_b128 v[156:159], v153
	ds_read_b128 v[160:163], v153 offset:1024
	ds_read_b128 v[164:167], v153 offset:2048
	ds_read_b128 v[168:171], v153 offset:3072
	ds_read_b128 v[172:175], v154
	ds_read_b128 v[176:179], v154 offset:1024
	ds_read_b128 v[180:183], v154 offset:2048
	ds_read_b128 v[184:187], v154 offset:3072
	s_add_u32 s36, s34, 0xfff00080
	s_addc_u32 s37, s35, -1
	s_cmp_eq_u32 s63, 60
	s_cselect_b32 s39, s25, s37
	s_cselect_b32 s38, s59, s36
	s_cselect_b32 s37, s23, s62
	s_cselect_b32 s36, s60, s61
	v_lshl_add_u64 v[148:149], s[34:35], 0, v[138:139]
	s_add_i32 m0, s31, 0xc000
	ds_read_b128 v[188:191], v155
	ds_read_b128 v[192:195], v155 offset:1024
	ds_read_b128 v[196:199], v155 offset:2048
	ds_read_b128 v[200:203], v155 offset:3072
	ds_read_b128 v[204:207], v155 offset:4096
	ds_read_b128 v[208:211], v155 offset:5120
	ds_read_b128 v[212:215], v155 offset:6144
	ds_read_b128 v[218:221], v155 offset:7168
	global_load_lds_dwordx4 v[148:149], off
	v_lshl_add_u64 v[148:149], s[34:35], 0, v[140:141]
	s_add_i32 m0, s31, 0xe000
	s_nop 0
	global_load_lds_dwordx4 v[148:149], off
	s_waitcnt vmcnt(8)
	s_waitcnt lgkmcnt(0)
	s_barrier
	s_setprio 1
	s_waitcnt lgkmcnt(0)
	v_mfma_f32_16x16x32_bf16 v[126:129], v[156:159], v[188:191], v[126:129]
	v_mfma_f32_16x16x32_bf16 v[122:125], v[164:167], v[188:191], v[122:125]
	v_mfma_f32_16x16x32_bf16 v[118:121], v[156:159], v[196:199], v[118:121]
	v_mfma_f32_16x16x32_bf16 v[114:117], v[164:167], v[196:199], v[114:117]
	v_mfma_f32_16x16x32_bf16 v[110:113], v[156:159], v[204:207], v[110:113]
	v_mfma_f32_16x16x32_bf16 v[102:105], v[164:167], v[204:207], v[102:105]
	v_mfma_f32_16x16x32_bf16 v[94:97], v[156:159], v[212:215], v[94:97]
	v_mfma_f32_16x16x32_bf16 v[74:77], v[164:167], v[212:215], v[74:77]
	v_mfma_f32_16x16x32_bf16 v[126:129], v[160:163], v[192:195], v[126:129]
	v_mfma_f32_16x16x32_bf16 v[122:125], v[168:171], v[192:195], v[122:125]
	v_mfma_f32_16x16x32_bf16 v[118:121], v[160:163], v[200:203], v[118:121]
	v_mfma_f32_16x16x32_bf16 v[114:117], v[168:171], v[200:203], v[114:117]
	v_mfma_f32_16x16x32_bf16 v[110:113], v[160:163], v[208:211], v[110:113]
	v_mfma_f32_16x16x32_bf16 v[102:105], v[168:171], v[208:211], v[102:105]
	v_mfma_f32_16x16x32_bf16 v[94:97], v[160:163], v[218:221], v[94:97]
	v_mfma_f32_16x16x32_bf16 v[74:77], v[168:171], v[218:221], v[74:77]
	s_setprio 0
	s_setprio 1
	v_mfma_f32_16x16x32_bf16 v[106:109], v[172:175], v[188:191], v[106:109]
	v_mfma_f32_16x16x32_bf16 v[98:101], v[180:183], v[188:191], v[98:101]
	v_mfma_f32_16x16x32_bf16 v[90:93], v[172:175], v[196:199], v[90:93]
	v_mfma_f32_16x16x32_bf16 v[86:89], v[180:183], v[196:199], v[86:89]
	v_mfma_f32_16x16x32_bf16 v[82:85], v[172:175], v[204:207], v[82:85]
	v_mfma_f32_16x16x32_bf16 v[78:81], v[180:183], v[204:207], v[78:81]
	v_mfma_f32_16x16x32_bf16 v[70:73], v[172:175], v[212:215], v[70:73]
	v_mfma_f32_16x16x32_bf16 v[66:69], v[180:183], v[212:215], v[66:69]
	v_mfma_f32_16x16x32_bf16 v[106:109], v[176:179], v[192:195], v[106:109]
	v_mfma_f32_16x16x32_bf16 v[98:101], v[184:187], v[192:195], v[98:101]
	v_mfma_f32_16x16x32_bf16 v[90:93], v[176:179], v[200:203], v[90:93]
	v_mfma_f32_16x16x32_bf16 v[86:89], v[184:187], v[200:203], v[86:89]
	v_mfma_f32_16x16x32_bf16 v[82:85], v[176:179], v[208:211], v[82:85]
	v_mfma_f32_16x16x32_bf16 v[78:81], v[184:187], v[208:211], v[78:81]
	v_mfma_f32_16x16x32_bf16 v[70:73], v[176:179], v[218:221], v[70:73]
	v_mfma_f32_16x16x32_bf16 v[66:69], v[184:187], v[218:221], v[66:69]
	s_setprio 0
	s_barrier
	s_add_i32 s64, s52, s44
	v_lshl_add_u64 v[148:149], s[36:37], 0, v[132:133]
	s_mov_b32 m0, s64
	global_load_lds_dwordx4 v[148:149], off
	s_add_i32 m0, s64, 0x2000
	s_add_u32 s64, s36, 0x100000
	v_lshl_add_u64 v[222:223], s[36:37], 0, v[136:137]
	s_addc_u32 s65, s37, 0
	s_add_i32 s66, s53, s44
	global_load_lds_dwordx4 v[222:223], off
	v_lshl_add_u64 v[224:225], s[64:65], 0, v[132:133]
	s_mov_b32 m0, s66
	v_lshl_add_u64 v[226:227], s[38:39], 0, v[134:135]
	global_load_lds_dwordx4 v[224:225], off
	v_lshl_add_u64 v[224:225], s[64:65], 0, v[136:137]
	s_add_i32 m0, s66, 0x2000
	s_nop 0
	global_load_lds_dwordx4 v[224:225], off
	v_lshl_add_u64 v[224:225], s[38:39], 0, v[130:131]
	ds_read_b128 v[188:191], v155 offset:16384
	ds_read_b128 v[192:195], v155 offset:17408
	ds_read_b128 v[196:199], v155 offset:18432
	ds_read_b128 v[200:203], v155 offset:19456
	ds_read_b128 v[204:207], v155 offset:20480
	ds_read_b128 v[208:211], v155 offset:21504
	ds_read_b128 v[212:215], v155 offset:22528
	ds_read_b128 v[218:221], v155 offset:23552
	s_waitcnt vmcnt(6)
	s_waitcnt lgkmcnt(0)
	s_barrier
; #define PG8_STAGE(bufoff, gbase, voff) do { _Pragma("unroll") for (int _i = 0; _i < 2; ++_i) \
;         __builtin_amdgcn_global_load_lds((const unsigned*)((const char*)(gbase) + (voff)[_i]), (PG8_LAS unsigned*)(lds + (bufoff) + ldsw + _i * 8192), 16, 0, 0); } while (0)
; #define PG8_LDA(dst, b, h) do { _Pragma("unroll") for (int m = 0; m < 4; ++m) _Pragma("unroll") for (int k = 0; k < 2; ++k) dst[m][k] = *(const PG8_LAS bf16x8*)(lds + PG8_SA(b, h) + aoff + m * 2048 + k * 1024); } while (0)
; #define PG8_LDB(dst, b, h) do { _Pragma("unroll") for (int n = 0; n < 2; ++n) _Pragma("unroll") for (int k = 0; k < 2; ++k) dst[n][k] = *(const PG8_LAS bf16x8*)(lds + PG8_SB(b, h) + boff + n * 2048 + k * 1024); } while (0)
; #define PG8_MMA(ai, bj, At, Bt) do { __builtin_amdgcn_s_setprio(1); _Pragma("unroll") for (int m = 0; m < 4; ++m) _Pragma("unroll") for (int n = 0; n < 2; ++n) _Pragma("unroll") for (int k = 0; k < 2; ++k) \
;         acc[ai][bj][m][n] = __builtin_amdgcn_mfma_f32_16x16x32_bf16(Bt[n][k], At[m][k], acc[ai][bj][m][n], 0, 0, 0); __builtin_amdgcn_s_setprio(0); } while (0)
; #define PG8_WAIT_V(n) asm volatile("s_waitcnt vmcnt(" #n ")" ::: "memory")
; #define PG8_WAIT_L(n) asm volatile("s_waitcnt lgkmcnt(" #n ")" ::: "memory")
; #define PG8_BAR __builtin_amdgcn_s_barrier()
; #define PG8_SCHED __builtin_amdgcn_sched_barrier(0)
; template <class Epi, class Sched, bool ALIGN_EPI = false, bool SP2 = false>
; __device__ __forceinline__ void gemm_phase(PG8_LAS unsigned char* lds, const Gemm g, const Sched& S, const Epi& E) {
;     ...
;             PG8_WAIT_V(8); PG8_WAIT_L(0); PG8_BAR; PG8_MMA(1, 0, At, B0); PG8_MMA(1, 1, At, B1); PG8_BAR; PG8_SCHED;
;             PG8_LDB(B0, 1, 0); PG8_LDB(B1, 1, 1); PG8_SCHED; PG8_LDA(At, 1, 0); PG8_STAGE(PG8_SA(0, 1), a2 + hstepA, voffA);
;             PG8_WAIT_V(8); PG8_WAIT_L(0); PG8_BAR; PG8_MMA(0, 0, At, B0); PG8_MMA(0, 1, At, B1); PG8_BAR; PG8_SCHED;
	s_setprio 1
	s_waitcnt lgkmcnt(0)
	v_mfma_f32_16x16x32_bf16 v[62:65], v[156:159], v[188:191], v[62:65]
	v_mfma_f32_16x16x32_bf16 v[58:61], v[164:167], v[188:191], v[58:61]
	v_mfma_f32_16x16x32_bf16 v[50:53], v[156:159], v[196:199], v[50:53]
	v_mfma_f32_16x16x32_bf16 v[42:45], v[164:167], v[196:199], v[42:45]
	v_mfma_f32_16x16x32_bf16 v[34:37], v[156:159], v[204:207], v[34:37]
	v_mfma_f32_16x16x32_bf16 v[26:29], v[164:167], v[204:207], v[26:29]
	v_mfma_f32_16x16x32_bf16 v[18:21], v[156:159], v[212:215], v[18:21]
	v_mfma_f32_16x16x32_bf16 v[10:13], v[164:167], v[212:215], v[10:13]
	v_mfma_f32_16x16x32_bf16 v[62:65], v[160:163], v[192:195], v[62:65]
	v_mfma_f32_16x16x32_bf16 v[58:61], v[168:171], v[192:195], v[58:61]
	v_mfma_f32_16x16x32_bf16 v[50:53], v[160:163], v[200:203], v[50:53]
	v_mfma_f32_16x16x32_bf16 v[42:45], v[168:171], v[200:203], v[42:45]
	v_mfma_f32_16x16x32_bf16 v[34:37], v[160:163], v[208:211], v[34:37]
	v_mfma_f32_16x16x32_bf16 v[26:29], v[168:171], v[208:211], v[26:29]
	v_mfma_f32_16x16x32_bf16 v[18:21], v[160:163], v[218:221], v[18:21]
	v_mfma_f32_16x16x32_bf16 v[10:13], v[168:171], v[218:221], v[10:13]
	s_setprio 0
	s_setprio 1
	v_mfma_f32_16x16x32_bf16 v[54:57], v[172:175], v[188:191], v[54:57]
	v_mfma_f32_16x16x32_bf16 v[46:49], v[180:183], v[188:191], v[46:49]
	v_mfma_f32_16x16x32_bf16 v[38:41], v[172:175], v[196:199], v[38:41]
	v_mfma_f32_16x16x32_bf16 v[30:33], v[180:183], v[196:199], v[30:33]
	v_mfma_f32_16x16x32_bf16 v[22:25], v[172:175], v[204:207], v[22:25]
	v_mfma_f32_16x16x32_bf16 v[14:17], v[180:183], v[204:207], v[14:17]
	v_mfma_f32_16x16x32_bf16 v[6:9], v[172:175], v[212:215], v[6:9]
	v_mfma_f32_16x16x32_bf16 v[2:5], v[180:183], v[212:215], v[2:5]
	v_mfma_f32_16x16x32_bf16 v[54:57], v[176:179], v[192:195], v[54:57]
	v_mfma_f32_16x16x32_bf16 v[46:49], v[184:187], v[192:195], v[46:49]
	v_mfma_f32_16x16x32_bf16 v[38:41], v[176:179], v[200:203], v[38:41]
	v_mfma_f32_16x16x32_bf16 v[30:33], v[184:187], v[200:203], v[30:33]
	v_mfma_f32_16x16x32_bf16 v[22:25], v[176:179], v[208:211], v[22:25]
	v_mfma_f32_16x16x32_bf16 v[14:17], v[184:187], v[208:211], v[14:17]
	v_mfma_f32_16x16x32_bf16 v[6:9], v[176:179], v[218:221], v[6:9]
	v_mfma_f32_16x16x32_bf16 v[2:5], v[184:187], v[218:221], v[2:5]
	s_setprio 0
	s_barrier
	s_mov_b32 m0, s31
	s_nop 0
	global_load_lds_dwordx4 v[224:225], off
	s_mov_b32 m0, s45
	s_nop 0
	global_load_lds_dwordx4 v[226:227], off
	s_add_i32 s64, 0, 0x18000
	v_add_u32_e32 v146, s64, v147
	s_add_i32 s65, 0, 0x1c000
	ds_read_b128 v[156:159], v146
	ds_read_b128 v[160:163], v146 offset:1024
	ds_read_b128 v[164:167], v146 offset:2048
	ds_read_b128 v[168:171], v146 offset:3072
	v_add_u32_e32 v146, s65, v147
	ds_read_b128 v[172:175], v146
	ds_read_b128 v[176:179], v146 offset:1024
	ds_read_b128 v[180:183], v146 offset:2048
	ds_read_b128 v[184:187], v146 offset:3072
	s_add_u32 s38, s38, 0x100000
	s_addc_u32 s39, s39, 0
	s_mov_b32 m0, s46
	v_lshl_add_u64 v[228:229], s[38:39], 0, v[130:131]
	ds_read_b128 v[188:191], v155 offset:32768
	ds_read_b128 v[192:195], v155 offset:33792
	ds_read_b128 v[196:199], v155 offset:34816
	ds_read_b128 v[200:203], v155 offset:35840
	ds_read_b128 v[204:207], v155 offset:36864
	ds_read_b128 v[208:211], v155 offset:37888
	ds_read_b128 v[212:215], v155 offset:38912
	ds_read_b128 v[218:221], v155 offset:39936
	global_load_lds_dwordx4 v[228:229], off
	v_lshl_add_u64 v[228:229], s[38:39], 0, v[134:135]
	s_mov_b32 m0, s47
	s_nop 0
	global_load_lds_dwordx4 v[228:229], off
	s_waitcnt vmcnt(8)
	s_waitcnt lgkmcnt(0)
	s_barrier
	s_setprio 1
	s_waitcnt lgkmcnt(0)
	v_mfma_f32_16x16x32_bf16 v[126:129], v[156:159], v[188:191], v[126:129]
	v_mfma_f32_16x16x32_bf16 v[122:125], v[164:167], v[188:191], v[122:125]
	v_mfma_f32_16x16x32_bf16 v[118:121], v[156:159], v[196:199], v[118:121]
	v_mfma_f32_16x16x32_bf16 v[114:117], v[164:167], v[196:199], v[114:117]
	v_mfma_f32_16x16x32_bf16 v[110:113], v[156:159], v[204:207], v[110:113]
	v_mfma_f32_16x16x32_bf16 v[102:105], v[164:167], v[204:207], v[102:105]
	v_mfma_f32_16x16x32_bf16 v[94:97], v[156:159], v[212:215], v[94:97]
	v_mfma_f32_16x16x32_bf16 v[74:77], v[164:167], v[212:215], v[74:77]
	v_mfma_f32_16x16x32_bf16 v[126:129], v[160:163], v[192:195], v[126:129]
	v_mfma_f32_16x16x32_bf16 v[122:125], v[168:171], v[192:195], v[122:125]
	v_mfma_f32_16x16x32_bf16 v[118:121], v[160:163], v[200:203], v[118:121]
	v_mfma_f32_16x16x32_bf16 v[114:117], v[168:171], v[200:203], v[114:117]
	v_mfma_f32_16x16x32_bf16 v[110:113], v[160:163], v[208:211], v[110:113]
	v_mfma_f32_16x16x32_bf16 v[102:105], v[168:171], v[208:211], v[102:105]
	v_mfma_f32_16x16x32_bf16 v[94:97], v[160:163], v[218:221], v[94:97]
	v_mfma_f32_16x16x32_bf16 v[74:77], v[168:171], v[218:221], v[74:77]
	s_setprio 0
	s_setprio 1
	v_mfma_f32_16x16x32_bf16 v[106:109], v[172:175], v[188:191], v[106:109]
	v_mfma_f32_16x16x32_bf16 v[98:101], v[180:183], v[188:191], v[98:101]
	v_mfma_f32_16x16x32_bf16 v[90:93], v[172:175], v[196:199], v[90:93]
	v_mfma_f32_16x16x32_bf16 v[86:89], v[180:183], v[196:199], v[86:89]
	v_mfma_f32_16x16x32_bf16 v[82:85], v[172:175], v[204:207], v[82:85]
	v_mfma_f32_16x16x32_bf16 v[78:81], v[180:183], v[204:207], v[78:81]
	v_mfma_f32_16x16x32_bf16 v[70:73], v[172:175], v[212:215], v[70:73]
	v_mfma_f32_16x16x32_bf16 v[66:69], v[180:183], v[212:215], v[66:69]
	v_mfma_f32_16x16x32_bf16 v[106:109], v[176:179], v[192:195], v[106:109]
	v_mfma_f32_16x16x32_bf16 v[98:101], v[184:187], v[192:195], v[98:101]
	v_mfma_f32_16x16x32_bf16 v[90:93], v[176:179], v[200:203], v[90:93]
	v_mfma_f32_16x16x32_bf16 v[86:89], v[184:187], v[200:203], v[86:89]
	v_mfma_f32_16x16x32_bf16 v[82:85], v[176:179], v[208:211], v[82:85]
	v_mfma_f32_16x16x32_bf16 v[78:81], v[184:187], v[208:211], v[78:81]
	v_mfma_f32_16x16x32_bf16 v[70:73], v[176:179], v[218:221], v[70:73]
	v_mfma_f32_16x16x32_bf16 v[66:69], v[184:187], v[218:221], v[66:69]
	s_setprio 0
	s_barrier
; #define PG8_STAGE(bufoff, gbase, voff) do { _Pragma("unroll") for (int _i = 0; _i < 2; ++_i) \
;         __builtin_amdgcn_global_load_lds((const unsigned*)((const char*)(gbase) + (voff)[_i]), (PG8_LAS unsigned*)(lds + (bufoff) + ldsw + _i * 8192), 16, 0, 0); } while (0)
; #define PG8_LDA(dst, b, h) do { _Pragma("unroll") for (int m = 0; m < 4; ++m) _Pragma("unroll") for (int k = 0; k < 2; ++k) dst[m][k] = *(const PG8_LAS bf16x8*)(lds + PG8_SA(b, h) + aoff + m * 2048 + k * 1024); } while (0)
; #define PG8_MMA(ai, bj, At, Bt) do { __builtin_amdgcn_s_setprio(1); _Pragma("unroll") for (int m = 0; m < 4; ++m) _Pragma("unroll") for (int n = 0; n < 2; ++n) _Pragma("unroll") for (int k = 0; k < 2; ++k) \
;         acc[ai][bj][m][n] = __builtin_amdgcn_mfma_f32_16x16x32_bf16(Bt[n][k], At[m][k], acc[ai][bj][m][n], 0, 0, 0); __builtin_amdgcn_s_setprio(0); } while (0)
; #define PG8_WAIT_V(n) asm volatile("s_waitcnt vmcnt(" #n ")" ::: "memory")
; #define PG8_WAIT_L(n) asm volatile("s_waitcnt lgkmcnt(" #n ")" ::: "memory")
; #define PG8_BAR __builtin_amdgcn_s_barrier()
; #define PG8_SCHED __builtin_amdgcn_sched_barrier(0)
; template <class Epi, class Sched, bool ALIGN_EPI = false, bool SP2 = false>
; __device__ __forceinline__ void gemm_phase(PG8_LAS unsigned char* lds, const Gemm g, const Sched& S, const Epi& E) {
;     ...
;         for (int t = 0; t < nt; t += 2) {
;             const bool last = (t == nt - 2);
;     ...
;             PG8_LDA(At, 1, 1); PG8_STAGE(PG8_SB(1, 0), b3, voffB); PG8_STAGE(PG8_SB(1, 1), b3 + hstepB, voffB); PG8_STAGE(PG8_SA(1, 0), a3, voffA);
;             PG8_WAIT_V(8); PG8_WAIT_L(0); PG8_BAR; PG8_MMA(1, 0, At, B0); PG8_MMA(1, 1, At, B1); PG8_BAR; PG8_SCHED;
	s_add_i32 s38, s64, s44
	v_lshl_add_u64 v[148:149], v[148:149], 0, s[10:11]
	s_mov_b32 m0, s38
	global_load_lds_dwordx4 v[148:149], off
	s_add_i32 m0, s38, 0x2000
	s_add_u32 s36, s36, 0x100080
	v_lshl_add_u64 v[148:149], v[222:223], 0, s[10:11]
	s_addc_u32 s37, s37, 0
	s_add_i32 s38, s65, s44
	global_load_lds_dwordx4 v[148:149], off
	v_lshl_add_u64 v[148:149], s[36:37], 0, v[132:133]
	s_mov_b32 m0, s38
	s_nop 0
	global_load_lds_dwordx4 v[148:149], off
	v_lshl_add_u64 v[148:149], s[36:37], 0, v[136:137]
	s_add_i32 m0, s38, 0x2000
	s_nop 0
	global_load_lds_dwordx4 v[148:149], off
	ds_read_b128 v[188:191], v155 offset:49152
	ds_read_b128 v[192:195], v155 offset:50176
	ds_read_b128 v[196:199], v155 offset:51200
	ds_read_b128 v[200:203], v155 offset:52224
	ds_read_b128 v[204:207], v155 offset:53248
	ds_read_b128 v[208:211], v155 offset:54272
	ds_read_b128 v[212:215], v155 offset:55296
	ds_read_b128 v[218:221], v155 offset:56320
	s_waitcnt vmcnt(6)
	s_waitcnt lgkmcnt(0)
	s_barrier
	s_setprio 1
	s_waitcnt lgkmcnt(0)
	v_mfma_f32_16x16x32_bf16 v[62:65], v[156:159], v[188:191], v[62:65]
	v_mfma_f32_16x16x32_bf16 v[58:61], v[164:167], v[188:191], v[58:61]
	v_mfma_f32_16x16x32_bf16 v[50:53], v[156:159], v[196:199], v[50:53]
	v_mfma_f32_16x16x32_bf16 v[42:45], v[164:167], v[196:199], v[42:45]
	v_mfma_f32_16x16x32_bf16 v[34:37], v[156:159], v[204:207], v[34:37]
	v_mfma_f32_16x16x32_bf16 v[26:29], v[164:167], v[204:207], v[26:29]
	v_mfma_f32_16x16x32_bf16 v[18:21], v[156:159], v[212:215], v[18:21]
	v_mfma_f32_16x16x32_bf16 v[10:13], v[164:167], v[212:215], v[10:13]
	v_mfma_f32_16x16x32_bf16 v[62:65], v[160:163], v[192:195], v[62:65]
	v_mfma_f32_16x16x32_bf16 v[58:61], v[168:171], v[192:195], v[58:61]
	v_mfma_f32_16x16x32_bf16 v[50:53], v[160:163], v[200:203], v[50:53]
	v_mfma_f32_16x16x32_bf16 v[42:45], v[168:171], v[200:203], v[42:45]
	v_mfma_f32_16x16x32_bf16 v[34:37], v[160:163], v[208:211], v[34:37]
	v_mfma_f32_16x16x32_bf16 v[26:29], v[168:171], v[208:211], v[26:29]
	v_mfma_f32_16x16x32_bf16 v[18:21], v[160:163], v[218:221], v[18:21]
	v_mfma_f32_16x16x32_bf16 v[10:13], v[168:171], v[218:221], v[10:13]
	s_setprio 0
	s_setprio 1
	v_mfma_f32_16x16x32_bf16 v[54:57], v[172:175], v[188:191], v[54:57]
	v_mfma_f32_16x16x32_bf16 v[46:49], v[180:183], v[188:191], v[46:49]
	v_mfma_f32_16x16x32_bf16 v[38:41], v[172:175], v[196:199], v[38:41]
	v_mfma_f32_16x16x32_bf16 v[30:33], v[180:183], v[196:199], v[30:33]
	v_mfma_f32_16x16x32_bf16 v[22:25], v[172:175], v[204:207], v[22:25]
	v_mfma_f32_16x16x32_bf16 v[14:17], v[180:183], v[204:207], v[14:17]
	v_mfma_f32_16x16x32_bf16 v[6:9], v[172:175], v[212:215], v[6:9]
	v_mfma_f32_16x16x32_bf16 v[2:5], v[180:183], v[212:215], v[2:5]
	v_mfma_f32_16x16x32_bf16 v[54:57], v[176:179], v[192:195], v[54:57]
	v_mfma_f32_16x16x32_bf16 v[46:49], v[184:187], v[192:195], v[46:49]
	v_mfma_f32_16x16x32_bf16 v[38:41], v[176:179], v[200:203], v[38:41]
	v_mfma_f32_16x16x32_bf16 v[30:33], v[184:187], v[200:203], v[30:33]
	v_mfma_f32_16x16x32_bf16 v[22:25], v[176:179], v[208:211], v[22:25]
	v_mfma_f32_16x16x32_bf16 v[14:17], v[184:187], v[208:211], v[14:17]
	v_mfma_f32_16x16x32_bf16 v[6:9], v[176:179], v[218:221], v[6:9]
	v_mfma_f32_16x16x32_bf16 v[2:5], v[184:187], v[218:221], v[2:5]
	s_setprio 0
	s_barrier
	v_lshl_add_u64 v[148:149], v[224:225], 0, s[10:11]
	s_mov_b32 m0, s49
	s_nop 0
	global_load_lds_dwordx4 v[148:149], off
	v_lshl_add_u64 v[148:149], v[226:227], 0, s[10:11]
	s_mov_b32 m0, s50
	s_nop 0
	global_load_lds_dwordx4 v[148:149], off
	s_add_i32 s63, s63, 2
	s_add_u32 s34, s34, 0x100
	s_addc_u32 s35, s35, 0
	s_add_u32 s61, s61, 0x100
	s_addc_u32 s62, s62, 0
	s_cmp_gt_u32 s63, 61
	s_cbranch_scc0 .LBB0_1097
	s_and_b64 vcc, exec, s[12:13]
	s_cbranch_vccz .LBB0_1100
	s_barrier

; #define PG8_STAGE(bufoff, gbase, voff) do { _Pragma("unroll") for (int _i = 0; _i < 2; ++_i) \
;         __builtin_amdgcn_global_load_lds((const unsigned*)((const char*)(gbase) + (voff)[_i]), (PG8_LAS unsigned*)(lds + (bufoff) + ldsw + _i * 8192), 16, 0, 0); } while (0)
; #define PG8_LDA(dst, b, h) do { _Pragma("unroll") for (int m = 0; m < 4; ++m) _Pragma("unroll") for (int k = 0; k < 2; ++k) dst[m][k] = *(const PG8_LAS bf16x8*)(lds + PG8_SA(b, h) + aoff + m * 2048 + k * 1024); } while (0)
; #define PG8_LDB(dst, b, h) do { _Pragma("unroll") for (int n = 0; n < 2; ++n) _Pragma("unroll") for (int k = 0; k < 2; ++k) dst[n][k] = *(const PG8_LAS bf16x8*)(lds + PG8_SB(b, h) + boff + n * 2048 + k * 1024); } while (0)
; #define PG8_MMA(ai, bj, At, Bt) do { __builtin_amdgcn_s_setprio(1); _Pragma("unroll") for (int m = 0; m < 4; ++m) _Pragma("unroll") for (int n = 0; n < 2; ++n) _Pragma("unroll") for (int k = 0; k < 2; ++k) \
;         acc[ai][bj][m][n] = __builtin_amdgcn_mfma_f32_16x16x32_bf16(Bt[n][k], At[m][k], acc[ai][bj][m][n], 0, 0, 0); __builtin_amdgcn_s_setprio(0); } while (0)
; #define PG8_WAIT_V(n) asm volatile("s_waitcnt vmcnt(" #n ")" ::: "memory")
; #define PG8_WAIT_L(n) asm volatile("s_waitcnt lgkmcnt(" #n ")" ::: "memory")
; #define PG8_BAR __builtin_amdgcn_s_barrier()
; #define PG8_SCHED __builtin_amdgcn_sched_barrier(0)
; template <class Epi, class Sched, bool ALIGN_EPI = false, bool SP2 = false>
; __device__ __forceinline__ void gemm_phase(PG8_LAS unsigned char* lds, const Gemm g, const Sched& S, const Epi& E) {
;     ...
;         for (int t = 0; t < nt; t += 2) {
;             const bool last = (t == nt - 2);
;             const char* a1 = cA + (size_t)(t + 1) * kstep;
;             const char* a2 = last ? nA : cA + (size_t)(t + 2) * kstep; const char* b2 = last ? nB : cB + (size_t)(t + 2) * kstep;
;             const char* a3 = a2 + kstep; const char* b3 = b2 + kstep;
;             if (last && has_next) S.a_ready(nxt);
;             if constexpr (SP2) {
;             PG8_LDB(B0, 0, 0); PG8_LDB(B1, 0, 1); PG8_SCHED; PG8_LDA(At, 0, 0); PG8_STAGE(PG8_SA(1, 1), a1 + hstepA, voffA);
;             PG8_WAIT_V(8); PG8_WAIT_L(0); PG8_BAR; PG8_MMA(0, 0, At, B0); PG8_MMA(0, 1, At, B1); PG8_BAR; PG8_SCHED;
;             PG8_LDA(At, 0, 1); PG8_STAGE(PG8_SB(0, 0), b2, voffB); PG8_STAGE(PG8_SB(0, 1), b2 + hstepB, voffB); PG8_STAGE(PG8_SA(0, 0), a2, voffA);
.LBB0_1743:
	s_lshl_b32 s36, s62, 7
	s_add_u32 s37, s24, s36
	s_addc_u32 s38, s25, 0
	v_add_u32_e32 v140, s53, v143
	s_add_u32 s39, s37, 0x100
	ds_read_b128 v[146:149], v140
	ds_read_b128 v[150:153], v140 offset:1024
	ds_read_b128 v[154:157], v140 offset:2048
	ds_read_b128 v[158:161], v140 offset:3072
	v_add_u32_e32 v140, s54, v143
	s_addc_u32 s63, s38, 0
	ds_read_b128 v[162:165], v140
	ds_read_b128 v[166:169], v140 offset:1024
	ds_read_b128 v[170:173], v140 offset:2048
	ds_read_b128 v[174:177], v140 offset:3072
	s_and_b64 s[34:35], s[30:31], exec
	s_cselect_b32 s35, s23, s63
	s_cselect_b32 s34, s59, s39
	s_add_u32 s36, s26, s36
	s_addc_u32 s39, s27, 0
	s_add_u32 s36, s36, 0x100
	s_addc_u32 s39, s39, 0
	s_and_b64 s[30:31], s[30:31], exec
	s_cselect_b32 s31, s60, s39
	s_cselect_b32 s30, s61, s36
	s_add_u32 s36, s37, 0x100080
	s_addc_u32 s37, s38, 0
	v_lshl_add_u64 v[140:141], s[36:37], 0, v[130:131]
	s_add_i32 m0, s45, 0xc000
	ds_read_b128 v[178:181], v144
	ds_read_b128 v[182:185], v144 offset:1024
	ds_read_b128 v[186:189], v144 offset:2048
	ds_read_b128 v[190:193], v144 offset:3072
	ds_read_b128 v[194:197], v144 offset:4096
	ds_read_b128 v[198:201], v144 offset:5120
	ds_read_b128 v[202:205], v144 offset:6144
	ds_read_b128 v[206:209], v144 offset:7168
	global_load_lds_dwordx4 v[140:141], off
	v_lshl_add_u64 v[140:141], s[36:37], 0, v[134:135]
	s_add_i32 m0, s45, 0xe000
	s_nop 0
	global_load_lds_dwordx4 v[140:141], off
	s_waitcnt vmcnt(8)
	s_waitcnt lgkmcnt(0)
	s_barrier
	s_setprio 1
	s_waitcnt lgkmcnt(0)
	v_mfma_f32_16x16x32_bf16 v[126:129], v[146:149], v[178:181], v[126:129]
	v_mfma_f32_16x16x32_bf16 v[122:125], v[154:157], v[178:181], v[122:125]
	v_mfma_f32_16x16x32_bf16 v[114:117], v[146:149], v[186:189], v[114:117]
	v_mfma_f32_16x16x32_bf16 v[106:109], v[154:157], v[186:189], v[106:109]
	v_mfma_f32_16x16x32_bf16 v[98:101], v[146:149], v[194:197], v[98:101]
	v_mfma_f32_16x16x32_bf16 v[90:93], v[154:157], v[194:197], v[90:93]
	v_mfma_f32_16x16x32_bf16 v[82:85], v[146:149], v[202:205], v[82:85]
	v_mfma_f32_16x16x32_bf16 v[74:77], v[154:157], v[202:205], v[74:77]
	v_mfma_f32_16x16x32_bf16 v[126:129], v[150:153], v[182:185], v[126:129]
	v_mfma_f32_16x16x32_bf16 v[122:125], v[158:161], v[182:185], v[122:125]
	v_mfma_f32_16x16x32_bf16 v[114:117], v[150:153], v[190:193], v[114:117]
	v_mfma_f32_16x16x32_bf16 v[106:109], v[158:161], v[190:193], v[106:109]
	v_mfma_f32_16x16x32_bf16 v[98:101], v[150:153], v[198:201], v[98:101]
	v_mfma_f32_16x16x32_bf16 v[90:93], v[158:161], v[198:201], v[90:93]
	v_mfma_f32_16x16x32_bf16 v[82:85], v[150:153], v[206:209], v[82:85]
	v_mfma_f32_16x16x32_bf16 v[74:77], v[158:161], v[206:209], v[74:77]
	s_setprio 0
	s_setprio 1
	v_mfma_f32_16x16x32_bf16 v[118:121], v[162:165], v[178:181], v[118:121]
	v_mfma_f32_16x16x32_bf16 v[110:113], v[170:173], v[178:181], v[110:113]
	v_mfma_f32_16x16x32_bf16 v[102:105], v[162:165], v[186:189], v[102:105]
	v_mfma_f32_16x16x32_bf16 v[94:97], v[170:173], v[186:189], v[94:97]
	v_mfma_f32_16x16x32_bf16 v[86:89], v[162:165], v[194:197], v[86:89]
	v_mfma_f32_16x16x32_bf16 v[78:81], v[170:173], v[194:197], v[78:81]
	v_mfma_f32_16x16x32_bf16 v[70:73], v[162:165], v[202:205], v[70:73]
	v_mfma_f32_16x16x32_bf16 v[66:69], v[170:173], v[202:205], v[66:69]
	v_mfma_f32_16x16x32_bf16 v[118:121], v[166:169], v[182:185], v[118:121]
	v_mfma_f32_16x16x32_bf16 v[110:113], v[174:177], v[182:185], v[110:113]
	v_mfma_f32_16x16x32_bf16 v[102:105], v[166:169], v[190:193], v[102:105]
	v_mfma_f32_16x16x32_bf16 v[94:97], v[174:177], v[190:193], v[94:97]
	v_mfma_f32_16x16x32_bf16 v[86:89], v[166:169], v[198:201], v[86:89]
	v_mfma_f32_16x16x32_bf16 v[78:81], v[174:177], v[198:201], v[78:81]
	v_mfma_f32_16x16x32_bf16 v[70:73], v[166:169], v[206:209], v[70:73]
	v_mfma_f32_16x16x32_bf16 v[66:69], v[174:177], v[206:209], v[66:69]
	s_setprio 0
	s_barrier
	s_add_i32 s36, s53, s43
	v_lshl_add_u64 v[140:141], s[30:31], 0, v[132:133]
	s_mov_b32 m0, s36
	global_load_lds_dwordx4 v[140:141], off
	s_add_i32 m0, s36, 0x2000
	s_add_u32 s36, s30, 0x100000
	v_lshl_add_u64 v[210:211], s[30:31], 0, v[136:137]
	s_addc_u32 s37, s31, 0
	s_add_i32 s38, s54, s43
	global_load_lds_dwordx4 v[210:211], off
	v_lshl_add_u64 v[212:213], s[36:37], 0, v[132:133]
	s_mov_b32 m0, s38
	v_lshl_add_u64 v[214:215], s[34:35], 0, v[134:135]
	global_load_lds_dwordx4 v[212:213], off
	v_lshl_add_u64 v[212:213], s[36:37], 0, v[136:137]
	s_add_i32 m0, s38, 0x2000
	s_nop 0
	global_load_lds_dwordx4 v[212:213], off
	v_lshl_add_u64 v[212:213], s[34:35], 0, v[130:131]
	ds_read_b128 v[178:181], v144 offset:16384
	ds_read_b128 v[182:185], v144 offset:17408
	ds_read_b128 v[186:189], v144 offset:18432
	ds_read_b128 v[190:193], v144 offset:19456
	ds_read_b128 v[194:197], v144 offset:20480
	ds_read_b128 v[198:201], v144 offset:21504
	ds_read_b128 v[202:205], v144 offset:22528
	ds_read_b128 v[206:209], v144 offset:23552
	s_waitcnt vmcnt(6)
	s_waitcnt lgkmcnt(0)
	s_barrier
; #define PG8_STAGE(bufoff, gbase, voff) do { _Pragma("unroll") for (int _i = 0; _i < 2; ++_i) \
;         __builtin_amdgcn_global_load_lds((const unsigned*)((const char*)(gbase) + (voff)[_i]), (PG8_LAS unsigned*)(lds + (bufoff) + ldsw + _i * 8192), 16, 0, 0); } while (0)
; #define PG8_LDA(dst, b, h) do { _Pragma("unroll") for (int m = 0; m < 4; ++m) _Pragma("unroll") for (int k = 0; k < 2; ++k) dst[m][k] = *(const PG8_LAS bf16x8*)(lds + PG8_SA(b, h) + aoff + m * 2048 + k * 1024); } while (0)
; #define PG8_LDB(dst, b, h) do { _Pragma("unroll") for (int n = 0; n < 2; ++n) _Pragma("unroll") for (int k = 0; k < 2; ++k) dst[n][k] = *(const PG8_LAS bf16x8*)(lds + PG8_SB(b, h) + boff + n * 2048 + k * 1024); } while (0)
; #define PG8_MMA(ai, bj, At, Bt) do { __builtin_amdgcn_s_setprio(1); _Pragma("unroll") for (int m = 0; m < 4; ++m) _Pragma("unroll") for (int n = 0; n < 2; ++n) _Pragma("unroll") for (int k = 0; k < 2; ++k) \
;         acc[ai][bj][m][n] = __builtin_amdgcn_mfma_f32_16x16x32_bf16(Bt[n][k], At[m][k], acc[ai][bj][m][n], 0, 0, 0); __builtin_amdgcn_s_setprio(0); } while (0)
; #define PG8_WAIT_V(n) asm volatile("s_waitcnt vmcnt(" #n ")" ::: "memory")
; #define PG8_WAIT_L(n) asm volatile("s_waitcnt lgkmcnt(" #n ")" ::: "memory")
; #define PG8_BAR __builtin_amdgcn_s_barrier()
; #define PG8_SCHED __builtin_amdgcn_sched_barrier(0)
; template <class Epi, class Sched, bool ALIGN_EPI = false, bool SP2 = false>
; __device__ __forceinline__ void gemm_phase(PG8_LAS unsigned char* lds, const Gemm g, const Sched& S, const Epi& E) {
;     ...
;             PG8_WAIT_V(8); PG8_WAIT_L(0); PG8_BAR; PG8_MMA(1, 0, At, B0); PG8_MMA(1, 1, At, B1); PG8_BAR; PG8_SCHED;
;             PG8_LDB(B0, 1, 0); PG8_LDB(B1, 1, 1); PG8_SCHED; PG8_LDA(At, 1, 0); PG8_STAGE(PG8_SA(0, 1), a2 + hstepA, voffA);
;             PG8_WAIT_V(8); PG8_WAIT_L(0); PG8_BAR; PG8_MMA(0, 0, At, B0); PG8_MMA(0, 1, At, B1); PG8_BAR; PG8_SCHED;
	s_setprio 1
	s_waitcnt lgkmcnt(0)
	v_mfma_f32_16x16x32_bf16 v[62:65], v[146:149], v[178:181], v[62:65]
	v_mfma_f32_16x16x32_bf16 v[58:61], v[154:157], v[178:181], v[58:61]
	v_mfma_f32_16x16x32_bf16 v[50:53], v[146:149], v[186:189], v[50:53]
	v_mfma_f32_16x16x32_bf16 v[42:45], v[154:157], v[186:189], v[42:45]
	v_mfma_f32_16x16x32_bf16 v[34:37], v[146:149], v[194:197], v[34:37]
	v_mfma_f32_16x16x32_bf16 v[26:29], v[154:157], v[194:197], v[26:29]
	v_mfma_f32_16x16x32_bf16 v[18:21], v[146:149], v[202:205], v[18:21]
	v_mfma_f32_16x16x32_bf16 v[10:13], v[154:157], v[202:205], v[10:13]
	v_mfma_f32_16x16x32_bf16 v[62:65], v[150:153], v[182:185], v[62:65]
	v_mfma_f32_16x16x32_bf16 v[58:61], v[158:161], v[182:185], v[58:61]
	v_mfma_f32_16x16x32_bf16 v[50:53], v[150:153], v[190:193], v[50:53]
	v_mfma_f32_16x16x32_bf16 v[42:45], v[158:161], v[190:193], v[42:45]
	v_mfma_f32_16x16x32_bf16 v[34:37], v[150:153], v[198:201], v[34:37]
	v_mfma_f32_16x16x32_bf16 v[26:29], v[158:161], v[198:201], v[26:29]
	v_mfma_f32_16x16x32_bf16 v[18:21], v[150:153], v[206:209], v[18:21]
	v_mfma_f32_16x16x32_bf16 v[10:13], v[158:161], v[206:209], v[10:13]
	s_setprio 0
	s_setprio 1
	v_mfma_f32_16x16x32_bf16 v[54:57], v[162:165], v[178:181], v[54:57]
	v_mfma_f32_16x16x32_bf16 v[46:49], v[170:173], v[178:181], v[46:49]
	v_mfma_f32_16x16x32_bf16 v[38:41], v[162:165], v[186:189], v[38:41]
	v_mfma_f32_16x16x32_bf16 v[30:33], v[170:173], v[186:189], v[30:33]
	v_mfma_f32_16x16x32_bf16 v[22:25], v[162:165], v[194:197], v[22:25]
	v_mfma_f32_16x16x32_bf16 v[14:17], v[170:173], v[194:197], v[14:17]
	v_mfma_f32_16x16x32_bf16 v[6:9], v[162:165], v[202:205], v[6:9]
	v_mfma_f32_16x16x32_bf16 v[2:5], v[170:173], v[202:205], v[2:5]
	v_mfma_f32_16x16x32_bf16 v[54:57], v[166:169], v[182:185], v[54:57]
	v_mfma_f32_16x16x32_bf16 v[46:49], v[174:177], v[182:185], v[46:49]
	v_mfma_f32_16x16x32_bf16 v[38:41], v[166:169], v[190:193], v[38:41]
	v_mfma_f32_16x16x32_bf16 v[30:33], v[174:177], v[190:193], v[30:33]
	v_mfma_f32_16x16x32_bf16 v[22:25], v[166:169], v[198:201], v[22:25]
	v_mfma_f32_16x16x32_bf16 v[14:17], v[174:177], v[198:201], v[14:17]
	v_mfma_f32_16x16x32_bf16 v[6:9], v[166:169], v[206:209], v[6:9]
	v_mfma_f32_16x16x32_bf16 v[2:5], v[174:177], v[206:209], v[2:5]
	s_setprio 0
	s_barrier
	s_mov_b32 m0, s45
	s_nop 0
	global_load_lds_dwordx4 v[212:213], off
	s_mov_b32 m0, s46
	s_nop 0
	global_load_lds_dwordx4 v[214:215], off
	s_add_i32 s36, 0, 0x18000
	v_add_u32_e32 v145, s36, v143
	s_add_i32 s37, 0, 0x1c000
	ds_read_b128 v[146:149], v145
	ds_read_b128 v[150:153], v145 offset:1024
	ds_read_b128 v[154:157], v145 offset:2048
	ds_read_b128 v[158:161], v145 offset:3072
	v_add_u32_e32 v145, s37, v143
	ds_read_b128 v[162:165], v145
	ds_read_b128 v[166:169], v145 offset:1024
	ds_read_b128 v[170:173], v145 offset:2048
	ds_read_b128 v[174:177], v145 offset:3072
	s_add_u32 s34, s34, 0x100000
	s_addc_u32 s35, s35, 0
	s_mov_b32 m0, s47
	v_lshl_add_u64 v[218:219], s[34:35], 0, v[130:131]
	ds_read_b128 v[178:181], v144 offset:32768
	ds_read_b128 v[182:185], v144 offset:33792
	ds_read_b128 v[186:189], v144 offset:34816
	ds_read_b128 v[190:193], v144 offset:35840
	ds_read_b128 v[194:197], v144 offset:36864
	ds_read_b128 v[198:201], v144 offset:37888
	ds_read_b128 v[202:205], v144 offset:38912
	ds_read_b128 v[206:209], v144 offset:39936
	global_load_lds_dwordx4 v[218:219], off
	v_lshl_add_u64 v[218:219], s[34:35], 0, v[134:135]
	s_mov_b32 m0, s48
	s_nop 0
	global_load_lds_dwordx4 v[218:219], off
	s_waitcnt vmcnt(8)
	s_waitcnt lgkmcnt(0)
	s_barrier
	s_setprio 1
	s_waitcnt lgkmcnt(0)
	v_mfma_f32_16x16x32_bf16 v[126:129], v[146:149], v[178:181], v[126:129]
	v_mfma_f32_16x16x32_bf16 v[122:125], v[154:157], v[178:181], v[122:125]
	v_mfma_f32_16x16x32_bf16 v[114:117], v[146:149], v[186:189], v[114:117]
	v_mfma_f32_16x16x32_bf16 v[106:109], v[154:157], v[186:189], v[106:109]
	v_mfma_f32_16x16x32_bf16 v[98:101], v[146:149], v[194:197], v[98:101]
	v_mfma_f32_16x16x32_bf16 v[90:93], v[154:157], v[194:197], v[90:93]
	v_mfma_f32_16x16x32_bf16 v[82:85], v[146:149], v[202:205], v[82:85]
	v_mfma_f32_16x16x32_bf16 v[74:77], v[154:157], v[202:205], v[74:77]
	v_mfma_f32_16x16x32_bf16 v[126:129], v[150:153], v[182:185], v[126:129]
	v_mfma_f32_16x16x32_bf16 v[122:125], v[158:161], v[182:185], v[122:125]
	v_mfma_f32_16x16x32_bf16 v[114:117], v[150:153], v[190:193], v[114:117]
	v_mfma_f32_16x16x32_bf16 v[106:109], v[158:161], v[190:193], v[106:109]
	v_mfma_f32_16x16x32_bf16 v[98:101], v[150:153], v[198:201], v[98:101]
	v_mfma_f32_16x16x32_bf16 v[90:93], v[158:161], v[198:201], v[90:93]
	v_mfma_f32_16x16x32_bf16 v[82:85], v[150:153], v[206:209], v[82:85]
	v_mfma_f32_16x16x32_bf16 v[74:77], v[158:161], v[206:209], v[74:77]
	s_setprio 0
	s_setprio 1
	v_mfma_f32_16x16x32_bf16 v[118:121], v[162:165], v[178:181], v[118:121]
	v_mfma_f32_16x16x32_bf16 v[110:113], v[170:173], v[178:181], v[110:113]
	v_mfma_f32_16x16x32_bf16 v[102:105], v[162:165], v[186:189], v[102:105]
	v_mfma_f32_16x16x32_bf16 v[94:97], v[170:173], v[186:189], v[94:97]
	v_mfma_f32_16x16x32_bf16 v[86:89], v[162:165], v[194:197], v[86:89]
	v_mfma_f32_16x16x32_bf16 v[78:81], v[170:173], v[194:197], v[78:81]
	v_mfma_f32_16x16x32_bf16 v[70:73], v[162:165], v[202:205], v[70:73]
	v_mfma_f32_16x16x32_bf16 v[66:69], v[170:173], v[202:205], v[66:69]
	v_mfma_f32_16x16x32_bf16 v[118:121], v[166:169], v[182:185], v[118:121]
	v_mfma_f32_16x16x32_bf16 v[110:113], v[174:177], v[182:185], v[110:113]
	v_mfma_f32_16x16x32_bf16 v[102:105], v[166:169], v[190:193], v[102:105]
	v_mfma_f32_16x16x32_bf16 v[94:97], v[174:177], v[190:193], v[94:97]
	v_mfma_f32_16x16x32_bf16 v[86:89], v[166:169], v[198:201], v[86:89]
	v_mfma_f32_16x16x32_bf16 v[78:81], v[174:177], v[198:201], v[78:81]
	v_mfma_f32_16x16x32_bf16 v[70:73], v[166:169], v[206:209], v[70:73]
	v_mfma_f32_16x16x32_bf16 v[66:69], v[174:177], v[206:209], v[66:69]
	s_setprio 0
	s_barrier
; #define PG8_STAGE(bufoff, gbase, voff) do { _Pragma("unroll") for (int _i = 0; _i < 2; ++_i) \
;         __builtin_amdgcn_global_load_lds((const unsigned*)((const char*)(gbase) + (voff)[_i]), (PG8_LAS unsigned*)(lds + (bufoff) + ldsw + _i * 8192), 16, 0, 0); } while (0)
; #define PG8_LDA(dst, b, h) do { _Pragma("unroll") for (int m = 0; m < 4; ++m) _Pragma("unroll") for (int k = 0; k < 2; ++k) dst[m][k] = *(const PG8_LAS bf16x8*)(lds + PG8_SA(b, h) + aoff + m * 2048 + k * 1024); } while (0)
; #define PG8_MMA(ai, bj, At, Bt) do { __builtin_amdgcn_s_setprio(1); _Pragma("unroll") for (int m = 0; m < 4; ++m) _Pragma("unroll") for (int n = 0; n < 2; ++n) _Pragma("unroll") for (int k = 0; k < 2; ++k) \
;         acc[ai][bj][m][n] = __builtin_amdgcn_mfma_f32_16x16x32_bf16(Bt[n][k], At[m][k], acc[ai][bj][m][n], 0, 0, 0); __builtin_amdgcn_s_setprio(0); } while (0)
; #define PG8_WAIT_V(n) asm volatile("s_waitcnt vmcnt(" #n ")" ::: "memory")
; #define PG8_WAIT_L(n) asm volatile("s_waitcnt lgkmcnt(" #n ")" ::: "memory")
; #define PG8_BAR __builtin_amdgcn_s_barrier()
; #define PG8_SCHED __builtin_amdgcn_sched_barrier(0)
; template <class Epi, class Sched, bool ALIGN_EPI = false, bool SP2 = false>
; __device__ __forceinline__ void gemm_phase(PG8_LAS unsigned char* lds, const Gemm g, const Sched& S, const Epi& E) {
;     ...
;         for (int t = 0; t < nt; t += 2) {
;             const bool last = (t == nt - 2);
;     ...
;             PG8_LDA(At, 1, 1); PG8_STAGE(PG8_SB(1, 0), b3, voffB); PG8_STAGE(PG8_SB(1, 1), b3 + hstepB, voffB); PG8_STAGE(PG8_SA(1, 0), a3, voffA);
;             PG8_WAIT_V(8); PG8_WAIT_L(0); PG8_BAR; PG8_MMA(1, 0, At, B0); PG8_MMA(1, 1, At, B1); PG8_BAR; PG8_SCHED;
	s_add_i32 s34, s36, s43
	v_lshl_add_u64 v[140:141], v[140:141], 0, s[10:11]
	s_mov_b32 m0, s34
	global_load_lds_dwordx4 v[140:141], off
	s_add_i32 m0, s34, 0x2000
	s_add_u32 s30, s30, 0x100080
	v_lshl_add_u64 v[140:141], v[210:211], 0, s[10:11]
	s_addc_u32 s31, s31, 0
	s_add_i32 s34, s37, s43
	global_load_lds_dwordx4 v[140:141], off
	v_lshl_add_u64 v[140:141], s[30:31], 0, v[132:133]
	s_mov_b32 m0, s34
	s_nop 0
	global_load_lds_dwordx4 v[140:141], off
	v_lshl_add_u64 v[140:141], s[30:31], 0, v[136:137]
	s_add_i32 m0, s34, 0x2000
	s_nop 0
	global_load_lds_dwordx4 v[140:141], off
	ds_read_b128 v[178:181], v144 offset:49152
	ds_read_b128 v[182:185], v144 offset:50176
	ds_read_b128 v[186:189], v144 offset:51200
	ds_read_b128 v[190:193], v144 offset:52224
	ds_read_b128 v[194:197], v144 offset:53248
	ds_read_b128 v[198:201], v144 offset:54272
	ds_read_b128 v[202:205], v144 offset:55296
	ds_read_b128 v[206:209], v144 offset:56320
	s_waitcnt vmcnt(6)
	s_waitcnt lgkmcnt(0)
	s_barrier
	s_setprio 1
	s_waitcnt lgkmcnt(0)
	v_mfma_f32_16x16x32_bf16 v[62:65], v[146:149], v[178:181], v[62:65]
	v_mfma_f32_16x16x32_bf16 v[58:61], v[154:157], v[178:181], v[58:61]
	v_mfma_f32_16x16x32_bf16 v[50:53], v[146:149], v[186:189], v[50:53]
	v_mfma_f32_16x16x32_bf16 v[42:45], v[154:157], v[186:189], v[42:45]
	v_mfma_f32_16x16x32_bf16 v[34:37], v[146:149], v[194:197], v[34:37]
	v_mfma_f32_16x16x32_bf16 v[26:29], v[154:157], v[194:197], v[26:29]
	v_mfma_f32_16x16x32_bf16 v[18:21], v[146:149], v[202:205], v[18:21]
	v_mfma_f32_16x16x32_bf16 v[10:13], v[154:157], v[202:205], v[10:13]
	v_mfma_f32_16x16x32_bf16 v[62:65], v[150:153], v[182:185], v[62:65]
	v_mfma_f32_16x16x32_bf16 v[58:61], v[158:161], v[182:185], v[58:61]
	v_mfma_f32_16x16x32_bf16 v[50:53], v[150:153], v[190:193], v[50:53]
	v_mfma_f32_16x16x32_bf16 v[42:45], v[158:161], v[190:193], v[42:45]
	v_mfma_f32_16x16x32_bf16 v[34:37], v[150:153], v[198:201], v[34:37]
	v_mfma_f32_16x16x32_bf16 v[26:29], v[158:161], v[198:201], v[26:29]
	v_mfma_f32_16x16x32_bf16 v[18:21], v[150:153], v[206:209], v[18:21]
	v_mfma_f32_16x16x32_bf16 v[10:13], v[158:161], v[206:209], v[10:13]
	s_setprio 0
	s_setprio 1
	v_mfma_f32_16x16x32_bf16 v[54:57], v[162:165], v[178:181], v[54:57]
	v_mfma_f32_16x16x32_bf16 v[46:49], v[170:173], v[178:181], v[46:49]
	v_mfma_f32_16x16x32_bf16 v[38:41], v[162:165], v[186:189], v[38:41]
	v_mfma_f32_16x16x32_bf16 v[30:33], v[170:173], v[186:189], v[30:33]
	v_mfma_f32_16x16x32_bf16 v[22:25], v[162:165], v[194:197], v[22:25]
	v_mfma_f32_16x16x32_bf16 v[14:17], v[170:173], v[194:197], v[14:17]
	v_mfma_f32_16x16x32_bf16 v[6:9], v[162:165], v[202:205], v[6:9]
	v_mfma_f32_16x16x32_bf16 v[2:5], v[170:173], v[202:205], v[2:5]
	v_mfma_f32_16x16x32_bf16 v[54:57], v[166:169], v[182:185], v[54:57]
	v_mfma_f32_16x16x32_bf16 v[46:49], v[174:177], v[182:185], v[46:49]
	v_mfma_f32_16x16x32_bf16 v[38:41], v[166:169], v[190:193], v[38:41]
	v_mfma_f32_16x16x32_bf16 v[30:33], v[174:177], v[190:193], v[30:33]
	v_mfma_f32_16x16x32_bf16 v[22:25], v[166:169], v[198:201], v[22:25]
	v_mfma_f32_16x16x32_bf16 v[14:17], v[174:177], v[198:201], v[14:17]
	v_mfma_f32_16x16x32_bf16 v[6:9], v[166:169], v[206:209], v[6:9]
	v_mfma_f32_16x16x32_bf16 v[2:5], v[174:177], v[206:209], v[2:5]
	s_setprio 0
	s_barrier
	v_lshl_add_u64 v[140:141], v[212:213], 0, s[10:11]
	s_mov_b32 m0, s49
	s_nop 0
	global_load_lds_dwordx4 v[140:141], off
	v_lshl_add_u64 v[140:141], v[214:215], 0, s[10:11]
	s_mov_b32 m0, s50
	s_nop 0
	global_load_lds_dwordx4 v[140:141], off
	s_add_i32 s30, s62, 2
	s_cmp_gt_u32 s62, 61
	s_mov_b32 s62, s30
	s_cbranch_scc1 .LBB0_1770

; #define PG8_STAGE(bufoff, gbase, voff) do { _Pragma("unroll") for (int _i = 0; _i < 2; ++_i) \
;         __builtin_amdgcn_global_load_lds((const unsigned*)((const char*)(gbase) + (voff)[_i]), (PG8_LAS unsigned*)(lds + (bufoff) + ldsw + _i * 8192), 16, 0, 0); } while (0)
; #define PG8_LDA(dst, b, h) do { _Pragma("unroll") for (int m = 0; m < 4; ++m) _Pragma("unroll") for (int k = 0; k < 2; ++k) dst[m][k] = *(const PG8_LAS bf16x8*)(lds + PG8_SA(b, h) + aoff + m * 2048 + k * 1024); } while (0)
; #define PG8_LDB(dst, b, h) do { _Pragma("unroll") for (int n = 0; n < 2; ++n) _Pragma("unroll") for (int k = 0; k < 2; ++k) dst[n][k] = *(const PG8_LAS bf16x8*)(lds + PG8_SB(b, h) + boff + n * 2048 + k * 1024); } while (0)
; #define PG8_MMA(ai, bj, At, Bt) do { __builtin_amdgcn_s_setprio(1); _Pragma("unroll") for (int m = 0; m < 4; ++m) _Pragma("unroll") for (int n = 0; n < 2; ++n) _Pragma("unroll") for (int k = 0; k < 2; ++k) \
;         acc[ai][bj][m][n] = __builtin_amdgcn_mfma_f32_16x16x32_bf16(Bt[n][k], At[m][k], acc[ai][bj][m][n], 0, 0, 0); __builtin_amdgcn_s_setprio(0); } while (0)
; #define PG8_WAIT_V(n) asm volatile("s_waitcnt vmcnt(" #n ")" ::: "memory")
; #define PG8_WAIT_L(n) asm volatile("s_waitcnt lgkmcnt(" #n ")" ::: "memory")
; #define PG8_BAR __builtin_amdgcn_s_barrier()
; #define PG8_SCHED __builtin_amdgcn_sched_barrier(0)
; template <class Epi, class Sched, bool ALIGN_EPI = false, bool SP2 = false>
; __device__ __forceinline__ void gemm_phase(PG8_LAS unsigned char* lds, const Gemm g, const Sched& S, const Epi& E) {
;     ...
;         for (int t = 0; t < nt; t += 2) {
;             const bool last = (t == nt - 2);
;             const char* a1 = cA + (size_t)(t + 1) * kstep;
;             const char* a2 = last ? nA : cA + (size_t)(t + 2) * kstep; const char* b2 = last ? nB : cB + (size_t)(t + 2) * kstep;
;             const char* a3 = a2 + kstep; const char* b3 = b2 + kstep;
;             if (last && has_next) S.a_ready(nxt);
;             if constexpr (SP2) {
;             PG8_LDB(B0, 0, 0); PG8_LDB(B1, 0, 1); PG8_SCHED; PG8_LDA(At, 0, 0); PG8_STAGE(PG8_SA(1, 1), a1 + hstepA, voffA);
;             PG8_WAIT_V(8); PG8_WAIT_L(0); PG8_BAR; PG8_MMA(0, 0, At, B0); PG8_MMA(0, 1, At, B1); PG8_BAR; PG8_SCHED;
;             PG8_LDA(At, 0, 1); PG8_STAGE(PG8_SB(0, 0), b2, voffB); PG8_STAGE(PG8_SB(0, 1), b2 + hstepB, voffB); PG8_STAGE(PG8_SA(0, 0), a2, voffA);
.LBB0_1868:
	ds_read_b128 v[160:163], v156
	ds_read_b128 v[164:167], v156 offset:1024
	ds_read_b128 v[168:171], v156 offset:2048
	ds_read_b128 v[172:175], v156 offset:3072
	ds_read_b128 v[176:179], v157
	ds_read_b128 v[180:183], v157 offset:1024
	ds_read_b128 v[184:187], v157 offset:2048
	ds_read_b128 v[188:191], v157 offset:3072
	s_add_u32 s34, s30, 0xfff00080
	s_addc_u32 s35, s31, -1
	s_cmp_eq_u32 s61, 60
	s_cselect_b32 s37, s23, s35
	s_cselect_b32 s36, s57, s34
	s_cselect_b32 s35, s21, s60
	s_cselect_b32 s34, s58, s59
	v_lshl_add_u64 v[146:147], s[30:31], 0, v[138:139]
	s_add_i32 m0, s29, 0xc000
	ds_read_b128 v[192:195], v158
	ds_read_b128 v[196:199], v158 offset:1024
	ds_read_b128 v[200:203], v158 offset:2048
	ds_read_b128 v[204:207], v158 offset:3072
	ds_read_b128 v[208:211], v158 offset:4096
	ds_read_b128 v[212:215], v158 offset:5120
	ds_read_b128 v[218:221], v158 offset:6144
	ds_read_b128 v[222:225], v158 offset:7168
	global_load_lds_dwordx4 v[146:147], off
	v_lshl_add_u64 v[146:147], s[30:31], 0, v[140:141]
	s_add_i32 m0, s29, 0xe000
	s_nop 0
	global_load_lds_dwordx4 v[146:147], off
	s_waitcnt vmcnt(8)
	s_waitcnt lgkmcnt(0)
	s_barrier
	s_setprio 1
	s_waitcnt lgkmcnt(0)
	v_mfma_f32_16x16x32_bf16 v[126:129], v[160:163], v[192:195], v[126:129]
	v_mfma_f32_16x16x32_bf16 v[122:125], v[168:171], v[192:195], v[122:125]
	v_mfma_f32_16x16x32_bf16 v[114:117], v[160:163], v[200:203], v[114:117]
	v_mfma_f32_16x16x32_bf16 v[106:109], v[168:171], v[200:203], v[106:109]
	v_mfma_f32_16x16x32_bf16 v[98:101], v[160:163], v[208:211], v[98:101]
	v_mfma_f32_16x16x32_bf16 v[90:93], v[168:171], v[208:211], v[90:93]
	v_mfma_f32_16x16x32_bf16 v[82:85], v[160:163], v[218:221], v[82:85]
	v_mfma_f32_16x16x32_bf16 v[74:77], v[168:171], v[218:221], v[74:77]
	v_mfma_f32_16x16x32_bf16 v[126:129], v[164:167], v[196:199], v[126:129]
	v_mfma_f32_16x16x32_bf16 v[122:125], v[172:175], v[196:199], v[122:125]
	v_mfma_f32_16x16x32_bf16 v[114:117], v[164:167], v[204:207], v[114:117]
	v_mfma_f32_16x16x32_bf16 v[106:109], v[172:175], v[204:207], v[106:109]
	v_mfma_f32_16x16x32_bf16 v[98:101], v[164:167], v[212:215], v[98:101]
	v_mfma_f32_16x16x32_bf16 v[90:93], v[172:175], v[212:215], v[90:93]
	v_mfma_f32_16x16x32_bf16 v[82:85], v[164:167], v[222:225], v[82:85]
	v_mfma_f32_16x16x32_bf16 v[74:77], v[172:175], v[222:225], v[74:77]
	s_setprio 0
	s_setprio 1
	v_mfma_f32_16x16x32_bf16 v[118:121], v[176:179], v[192:195], v[118:121]
	v_mfma_f32_16x16x32_bf16 v[110:113], v[184:187], v[192:195], v[110:113]
	v_mfma_f32_16x16x32_bf16 v[102:105], v[176:179], v[200:203], v[102:105]
	v_mfma_f32_16x16x32_bf16 v[94:97], v[184:187], v[200:203], v[94:97]
	v_mfma_f32_16x16x32_bf16 v[86:89], v[176:179], v[208:211], v[86:89]
	v_mfma_f32_16x16x32_bf16 v[78:81], v[184:187], v[208:211], v[78:81]
	v_mfma_f32_16x16x32_bf16 v[70:73], v[176:179], v[218:221], v[70:73]
	v_mfma_f32_16x16x32_bf16 v[66:69], v[184:187], v[218:221], v[66:69]
	v_mfma_f32_16x16x32_bf16 v[118:121], v[180:183], v[196:199], v[118:121]
	v_mfma_f32_16x16x32_bf16 v[110:113], v[188:191], v[196:199], v[110:113]
	v_mfma_f32_16x16x32_bf16 v[102:105], v[180:183], v[204:207], v[102:105]
	v_mfma_f32_16x16x32_bf16 v[94:97], v[188:191], v[204:207], v[94:97]
	v_mfma_f32_16x16x32_bf16 v[86:89], v[180:183], v[212:215], v[86:89]
	v_mfma_f32_16x16x32_bf16 v[78:81], v[188:191], v[212:215], v[78:81]
	v_mfma_f32_16x16x32_bf16 v[70:73], v[180:183], v[222:225], v[70:73]
	v_mfma_f32_16x16x32_bf16 v[66:69], v[188:191], v[222:225], v[66:69]
	s_setprio 0
	s_barrier
	s_add_i32 s62, s50, s42
	v_lshl_add_u64 v[146:147], s[34:35], 0, v[132:133]
	s_mov_b32 m0, s62
	global_load_lds_dwordx4 v[146:147], off
	s_add_i32 m0, s62, 0x2000
	s_add_u32 s62, s34, 0x100000
	v_lshl_add_u64 v[226:227], s[34:35], 0, v[136:137]
	s_addc_u32 s63, s35, 0
	s_add_i32 s64, s51, s42
	global_load_lds_dwordx4 v[226:227], off
	v_lshl_add_u64 v[228:229], s[62:63], 0, v[132:133]
	s_mov_b32 m0, s64
	v_lshl_add_u64 v[230:231], s[36:37], 0, v[134:135]
	global_load_lds_dwordx4 v[228:229], off
	v_lshl_add_u64 v[228:229], s[62:63], 0, v[136:137]
	s_add_i32 m0, s64, 0x2000
	s_nop 0
	global_load_lds_dwordx4 v[228:229], off
	v_lshl_add_u64 v[228:229], s[36:37], 0, v[130:131]
	ds_read_b128 v[192:195], v158 offset:16384
	ds_read_b128 v[196:199], v158 offset:17408
	ds_read_b128 v[200:203], v158 offset:18432
	ds_read_b128 v[204:207], v158 offset:19456
	ds_read_b128 v[208:211], v158 offset:20480
	ds_read_b128 v[212:215], v158 offset:21504
	ds_read_b128 v[218:221], v158 offset:22528
	ds_read_b128 v[222:225], v158 offset:23552
	s_waitcnt vmcnt(6)
	s_waitcnt lgkmcnt(0)
	s_barrier
; #define PG8_STAGE(bufoff, gbase, voff) do { _Pragma("unroll") for (int _i = 0; _i < 2; ++_i) \
;         __builtin_amdgcn_global_load_lds((const unsigned*)((const char*)(gbase) + (voff)[_i]), (PG8_LAS unsigned*)(lds + (bufoff) + ldsw + _i * 8192), 16, 0, 0); } while (0)
; #define PG8_LDA(dst, b, h) do { _Pragma("unroll") for (int m = 0; m < 4; ++m) _Pragma("unroll") for (int k = 0; k < 2; ++k) dst[m][k] = *(const PG8_LAS bf16x8*)(lds + PG8_SA(b, h) + aoff + m * 2048 + k * 1024); } while (0)
; #define PG8_LDB(dst, b, h) do { _Pragma("unroll") for (int n = 0; n < 2; ++n) _Pragma("unroll") for (int k = 0; k < 2; ++k) dst[n][k] = *(const PG8_LAS bf16x8*)(lds + PG8_SB(b, h) + boff + n * 2048 + k * 1024); } while (0)
; #define PG8_MMA(ai, bj, At, Bt) do { __builtin_amdgcn_s_setprio(1); _Pragma("unroll") for (int m = 0; m < 4; ++m) _Pragma("unroll") for (int n = 0; n < 2; ++n) _Pragma("unroll") for (int k = 0; k < 2; ++k) \
;         acc[ai][bj][m][n] = __builtin_amdgcn_mfma_f32_16x16x32_bf16(Bt[n][k], At[m][k], acc[ai][bj][m][n], 0, 0, 0); __builtin_amdgcn_s_setprio(0); } while (0)
; #define PG8_WAIT_V(n) asm volatile("s_waitcnt vmcnt(" #n ")" ::: "memory")
; #define PG8_WAIT_L(n) asm volatile("s_waitcnt lgkmcnt(" #n ")" ::: "memory")
; #define PG8_BAR __builtin_amdgcn_s_barrier()
; #define PG8_SCHED __builtin_amdgcn_sched_barrier(0)
; template <class Epi, class Sched, bool ALIGN_EPI = false, bool SP2 = false>
; __device__ __forceinline__ void gemm_phase(PG8_LAS unsigned char* lds, const Gemm g, const Sched& S, const Epi& E) {
;     ...
;             PG8_WAIT_V(8); PG8_WAIT_L(0); PG8_BAR; PG8_MMA(1, 0, At, B0); PG8_MMA(1, 1, At, B1); PG8_BAR; PG8_SCHED;
;             PG8_LDB(B0, 1, 0); PG8_LDB(B1, 1, 1); PG8_SCHED; PG8_LDA(At, 1, 0); PG8_STAGE(PG8_SA(0, 1), a2 + hstepA, voffA);
;             PG8_WAIT_V(8); PG8_WAIT_L(0); PG8_BAR; PG8_MMA(0, 0, At, B0); PG8_MMA(0, 1, At, B1); PG8_BAR; PG8_SCHED;
	s_setprio 1
	s_waitcnt lgkmcnt(0)
	v_mfma_f32_16x16x32_bf16 v[62:65], v[160:163], v[192:195], v[62:65]
	v_mfma_f32_16x16x32_bf16 v[58:61], v[168:171], v[192:195], v[58:61]
	v_mfma_f32_16x16x32_bf16 v[50:53], v[160:163], v[200:203], v[50:53]
	v_mfma_f32_16x16x32_bf16 v[42:45], v[168:171], v[200:203], v[42:45]
	v_mfma_f32_16x16x32_bf16 v[34:37], v[160:163], v[208:211], v[34:37]
	v_mfma_f32_16x16x32_bf16 v[26:29], v[168:171], v[208:211], v[26:29]
	v_mfma_f32_16x16x32_bf16 v[18:21], v[160:163], v[218:221], v[18:21]
	v_mfma_f32_16x16x32_bf16 v[10:13], v[168:171], v[218:221], v[10:13]
	v_mfma_f32_16x16x32_bf16 v[62:65], v[164:167], v[196:199], v[62:65]
	v_mfma_f32_16x16x32_bf16 v[58:61], v[172:175], v[196:199], v[58:61]
	v_mfma_f32_16x16x32_bf16 v[50:53], v[164:167], v[204:207], v[50:53]
	v_mfma_f32_16x16x32_bf16 v[42:45], v[172:175], v[204:207], v[42:45]
	v_mfma_f32_16x16x32_bf16 v[34:37], v[164:167], v[212:215], v[34:37]
	v_mfma_f32_16x16x32_bf16 v[26:29], v[172:175], v[212:215], v[26:29]
	v_mfma_f32_16x16x32_bf16 v[18:21], v[164:167], v[222:225], v[18:21]
	v_mfma_f32_16x16x32_bf16 v[10:13], v[172:175], v[222:225], v[10:13]
	s_setprio 0
	s_setprio 1
	v_mfma_f32_16x16x32_bf16 v[54:57], v[176:179], v[192:195], v[54:57]
	v_mfma_f32_16x16x32_bf16 v[46:49], v[184:187], v[192:195], v[46:49]
	v_mfma_f32_16x16x32_bf16 v[38:41], v[176:179], v[200:203], v[38:41]
	v_mfma_f32_16x16x32_bf16 v[30:33], v[184:187], v[200:203], v[30:33]
	v_mfma_f32_16x16x32_bf16 v[22:25], v[176:179], v[208:211], v[22:25]
	v_mfma_f32_16x16x32_bf16 v[14:17], v[184:187], v[208:211], v[14:17]
	v_mfma_f32_16x16x32_bf16 v[6:9], v[176:179], v[218:221], v[6:9]
	v_mfma_f32_16x16x32_bf16 v[2:5], v[184:187], v[218:221], v[2:5]
	v_mfma_f32_16x16x32_bf16 v[54:57], v[180:183], v[196:199], v[54:57]
	v_mfma_f32_16x16x32_bf16 v[46:49], v[188:191], v[196:199], v[46:49]
	v_mfma_f32_16x16x32_bf16 v[38:41], v[180:183], v[204:207], v[38:41]
	v_mfma_f32_16x16x32_bf16 v[30:33], v[188:191], v[204:207], v[30:33]
	v_mfma_f32_16x16x32_bf16 v[22:25], v[180:183], v[212:215], v[22:25]
	v_mfma_f32_16x16x32_bf16 v[14:17], v[188:191], v[212:215], v[14:17]
	v_mfma_f32_16x16x32_bf16 v[6:9], v[180:183], v[222:225], v[6:9]
	v_mfma_f32_16x16x32_bf16 v[2:5], v[188:191], v[222:225], v[2:5]
	s_setprio 0
	s_barrier
	s_mov_b32 m0, s29
	s_nop 0
	global_load_lds_dwordx4 v[228:229], off
	s_mov_b32 m0, s43
	s_nop 0
	global_load_lds_dwordx4 v[230:231], off
	s_add_i32 s62, 0, 0x18000
	v_add_u32_e32 v159, s62, v154
	s_add_i32 s63, 0, 0x1c000
	ds_read_b128 v[160:163], v159
	ds_read_b128 v[164:167], v159 offset:1024
	ds_read_b128 v[168:171], v159 offset:2048
	ds_read_b128 v[172:175], v159 offset:3072
	v_add_u32_e32 v159, s63, v154
	ds_read_b128 v[176:179], v159
	ds_read_b128 v[180:183], v159 offset:1024
	ds_read_b128 v[184:187], v159 offset:2048
	ds_read_b128 v[188:191], v159 offset:3072
	s_add_u32 s36, s36, 0x100000
	s_addc_u32 s37, s37, 0
	s_mov_b32 m0, s44
	v_lshl_add_u64 v[232:233], s[36:37], 0, v[130:131]
	ds_read_b128 v[192:195], v158 offset:32768
	ds_read_b128 v[196:199], v158 offset:33792
	ds_read_b128 v[200:203], v158 offset:34816
	ds_read_b128 v[204:207], v158 offset:35840
	ds_read_b128 v[208:211], v158 offset:36864
	ds_read_b128 v[212:215], v158 offset:37888
	ds_read_b128 v[218:221], v158 offset:38912
	ds_read_b128 v[222:225], v158 offset:39936
	global_load_lds_dwordx4 v[232:233], off
	v_lshl_add_u64 v[232:233], s[36:37], 0, v[134:135]
	s_mov_b32 m0, s45
	s_nop 0
	global_load_lds_dwordx4 v[232:233], off
	s_waitcnt vmcnt(8)
	s_waitcnt lgkmcnt(0)
	s_barrier
	s_setprio 1
	s_waitcnt lgkmcnt(0)
	v_mfma_f32_16x16x32_bf16 v[126:129], v[160:163], v[192:195], v[126:129]
	v_mfma_f32_16x16x32_bf16 v[122:125], v[168:171], v[192:195], v[122:125]
	v_mfma_f32_16x16x32_bf16 v[114:117], v[160:163], v[200:203], v[114:117]
	v_mfma_f32_16x16x32_bf16 v[106:109], v[168:171], v[200:203], v[106:109]
	v_mfma_f32_16x16x32_bf16 v[98:101], v[160:163], v[208:211], v[98:101]
	v_mfma_f32_16x16x32_bf16 v[90:93], v[168:171], v[208:211], v[90:93]
	v_mfma_f32_16x16x32_bf16 v[82:85], v[160:163], v[218:221], v[82:85]
	v_mfma_f32_16x16x32_bf16 v[74:77], v[168:171], v[218:221], v[74:77]
	v_mfma_f32_16x16x32_bf16 v[126:129], v[164:167], v[196:199], v[126:129]
	v_mfma_f32_16x16x32_bf16 v[122:125], v[172:175], v[196:199], v[122:125]
	v_mfma_f32_16x16x32_bf16 v[114:117], v[164:167], v[204:207], v[114:117]
	v_mfma_f32_16x16x32_bf16 v[106:109], v[172:175], v[204:207], v[106:109]
	v_mfma_f32_16x16x32_bf16 v[98:101], v[164:167], v[212:215], v[98:101]
	v_mfma_f32_16x16x32_bf16 v[90:93], v[172:175], v[212:215], v[90:93]
	v_mfma_f32_16x16x32_bf16 v[82:85], v[164:167], v[222:225], v[82:85]
	v_mfma_f32_16x16x32_bf16 v[74:77], v[172:175], v[222:225], v[74:77]
	s_setprio 0
	s_setprio 1
	v_mfma_f32_16x16x32_bf16 v[118:121], v[176:179], v[192:195], v[118:121]
	v_mfma_f32_16x16x32_bf16 v[110:113], v[184:187], v[192:195], v[110:113]
	v_mfma_f32_16x16x32_bf16 v[102:105], v[176:179], v[200:203], v[102:105]
	v_mfma_f32_16x16x32_bf16 v[94:97], v[184:187], v[200:203], v[94:97]
	v_mfma_f32_16x16x32_bf16 v[86:89], v[176:179], v[208:211], v[86:89]
	v_mfma_f32_16x16x32_bf16 v[78:81], v[184:187], v[208:211], v[78:81]
	v_mfma_f32_16x16x32_bf16 v[70:73], v[176:179], v[218:221], v[70:73]
	v_mfma_f32_16x16x32_bf16 v[66:69], v[184:187], v[218:221], v[66:69]
	v_mfma_f32_16x16x32_bf16 v[118:121], v[180:183], v[196:199], v[118:121]
	v_mfma_f32_16x16x32_bf16 v[110:113], v[188:191], v[196:199], v[110:113]
	v_mfma_f32_16x16x32_bf16 v[102:105], v[180:183], v[204:207], v[102:105]
	v_mfma_f32_16x16x32_bf16 v[94:97], v[188:191], v[204:207], v[94:97]
	v_mfma_f32_16x16x32_bf16 v[86:89], v[180:183], v[212:215], v[86:89]
	v_mfma_f32_16x16x32_bf16 v[78:81], v[188:191], v[212:215], v[78:81]
	v_mfma_f32_16x16x32_bf16 v[70:73], v[180:183], v[222:225], v[70:73]
	v_mfma_f32_16x16x32_bf16 v[66:69], v[188:191], v[222:225], v[66:69]
	s_setprio 0
	s_barrier
; #define PG8_STAGE(bufoff, gbase, voff) do { _Pragma("unroll") for (int _i = 0; _i < 2; ++_i) \
;         __builtin_amdgcn_global_load_lds((const unsigned*)((const char*)(gbase) + (voff)[_i]), (PG8_LAS unsigned*)(lds + (bufoff) + ldsw + _i * 8192), 16, 0, 0); } while (0)
; #define PG8_LDA(dst, b, h) do { _Pragma("unroll") for (int m = 0; m < 4; ++m) _Pragma("unroll") for (int k = 0; k < 2; ++k) dst[m][k] = *(const PG8_LAS bf16x8*)(lds + PG8_SA(b, h) + aoff + m * 2048 + k * 1024); } while (0)
; #define PG8_MMA(ai, bj, At, Bt) do { __builtin_amdgcn_s_setprio(1); _Pragma("unroll") for (int m = 0; m < 4; ++m) _Pragma("unroll") for (int n = 0; n < 2; ++n) _Pragma("unroll") for (int k = 0; k < 2; ++k) \
;         acc[ai][bj][m][n] = __builtin_amdgcn_mfma_f32_16x16x32_bf16(Bt[n][k], At[m][k], acc[ai][bj][m][n], 0, 0, 0); __builtin_amdgcn_s_setprio(0); } while (0)
; #define PG8_WAIT_V(n) asm volatile("s_waitcnt vmcnt(" #n ")" ::: "memory")
; #define PG8_WAIT_L(n) asm volatile("s_waitcnt lgkmcnt(" #n ")" ::: "memory")
; #define PG8_BAR __builtin_amdgcn_s_barrier()
; #define PG8_SCHED __builtin_amdgcn_sched_barrier(0)
; template <class Epi, class Sched, bool ALIGN_EPI = false, bool SP2 = false>
; __device__ __forceinline__ void gemm_phase(PG8_LAS unsigned char* lds, const Gemm g, const Sched& S, const Epi& E) {
;     ...
;         for (int t = 0; t < nt; t += 2) {
;             const bool last = (t == nt - 2);
;     ...
;             PG8_LDA(At, 1, 1); PG8_STAGE(PG8_SB(1, 0), b3, voffB); PG8_STAGE(PG8_SB(1, 1), b3 + hstepB, voffB); PG8_STAGE(PG8_SA(1, 0), a3, voffA);
;             PG8_WAIT_V(8); PG8_WAIT_L(0); PG8_BAR; PG8_MMA(1, 0, At, B0); PG8_MMA(1, 1, At, B1); PG8_BAR; PG8_SCHED;
	s_add_i32 s36, s62, s42
	v_lshl_add_u64 v[146:147], v[146:147], 0, s[10:11]
	s_mov_b32 m0, s36
	global_load_lds_dwordx4 v[146:147], off
	s_add_i32 m0, s36, 0x2000
	s_add_u32 s34, s34, 0x100080
	v_lshl_add_u64 v[146:147], v[226:227], 0, s[10:11]
	s_addc_u32 s35, s35, 0
	s_add_i32 s36, s63, s42
	global_load_lds_dwordx4 v[146:147], off
	v_lshl_add_u64 v[146:147], s[34:35], 0, v[132:133]
	s_mov_b32 m0, s36
	s_nop 0
	global_load_lds_dwordx4 v[146:147], off
	v_lshl_add_u64 v[146:147], s[34:35], 0, v[136:137]
	s_add_i32 m0, s36, 0x2000
	s_nop 0
	global_load_lds_dwordx4 v[146:147], off
	ds_read_b128 v[192:195], v158 offset:49152
	ds_read_b128 v[196:199], v158 offset:50176
	ds_read_b128 v[200:203], v158 offset:51200
	ds_read_b128 v[204:207], v158 offset:52224
	ds_read_b128 v[208:211], v158 offset:53248
	ds_read_b128 v[212:215], v158 offset:54272
	ds_read_b128 v[218:221], v158 offset:55296
	ds_read_b128 v[222:225], v158 offset:56320
	s_waitcnt vmcnt(6)
	s_waitcnt lgkmcnt(0)
	s_barrier
	s_setprio 1
	s_waitcnt lgkmcnt(0)
	v_mfma_f32_16x16x32_bf16 v[62:65], v[160:163], v[192:195], v[62:65]
	v_mfma_f32_16x16x32_bf16 v[58:61], v[168:171], v[192:195], v[58:61]
	v_mfma_f32_16x16x32_bf16 v[50:53], v[160:163], v[200:203], v[50:53]
	v_mfma_f32_16x16x32_bf16 v[42:45], v[168:171], v[200:203], v[42:45]
	v_mfma_f32_16x16x32_bf16 v[34:37], v[160:163], v[208:211], v[34:37]
	v_mfma_f32_16x16x32_bf16 v[26:29], v[168:171], v[208:211], v[26:29]
	v_mfma_f32_16x16x32_bf16 v[18:21], v[160:163], v[218:221], v[18:21]
	v_mfma_f32_16x16x32_bf16 v[10:13], v[168:171], v[218:221], v[10:13]
	v_mfma_f32_16x16x32_bf16 v[62:65], v[164:167], v[196:199], v[62:65]
	v_mfma_f32_16x16x32_bf16 v[58:61], v[172:175], v[196:199], v[58:61]
	v_mfma_f32_16x16x32_bf16 v[50:53], v[164:167], v[204:207], v[50:53]
	v_mfma_f32_16x16x32_bf16 v[42:45], v[172:175], v[204:207], v[42:45]
	v_mfma_f32_16x16x32_bf16 v[34:37], v[164:167], v[212:215], v[34:37]
	v_mfma_f32_16x16x32_bf16 v[26:29], v[172:175], v[212:215], v[26:29]
	v_mfma_f32_16x16x32_bf16 v[18:21], v[164:167], v[222:225], v[18:21]
	v_mfma_f32_16x16x32_bf16 v[10:13], v[172:175], v[222:225], v[10:13]
	s_setprio 0
	s_setprio 1
	v_mfma_f32_16x16x32_bf16 v[54:57], v[176:179], v[192:195], v[54:57]
	v_mfma_f32_16x16x32_bf16 v[46:49], v[184:187], v[192:195], v[46:49]
	v_mfma_f32_16x16x32_bf16 v[38:41], v[176:179], v[200:203], v[38:41]
	v_mfma_f32_16x16x32_bf16 v[30:33], v[184:187], v[200:203], v[30:33]
	v_mfma_f32_16x16x32_bf16 v[22:25], v[176:179], v[208:211], v[22:25]
	v_mfma_f32_16x16x32_bf16 v[14:17], v[184:187], v[208:211], v[14:17]
	v_mfma_f32_16x16x32_bf16 v[6:9], v[176:179], v[218:221], v[6:9]
	v_mfma_f32_16x16x32_bf16 v[2:5], v[184:187], v[218:221], v[2:5]
	v_mfma_f32_16x16x32_bf16 v[54:57], v[180:183], v[196:199], v[54:57]
	v_mfma_f32_16x16x32_bf16 v[46:49], v[188:191], v[196:199], v[46:49]
	v_mfma_f32_16x16x32_bf16 v[38:41], v[180:183], v[204:207], v[38:41]
	v_mfma_f32_16x16x32_bf16 v[30:33], v[188:191], v[204:207], v[30:33]
	v_mfma_f32_16x16x32_bf16 v[22:25], v[180:183], v[212:215], v[22:25]
	v_mfma_f32_16x16x32_bf16 v[14:17], v[188:191], v[212:215], v[14:17]
	v_mfma_f32_16x16x32_bf16 v[6:9], v[180:183], v[222:225], v[6:9]
	v_mfma_f32_16x16x32_bf16 v[2:5], v[188:191], v[222:225], v[2:5]
	s_setprio 0
	s_barrier
	v_lshl_add_u64 v[146:147], v[228:229], 0, s[10:11]
	s_mov_b32 m0, s47
	s_nop 0
	global_load_lds_dwordx4 v[146:147], off
	v_lshl_add_u64 v[146:147], v[230:231], 0, s[10:11]
	s_mov_b32 m0, s48
	s_nop 0
	global_load_lds_dwordx4 v[146:147], off
	s_add_i32 s61, s61, 2
	s_add_u32 s30, s30, 0x100
	s_addc_u32 s31, s31, 0
	s_add_u32 s59, s59, 0x100
	s_addc_u32 s60, s60, 0
	s_cmp_gt_u32 s61, 61
	s_cbranch_scc0 .LBB0_1868
	s_and_b64 vcc, exec, s[12:13]
	s_cbranch_vccz .LBB0_1871
	s_barrier

; #define PG8_STAGE(bufoff, gbase, voff) do { _Pragma("unroll") for (int _i = 0; _i < 2; ++_i) \
;         __builtin_amdgcn_global_load_lds((const unsigned*)((const char*)(gbase) + (voff)[_i]), (PG8_LAS unsigned*)(lds + (bufoff) + ldsw + _i * 8192), 16, 0, 0); } while (0)
; #define PG8_LDA(dst, b, h) do { _Pragma("unroll") for (int m = 0; m < 4; ++m) _Pragma("unroll") for (int k = 0; k < 2; ++k) dst[m][k] = *(const PG8_LAS bf16x8*)(lds + PG8_SA(b, h) + aoff + m * 2048 + k * 1024); } while (0)
; #define PG8_LDB(dst, b, h) do { _Pragma("unroll") for (int n = 0; n < 2; ++n) _Pragma("unroll") for (int k = 0; k < 2; ++k) dst[n][k] = *(const PG8_LAS bf16x8*)(lds + PG8_SB(b, h) + boff + n * 2048 + k * 1024); } while (0)
; #define PG8_MMA(ai, bj, At, Bt) do { __builtin_amdgcn_s_setprio(1); _Pragma("unroll") for (int m = 0; m < 4; ++m) _Pragma("unroll") for (int n = 0; n < 2; ++n) _Pragma("unroll") for (int k = 0; k < 2; ++k) \
;         acc[ai][bj][m][n] = __builtin_amdgcn_mfma_f32_16x16x32_bf16(Bt[n][k], At[m][k], acc[ai][bj][m][n], 0, 0, 0); __builtin_amdgcn_s_setprio(0); } while (0)
; #define PG8_WAIT_V(n) asm volatile("s_waitcnt vmcnt(" #n ")" ::: "memory")
; #define PG8_WAIT_L(n) asm volatile("s_waitcnt lgkmcnt(" #n ")" ::: "memory")
; #define PG8_BAR __builtin_amdgcn_s_barrier()
; #define PG8_SCHED __builtin_amdgcn_sched_barrier(0)
; template <class Epi, class Sched, bool ALIGN_EPI = false, bool SP2 = false>
; __device__ __forceinline__ void gemm_phase(PG8_LAS unsigned char* lds, const Gemm g, const Sched& S, const Epi& E) {
;     ...
;         for (int t = 0; t < nt; t += 2) {
;             const bool last = (t == nt - 2);
;             const char* a1 = cA + (size_t)(t + 1) * kstep;
;             const char* a2 = last ? nA : cA + (size_t)(t + 2) * kstep; const char* b2 = last ? nB : cB + (size_t)(t + 2) * kstep;
;             const char* a3 = a2 + kstep; const char* b3 = b2 + kstep;
;             if (last && has_next) S.a_ready(nxt);
;             if constexpr (SP2) {
;             PG8_LDB(B0, 0, 0); PG8_LDB(B1, 0, 1); PG8_SCHED; PG8_LDA(At, 0, 0); PG8_STAGE(PG8_SA(1, 1), a1 + hstepA, voffA);
;             PG8_WAIT_V(8); PG8_WAIT_L(0); PG8_BAR; PG8_MMA(0, 0, At, B0); PG8_MMA(0, 1, At, B1); PG8_BAR; PG8_SCHED;
;             PG8_LDA(At, 0, 1); PG8_STAGE(PG8_SB(0, 0), b2, voffB); PG8_STAGE(PG8_SB(0, 1), b2 + hstepB, voffB); PG8_STAGE(PG8_SA(0, 0), a2, voffA);
.LBB0_1880:
	ds_read_b128 v[148:151], v143
	ds_read_b128 v[152:155], v143 offset:1024
	ds_read_b128 v[156:159], v143 offset:2048
	ds_read_b128 v[160:163], v143 offset:3072
	ds_read_b128 v[164:167], v144
	ds_read_b128 v[168:171], v144 offset:1024
	ds_read_b128 v[172:175], v144 offset:2048
	ds_read_b128 v[176:179], v144 offset:3072
	s_add_u32 s16, s12, s14
	s_addc_u32 s17, s13, s15
	s_add_u32 s16, s16, 0x34000100
	s_addc_u32 s17, s17, 0
	s_add_u32 s42, s28, s14
	s_addc_u32 s43, s29, s15
	s_cmpk_eq_i32 s14, 0x1f00
	s_cselect_b32 s19, s9, s17
	s_cselect_b32 s18, s8, s16
	s_cselect_b32 s17, s7, s43
	s_cselect_b32 s16, s6, s42
	s_mov_b32 m0, s31
	v_lshl_add_u64 v[212:213], v[138:139], 0, s[14:15]
	ds_read_b128 v[180:183], v145
	ds_read_b128 v[184:187], v145 offset:1024
	ds_read_b128 v[188:191], v145 offset:2048
	ds_read_b128 v[192:195], v145 offset:3072
	ds_read_b128 v[196:199], v145 offset:4096
	ds_read_b128 v[200:203], v145 offset:5120
	ds_read_b128 v[204:207], v145 offset:6144
	ds_read_b128 v[208:211], v145 offset:7168
	global_load_lds_dwordx4 v[212:213], off
	v_lshl_add_u64 v[212:213], v[140:141], 0, s[14:15]
	s_mov_b32 m0, s33
	s_nop 0
	global_load_lds_dwordx4 v[212:213], off
	s_waitcnt vmcnt(8)
	s_waitcnt lgkmcnt(0)
	s_barrier
	s_setprio 1
	s_waitcnt lgkmcnt(0)
	v_mfma_f32_16x16x32_bf16 v[126:129], v[148:151], v[180:183], v[126:129]
	v_mfma_f32_16x16x32_bf16 v[122:125], v[156:159], v[180:183], v[122:125]
	v_mfma_f32_16x16x32_bf16 v[114:117], v[148:151], v[188:191], v[114:117]
	v_mfma_f32_16x16x32_bf16 v[106:109], v[156:159], v[188:191], v[106:109]
	v_mfma_f32_16x16x32_bf16 v[98:101], v[148:151], v[196:199], v[98:101]
	v_mfma_f32_16x16x32_bf16 v[90:93], v[156:159], v[196:199], v[90:93]
	v_mfma_f32_16x16x32_bf16 v[82:85], v[148:151], v[204:207], v[82:85]
	v_mfma_f32_16x16x32_bf16 v[74:77], v[156:159], v[204:207], v[74:77]
	v_mfma_f32_16x16x32_bf16 v[126:129], v[152:155], v[184:187], v[126:129]
	v_mfma_f32_16x16x32_bf16 v[122:125], v[160:163], v[184:187], v[122:125]
	v_mfma_f32_16x16x32_bf16 v[114:117], v[152:155], v[192:195], v[114:117]
	v_mfma_f32_16x16x32_bf16 v[106:109], v[160:163], v[192:195], v[106:109]
	v_mfma_f32_16x16x32_bf16 v[98:101], v[152:155], v[200:203], v[98:101]
	v_mfma_f32_16x16x32_bf16 v[90:93], v[160:163], v[200:203], v[90:93]
	v_mfma_f32_16x16x32_bf16 v[82:85], v[152:155], v[208:211], v[82:85]
	v_mfma_f32_16x16x32_bf16 v[74:77], v[160:163], v[208:211], v[74:77]
	s_setprio 0
	s_setprio 1
	v_mfma_f32_16x16x32_bf16 v[118:121], v[164:167], v[180:183], v[118:121]
	v_mfma_f32_16x16x32_bf16 v[110:113], v[172:175], v[180:183], v[110:113]
	v_mfma_f32_16x16x32_bf16 v[102:105], v[164:167], v[188:191], v[102:105]
	v_mfma_f32_16x16x32_bf16 v[94:97], v[172:175], v[188:191], v[94:97]
	v_mfma_f32_16x16x32_bf16 v[86:89], v[164:167], v[196:199], v[86:89]
	v_mfma_f32_16x16x32_bf16 v[78:81], v[172:175], v[196:199], v[78:81]
	v_mfma_f32_16x16x32_bf16 v[70:73], v[164:167], v[204:207], v[70:73]
	v_mfma_f32_16x16x32_bf16 v[66:69], v[172:175], v[204:207], v[66:69]
	v_mfma_f32_16x16x32_bf16 v[118:121], v[168:171], v[184:187], v[118:121]
	v_mfma_f32_16x16x32_bf16 v[110:113], v[176:179], v[184:187], v[110:113]
	v_mfma_f32_16x16x32_bf16 v[102:105], v[168:171], v[192:195], v[102:105]
	v_mfma_f32_16x16x32_bf16 v[94:97], v[176:179], v[192:195], v[94:97]
	v_mfma_f32_16x16x32_bf16 v[86:89], v[168:171], v[200:203], v[86:89]
	v_mfma_f32_16x16x32_bf16 v[78:81], v[176:179], v[200:203], v[78:81]
	v_mfma_f32_16x16x32_bf16 v[70:73], v[168:171], v[208:211], v[70:73]
	v_mfma_f32_16x16x32_bf16 v[66:69], v[176:179], v[208:211], v[66:69]
	s_setprio 0
	s_barrier
	s_mov_b32 m0, s34
	v_lshl_add_u64 v[212:213], s[16:17], 0, v[132:133]
	s_add_u32 s42, s16, 0x100000
	global_load_lds_dwordx4 v[212:213], off
	v_lshl_add_u64 v[214:215], s[16:17], 0, v[136:137]
	s_mov_b32 m0, s35
	s_addc_u32 s43, s17, 0
	global_load_lds_dwordx4 v[214:215], off
	v_lshl_add_u64 v[218:219], s[42:43], 0, v[132:133]
	s_mov_b32 m0, s36
	v_lshl_add_u64 v[220:221], s[18:19], 0, v[134:135]
	global_load_lds_dwordx4 v[218:219], off
	v_lshl_add_u64 v[218:219], s[42:43], 0, v[136:137]
	s_mov_b32 m0, s37
	s_nop 0
	global_load_lds_dwordx4 v[218:219], off
	v_lshl_add_u64 v[218:219], s[18:19], 0, v[130:131]
	ds_read_b128 v[180:183], v145 offset:16384
	ds_read_b128 v[184:187], v145 offset:17408
	ds_read_b128 v[188:191], v145 offset:18432
	ds_read_b128 v[192:195], v145 offset:19456
	ds_read_b128 v[196:199], v145 offset:20480
	ds_read_b128 v[200:203], v145 offset:21504
	ds_read_b128 v[204:207], v145 offset:22528
	ds_read_b128 v[208:211], v145 offset:23552
	s_waitcnt vmcnt(6)
	s_waitcnt lgkmcnt(0)
	s_barrier
; #define PG8_STAGE(bufoff, gbase, voff) do { _Pragma("unroll") for (int _i = 0; _i < 2; ++_i) \
;         __builtin_amdgcn_global_load_lds((const unsigned*)((const char*)(gbase) + (voff)[_i]), (PG8_LAS unsigned*)(lds + (bufoff) + ldsw + _i * 8192), 16, 0, 0); } while (0)
; #define PG8_LDA(dst, b, h) do { _Pragma("unroll") for (int m = 0; m < 4; ++m) _Pragma("unroll") for (int k = 0; k < 2; ++k) dst[m][k] = *(const PG8_LAS bf16x8*)(lds + PG8_SA(b, h) + aoff + m * 2048 + k * 1024); } while (0)
; #define PG8_LDB(dst, b, h) do { _Pragma("unroll") for (int n = 0; n < 2; ++n) _Pragma("unroll") for (int k = 0; k < 2; ++k) dst[n][k] = *(const PG8_LAS bf16x8*)(lds + PG8_SB(b, h) + boff + n * 2048 + k * 1024); } while (0)
; #define PG8_MMA(ai, bj, At, Bt) do { __builtin_amdgcn_s_setprio(1); _Pragma("unroll") for (int m = 0; m < 4; ++m) _Pragma("unroll") for (int n = 0; n < 2; ++n) _Pragma("unroll") for (int k = 0; k < 2; ++k) \
;         acc[ai][bj][m][n] = __builtin_amdgcn_mfma_f32_16x16x32_bf16(Bt[n][k], At[m][k], acc[ai][bj][m][n], 0, 0, 0); __builtin_amdgcn_s_setprio(0); } while (0)
; #define PG8_WAIT_V(n) asm volatile("s_waitcnt vmcnt(" #n ")" ::: "memory")
; #define PG8_WAIT_L(n) asm volatile("s_waitcnt lgkmcnt(" #n ")" ::: "memory")
; #define PG8_BAR __builtin_amdgcn_s_barrier()
; #define PG8_SCHED __builtin_amdgcn_sched_barrier(0)
; template <class Epi, class Sched, bool ALIGN_EPI = false, bool SP2 = false>
; __device__ __forceinline__ void gemm_phase(PG8_LAS unsigned char* lds, const Gemm g, const Sched& S, const Epi& E) {
;     ...
;             PG8_WAIT_V(8); PG8_WAIT_L(0); PG8_BAR; PG8_MMA(1, 0, At, B0); PG8_MMA(1, 1, At, B1); PG8_BAR; PG8_SCHED;
;             PG8_LDB(B0, 1, 0); PG8_LDB(B1, 1, 1); PG8_SCHED; PG8_LDA(At, 1, 0); PG8_STAGE(PG8_SA(0, 1), a2 + hstepA, voffA);
;             PG8_WAIT_V(8); PG8_WAIT_L(0); PG8_BAR; PG8_MMA(0, 0, At, B0); PG8_MMA(0, 1, At, B1); PG8_BAR; PG8_SCHED;
	s_setprio 1
	s_waitcnt lgkmcnt(0)
	v_mfma_f32_16x16x32_bf16 v[62:65], v[148:151], v[180:183], v[62:65]
	v_mfma_f32_16x16x32_bf16 v[58:61], v[156:159], v[180:183], v[58:61]
	v_mfma_f32_16x16x32_bf16 v[50:53], v[148:151], v[188:191], v[50:53]
	v_mfma_f32_16x16x32_bf16 v[42:45], v[156:159], v[188:191], v[42:45]
	v_mfma_f32_16x16x32_bf16 v[34:37], v[148:151], v[196:199], v[34:37]
	v_mfma_f32_16x16x32_bf16 v[26:29], v[156:159], v[196:199], v[26:29]
	v_mfma_f32_16x16x32_bf16 v[18:21], v[148:151], v[204:207], v[18:21]
	v_mfma_f32_16x16x32_bf16 v[10:13], v[156:159], v[204:207], v[10:13]
	v_mfma_f32_16x16x32_bf16 v[62:65], v[152:155], v[184:187], v[62:65]
	v_mfma_f32_16x16x32_bf16 v[58:61], v[160:163], v[184:187], v[58:61]
	v_mfma_f32_16x16x32_bf16 v[50:53], v[152:155], v[192:195], v[50:53]
	v_mfma_f32_16x16x32_bf16 v[42:45], v[160:163], v[192:195], v[42:45]
	v_mfma_f32_16x16x32_bf16 v[34:37], v[152:155], v[200:203], v[34:37]
	v_mfma_f32_16x16x32_bf16 v[26:29], v[160:163], v[200:203], v[26:29]
	v_mfma_f32_16x16x32_bf16 v[18:21], v[152:155], v[208:211], v[18:21]
	v_mfma_f32_16x16x32_bf16 v[10:13], v[160:163], v[208:211], v[10:13]
	s_setprio 0
	s_setprio 1
	v_mfma_f32_16x16x32_bf16 v[54:57], v[164:167], v[180:183], v[54:57]
	v_mfma_f32_16x16x32_bf16 v[46:49], v[172:175], v[180:183], v[46:49]
	v_mfma_f32_16x16x32_bf16 v[38:41], v[164:167], v[188:191], v[38:41]
	v_mfma_f32_16x16x32_bf16 v[30:33], v[172:175], v[188:191], v[30:33]
	v_mfma_f32_16x16x32_bf16 v[22:25], v[164:167], v[196:199], v[22:25]
	v_mfma_f32_16x16x32_bf16 v[14:17], v[172:175], v[196:199], v[14:17]
	v_mfma_f32_16x16x32_bf16 v[6:9], v[164:167], v[204:207], v[6:9]
	v_mfma_f32_16x16x32_bf16 v[2:5], v[172:175], v[204:207], v[2:5]
	v_mfma_f32_16x16x32_bf16 v[54:57], v[168:171], v[184:187], v[54:57]
	v_mfma_f32_16x16x32_bf16 v[46:49], v[176:179], v[184:187], v[46:49]
	v_mfma_f32_16x16x32_bf16 v[38:41], v[168:171], v[192:195], v[38:41]
	v_mfma_f32_16x16x32_bf16 v[30:33], v[176:179], v[192:195], v[30:33]
	v_mfma_f32_16x16x32_bf16 v[22:25], v[168:171], v[200:203], v[22:25]
	v_mfma_f32_16x16x32_bf16 v[14:17], v[176:179], v[200:203], v[14:17]
	v_mfma_f32_16x16x32_bf16 v[6:9], v[168:171], v[208:211], v[6:9]
	v_mfma_f32_16x16x32_bf16 v[2:5], v[176:179], v[208:211], v[2:5]
	s_setprio 0
	s_barrier
	s_mov_b32 m0, s3
	s_nop 0
	global_load_lds_dwordx4 v[218:219], off
	s_mov_b32 m0, s22
	s_nop 0
	global_load_lds_dwordx4 v[220:221], off
	ds_read_b128 v[148:151], v146
	ds_read_b128 v[152:155], v146 offset:1024
	ds_read_b128 v[156:159], v146 offset:2048
	ds_read_b128 v[160:163], v146 offset:3072
	ds_read_b128 v[164:167], v147
	ds_read_b128 v[168:171], v147 offset:1024
	ds_read_b128 v[172:175], v147 offset:2048
	ds_read_b128 v[176:179], v147 offset:3072
	s_add_u32 s18, s18, 0x100000
	s_addc_u32 s19, s19, 0
	s_mov_b32 m0, s23
	v_lshl_add_u64 v[222:223], s[18:19], 0, v[130:131]
	ds_read_b128 v[180:183], v145 offset:32768
	ds_read_b128 v[184:187], v145 offset:33792
	ds_read_b128 v[188:191], v145 offset:34816
	ds_read_b128 v[192:195], v145 offset:35840
	ds_read_b128 v[196:199], v145 offset:36864
	ds_read_b128 v[200:203], v145 offset:37888
	ds_read_b128 v[204:207], v145 offset:38912
	ds_read_b128 v[208:211], v145 offset:39936
	global_load_lds_dwordx4 v[222:223], off
	v_lshl_add_u64 v[222:223], s[18:19], 0, v[134:135]
	s_mov_b32 m0, s24
	s_nop 0
	global_load_lds_dwordx4 v[222:223], off
	s_waitcnt vmcnt(8)
	s_waitcnt lgkmcnt(0)
	s_barrier
	s_setprio 1
	s_waitcnt lgkmcnt(0)
	v_mfma_f32_16x16x32_bf16 v[126:129], v[148:151], v[180:183], v[126:129]
	v_mfma_f32_16x16x32_bf16 v[122:125], v[156:159], v[180:183], v[122:125]
	v_mfma_f32_16x16x32_bf16 v[114:117], v[148:151], v[188:191], v[114:117]
	v_mfma_f32_16x16x32_bf16 v[106:109], v[156:159], v[188:191], v[106:109]
	v_mfma_f32_16x16x32_bf16 v[98:101], v[148:151], v[196:199], v[98:101]
	v_mfma_f32_16x16x32_bf16 v[90:93], v[156:159], v[196:199], v[90:93]
	v_mfma_f32_16x16x32_bf16 v[82:85], v[148:151], v[204:207], v[82:85]
	v_mfma_f32_16x16x32_bf16 v[74:77], v[156:159], v[204:207], v[74:77]
	v_mfma_f32_16x16x32_bf16 v[126:129], v[152:155], v[184:187], v[126:129]
	v_mfma_f32_16x16x32_bf16 v[122:125], v[160:163], v[184:187], v[122:125]
	v_mfma_f32_16x16x32_bf16 v[114:117], v[152:155], v[192:195], v[114:117]
	v_mfma_f32_16x16x32_bf16 v[106:109], v[160:163], v[192:195], v[106:109]
	v_mfma_f32_16x16x32_bf16 v[98:101], v[152:155], v[200:203], v[98:101]
	v_mfma_f32_16x16x32_bf16 v[90:93], v[160:163], v[200:203], v[90:93]
	v_mfma_f32_16x16x32_bf16 v[82:85], v[152:155], v[208:211], v[82:85]
	v_mfma_f32_16x16x32_bf16 v[74:77], v[160:163], v[208:211], v[74:77]
	s_setprio 0
	s_setprio 1
	v_mfma_f32_16x16x32_bf16 v[118:121], v[164:167], v[180:183], v[118:121]
	v_mfma_f32_16x16x32_bf16 v[110:113], v[172:175], v[180:183], v[110:113]
	v_mfma_f32_16x16x32_bf16 v[102:105], v[164:167], v[188:191], v[102:105]
	v_mfma_f32_16x16x32_bf16 v[94:97], v[172:175], v[188:191], v[94:97]
	v_mfma_f32_16x16x32_bf16 v[86:89], v[164:167], v[196:199], v[86:89]
	v_mfma_f32_16x16x32_bf16 v[78:81], v[172:175], v[196:199], v[78:81]
	v_mfma_f32_16x16x32_bf16 v[70:73], v[164:167], v[204:207], v[70:73]
	v_mfma_f32_16x16x32_bf16 v[66:69], v[172:175], v[204:207], v[66:69]
	v_mfma_f32_16x16x32_bf16 v[118:121], v[168:171], v[184:187], v[118:121]
	v_mfma_f32_16x16x32_bf16 v[110:113], v[176:179], v[184:187], v[110:113]
	v_mfma_f32_16x16x32_bf16 v[102:105], v[168:171], v[192:195], v[102:105]
	v_mfma_f32_16x16x32_bf16 v[94:97], v[176:179], v[192:195], v[94:97]
	v_mfma_f32_16x16x32_bf16 v[86:89], v[168:171], v[200:203], v[86:89]
	v_mfma_f32_16x16x32_bf16 v[78:81], v[176:179], v[200:203], v[78:81]
	v_mfma_f32_16x16x32_bf16 v[70:73], v[168:171], v[208:211], v[70:73]
	v_mfma_f32_16x16x32_bf16 v[66:69], v[176:179], v[208:211], v[66:69]
	s_setprio 0
	s_barrier
; #define PG8_STAGE(bufoff, gbase, voff) do { _Pragma("unroll") for (int _i = 0; _i < 2; ++_i) \
;         __builtin_amdgcn_global_load_lds((const unsigned*)((const char*)(gbase) + (voff)[_i]), (PG8_LAS unsigned*)(lds + (bufoff) + ldsw + _i * 8192), 16, 0, 0); } while (0)
; #define PG8_LDA(dst, b, h) do { _Pragma("unroll") for (int m = 0; m < 4; ++m) _Pragma("unroll") for (int k = 0; k < 2; ++k) dst[m][k] = *(const PG8_LAS bf16x8*)(lds + PG8_SA(b, h) + aoff + m * 2048 + k * 1024); } while (0)
; #define PG8_MMA(ai, bj, At, Bt) do { __builtin_amdgcn_s_setprio(1); _Pragma("unroll") for (int m = 0; m < 4; ++m) _Pragma("unroll") for (int n = 0; n < 2; ++n) _Pragma("unroll") for (int k = 0; k < 2; ++k) \
;         acc[ai][bj][m][n] = __builtin_amdgcn_mfma_f32_16x16x32_bf16(Bt[n][k], At[m][k], acc[ai][bj][m][n], 0, 0, 0); __builtin_amdgcn_s_setprio(0); } while (0)
; #define PG8_WAIT_V(n) asm volatile("s_waitcnt vmcnt(" #n ")" ::: "memory")
; #define PG8_WAIT_L(n) asm volatile("s_waitcnt lgkmcnt(" #n ")" ::: "memory")
; #define PG8_BAR __builtin_amdgcn_s_barrier()
; #define PG8_SCHED __builtin_amdgcn_sched_barrier(0)
; template <class Epi, class Sched, bool ALIGN_EPI = false, bool SP2 = false>
; __device__ __forceinline__ void gemm_phase(PG8_LAS unsigned char* lds, const Gemm g, const Sched& S, const Epi& E) {
;     ...
;         for (int t = 0; t < nt; t += 2) {
;             const bool last = (t == nt - 2);
;     ...
;             PG8_LDA(At, 1, 1); PG8_STAGE(PG8_SB(1, 0), b3, voffB); PG8_STAGE(PG8_SB(1, 1), b3 + hstepB, voffB); PG8_STAGE(PG8_SA(1, 0), a3, voffA);
;             PG8_WAIT_V(8); PG8_WAIT_L(0); PG8_BAR; PG8_MMA(1, 0, At, B0); PG8_MMA(1, 1, At, B1); PG8_BAR; PG8_SCHED;
	s_mov_b32 m0, s38
	v_lshl_add_u64 v[212:213], v[212:213], 0, s[10:11]
	s_add_u32 s16, s16, 0x100080
	global_load_lds_dwordx4 v[212:213], off
	v_lshl_add_u64 v[212:213], v[214:215], 0, s[10:11]
	s_mov_b32 m0, s39
	s_addc_u32 s17, s17, 0
	global_load_lds_dwordx4 v[212:213], off
	v_lshl_add_u64 v[212:213], s[16:17], 0, v[132:133]
	s_mov_b32 m0, s40
	s_nop 0
	global_load_lds_dwordx4 v[212:213], off
	v_lshl_add_u64 v[212:213], s[16:17], 0, v[136:137]
	s_mov_b32 m0, s41
	s_nop 0
	global_load_lds_dwordx4 v[212:213], off
	ds_read_b128 v[180:183], v145 offset:49152
	ds_read_b128 v[184:187], v145 offset:50176
	ds_read_b128 v[188:191], v145 offset:51200
	ds_read_b128 v[192:195], v145 offset:52224
	ds_read_b128 v[196:199], v145 offset:53248
	ds_read_b128 v[200:203], v145 offset:54272
	ds_read_b128 v[204:207], v145 offset:55296
	ds_read_b128 v[208:211], v145 offset:56320
	s_waitcnt vmcnt(6)
	s_waitcnt lgkmcnt(0)
	s_barrier
	s_setprio 1
	s_waitcnt lgkmcnt(0)
	v_mfma_f32_16x16x32_bf16 v[62:65], v[148:151], v[180:183], v[62:65]
	v_mfma_f32_16x16x32_bf16 v[58:61], v[156:159], v[180:183], v[58:61]
	v_mfma_f32_16x16x32_bf16 v[50:53], v[148:151], v[188:191], v[50:53]
	v_mfma_f32_16x16x32_bf16 v[42:45], v[156:159], v[188:191], v[42:45]
	v_mfma_f32_16x16x32_bf16 v[34:37], v[148:151], v[196:199], v[34:37]
	v_mfma_f32_16x16x32_bf16 v[26:29], v[156:159], v[196:199], v[26:29]
	v_mfma_f32_16x16x32_bf16 v[18:21], v[148:151], v[204:207], v[18:21]
	v_mfma_f32_16x16x32_bf16 v[10:13], v[156:159], v[204:207], v[10:13]
	v_mfma_f32_16x16x32_bf16 v[62:65], v[152:155], v[184:187], v[62:65]
	v_mfma_f32_16x16x32_bf16 v[58:61], v[160:163], v[184:187], v[58:61]
	v_mfma_f32_16x16x32_bf16 v[50:53], v[152:155], v[192:195], v[50:53]
	v_mfma_f32_16x16x32_bf16 v[42:45], v[160:163], v[192:195], v[42:45]
	v_mfma_f32_16x16x32_bf16 v[34:37], v[152:155], v[200:203], v[34:37]
	v_mfma_f32_16x16x32_bf16 v[26:29], v[160:163], v[200:203], v[26:29]
	v_mfma_f32_16x16x32_bf16 v[18:21], v[152:155], v[208:211], v[18:21]
	v_mfma_f32_16x16x32_bf16 v[10:13], v[160:163], v[208:211], v[10:13]
	s_setprio 0
	s_setprio 1
	v_mfma_f32_16x16x32_bf16 v[54:57], v[164:167], v[180:183], v[54:57]
	v_mfma_f32_16x16x32_bf16 v[46:49], v[172:175], v[180:183], v[46:49]
	v_mfma_f32_16x16x32_bf16 v[38:41], v[164:167], v[188:191], v[38:41]
	v_mfma_f32_16x16x32_bf16 v[30:33], v[172:175], v[188:191], v[30:33]
	v_mfma_f32_16x16x32_bf16 v[22:25], v[164:167], v[196:199], v[22:25]
	v_mfma_f32_16x16x32_bf16 v[14:17], v[172:175], v[196:199], v[14:17]
	v_mfma_f32_16x16x32_bf16 v[6:9], v[164:167], v[204:207], v[6:9]
	v_mfma_f32_16x16x32_bf16 v[2:5], v[172:175], v[204:207], v[2:5]
	v_mfma_f32_16x16x32_bf16 v[54:57], v[168:171], v[184:187], v[54:57]
	v_mfma_f32_16x16x32_bf16 v[46:49], v[176:179], v[184:187], v[46:49]
	v_mfma_f32_16x16x32_bf16 v[38:41], v[168:171], v[192:195], v[38:41]
	v_mfma_f32_16x16x32_bf16 v[30:33], v[176:179], v[192:195], v[30:33]
	v_mfma_f32_16x16x32_bf16 v[22:25], v[168:171], v[200:203], v[22:25]
	v_mfma_f32_16x16x32_bf16 v[14:17], v[176:179], v[200:203], v[14:17]
	v_mfma_f32_16x16x32_bf16 v[6:9], v[168:171], v[208:211], v[6:9]
	v_mfma_f32_16x16x32_bf16 v[2:5], v[176:179], v[208:211], v[2:5]
	s_setprio 0
	s_barrier
	v_lshl_add_u64 v[212:213], v[218:219], 0, s[10:11]
	s_mov_b32 m0, s26
	s_nop 0
	global_load_lds_dwordx4 v[212:213], off
	v_lshl_add_u64 v[212:213], v[220:221], 0, s[10:11]
	s_mov_b32 m0, s27
	s_nop 0
	global_load_lds_dwordx4 v[212:213], off
	s_add_i32 s30, s30, 2
	s_add_u32 s14, s14, 0x100
	s_addc_u32 s15, s15, 0
	s_cmp_gt_u32 s30, 61
	s_cbranch_scc0 .LBB0_1880
	s_cmpk_lt_u32 s20, 0x100
	s_cbranch_scc0 .LBB0_1883
	s_barrier
